# both pass-2 scans hand-written: decay factored out of the state (renormalised every 32 steps), rank-1 updates on f32 4x4x1 MFMA, DPP dots, 3-deep operand prefetch
# speedup vs baseline: 1.0534x; 1.0448x over previous
; #define MKR(ptr) __builtin_amdgcn_make_buffer_rsrc((void*)(ptr), 0, 0x7fffffff, 0x00027000)
; __device__ __forceinline__ void scan_pass2(const Params& p, int d) {
;     const int lane = threadIdx.x & 63, wid = __builtin_amdgcn_readfirstlane(threadIdx.x >> 6); const unsigned lo16 = (lane & 15) * 16, lo2 = lane * 2, lo4b = lane * 4;
;     const float* Wd = (const float*)(p.ws + O_KD); const float* Bd = (const float*)(p.ws + O_Y); const u16* KB = (const u16*)(p.ws + O_K); const float* A = (const float*)(p.ws + O_A); const float* R = (const float*)(p.ws + O_R); const unsigned lo8 = (lane & 15) * 8;
;     const u16* V = (const u16*)(p.ws + O_V); const float* SIT = (const float*)(p.ws + O_SIT); float* Y = p.out;
;     for (int item = blockIdx.x * 8 + wid; item < 32 * NC; item += gridDim.x * 8) {
;         const int bh = item / NC, c = item - bh * NC, b = bh >> 4, h = bh & 15;
;         const int t0 = d ? (SEQ - 1 - c * LC) : c * LC;
;         const size_t off0 = ((size_t)(b * SEQ + t0)) * RW + h * 64; const long stp = d ? -(long)RW : (long)RW;
;         const unsigned ob4 = (unsigned)(off0 * 4), ob2 = (unsigned)(off0 * 2);
;         const __amdgpu_buffer_rsrc_t rW = MKR(Wd), rA = MKR(A), rB = MKR(Bd), rK = MKR(KB), rV = MKR(V), rR = MKR(R), rY = MKR(Y);
;         const f32x4 ka4 = *(const f32x4*)(p.k_a + h * 64 + (lane & 15) * 4), c04 = 1.0f - ka4;
;         float S[64];
;         if (c == 0) {
; #pragma unroll
;             for (int i = 0; i < 64; ++i) S[i] = 0.f;
;         } else { const float* si = SIT + ((size_t)(bh * NC + c)) * 4096 + lane * 64;
; #pragma unroll
;             for (int i = 0; i < 16; ++i) { const f32x4 q = *(const f32x4*)(si + 4 * i); S[4 * i] = q[0]; S[4 * i + 1] = q[1]; S[4 * i + 2] = q[2]; S[4 * i + 3] = q[3]; } }
;     ...
;         In2 i0, i1; LD2(i0, 0);
.LBB0_688:
	s_cmp_lt_i32 s58, 7
	s_cselect_b64 s[0:1], -1, 0
	s_cmp_gt_i32 s59, 6
	s_cselect_b64 s[4:5], -1, 0
	s_and_b64 s[0:1], s[0:1], s[4:5]
	s_andn2_b64 vcc, exec, s[0:1]
	s_cbranch_vccnz .LBB0_750
	v_readfirstlane_b32 s0, v254
	s_nop 3
	s_lshr_b32 s1, s0, 6
	s_lshl_b32 s0, s2, 3
	s_add_i32 s0, s1, s0
	s_mov_b32 s64, s56
	s_and_b32 s65, s57, 0xffff
	s_brev_b32 s66, -2
	s_mov_b32 s67, 0x27000
	s_mov_b32 s68, s54
	s_and_b32 s69, s55, 0xffff
	s_mov_b32 s70, s66
	s_mov_b32 s71, s67
	v_and_b32_e32 v212, 63, v254
	v_and_b32_e32 v213, 15, v254
	v_lshlrev_b32_e32 v204, 4, v213
	v_lshlrev_b32_e32 v205, 3, v213
	v_lshlrev_b32_e32 v206, 1, v212
	v_lshlrev_b32_e32 v207, 2, v212
	v_lshlrev_b32_e32 v210, 8, v212
	s_lshl_b32 s3, s1, 10
	s_add_u32 s3, s3, 0x10000
	v_add_u32_e32 v208, s3, v204
	v_and_b32_e32 v209, 3, v254
	v_lshlrev_b32_e32 v209, 2, v209
	v_add_u32_e32 v209, s3, v209
.Lmy_p2d0_item:
	s_cmpk_gt_i32 s0, 0x7ff
	s_cbranch_scc1 .Lmy_p2d0_end
	s_lshr_b32 s86, s0, 6
	s_and_b32 s85, s0, 63
	s_and_b32 s87, s86, 15
	s_lshr_b32 s6, s86, 4
	s_lshl_b32 s6, s6, 14
	s_lshl_b32 s7, s85, 8
	s_add_u32 s6, s6, s7
	s_lshl_b32 s6, s6, 10
	s_lshl_b32 s7, s87, 6
	s_add_u32 s84, s6, s7
	s_lshl_b32 s6, s84, 2
	s_lshl_b32 s7, s84, 1
	s_add_u32 s72, s6, 0xb800000
	s_add_u32 s73, s6, 0x24800000
	s_add_u32 s74, s6, 0x35a00000
	s_add_u32 s75, s6, 0x1c800000
	s_add_u32 s76, s7, 0x30800000
	s_add_u32 s77, s7, 0x2c800000
	s_mov_b32 s78, s6
	s_mov_b32 s79, s6
	s_mov_b32 s80, 0
	s_lshl_b32 s8, s87, 8
	s_add_u32 s4, s42, s8
	s_addc_u32 s5, s43, 0
	global_load_dwordx4 v[188:191], v204, s[4:5]
	buffer_load_dwordx4 v[96:99], v204, s[64:67], s72 offen
	buffer_load_dwordx4 v[100:103], v204, s[64:67], s73 offen
	buffer_load_dwordx4 v[104:107], v204, s[64:67], s74 offen
	buffer_load_dwordx4 v[108:111], v204, s[64:67], s75 offen
	buffer_load_dwordx2 v[112:113], v205, s[64:67], s76 offen
	buffer_load_ushort v114, v206, s[64:67], s77 offen
	s_add_u32 s72, s72, 0x1000
	s_add_u32 s73, s73, 0x1000
	s_add_u32 s74, s74, 0x1000
	s_add_u32 s75, s75, 0x1000
	s_add_u32 s78, s78, 0x1000
	s_add_u32 s76, s76, 0x800
	s_add_u32 s77, s77, 0x800
	buffer_load_dwordx4 v[116:119], v204, s[64:67], s72 offen
	buffer_load_dwordx4 v[120:123], v204, s[64:67], s73 offen
	buffer_load_dwordx4 v[124:127], v204, s[64:67], s74 offen
	buffer_load_dwordx4 v[128:131], v204, s[64:67], s75 offen
	buffer_load_dwordx2 v[132:133], v205, s[64:67], s76 offen
	buffer_load_ushort v134, v206, s[64:67], s77 offen
	s_add_u32 s72, s72, 0x1000
	s_add_u32 s73, s73, 0x1000
	s_add_u32 s74, s74, 0x1000
	s_add_u32 s75, s75, 0x1000
	s_add_u32 s78, s78, 0x1000
	s_add_u32 s76, s76, 0x800
	s_add_u32 s77, s77, 0x800
	buffer_load_dwordx4 v[136:139], v204, s[64:67], s72 offen
	buffer_load_dwordx4 v[140:143], v204, s[64:67], s73 offen
	buffer_load_dwordx4 v[144:147], v204, s[64:67], s74 offen
	buffer_load_dwordx4 v[148:151], v204, s[64:67], s75 offen
	buffer_load_dwordx2 v[152:153], v205, s[64:67], s76 offen
	buffer_load_ushort v154, v206, s[64:67], s77 offen
	s_add_u32 s72, s72, 0x1000
	s_add_u32 s73, s73, 0x1000
	s_add_u32 s74, s74, 0x1000
	s_add_u32 s75, s75, 0x1000
	s_add_u32 s78, s78, 0x1000
	s_add_u32 s76, s76, 0x800
	s_add_u32 s77, s77, 0x800
	s_mov_b32 s80, 3
	s_cmp_eq_u32 s85, 0
	s_cbranch_scc1 .Lmy_p2d0_zero
	s_lshl_b32 s8, s0, 14
	s_add_u32 s8, s8, 0x3da00000
	s_add_u32 s4, s56, s8
	s_addc_u32 s5, s57, 0
	global_load_dwordx4 v[0:3], v210, s[4:5] offset:0
	global_load_dwordx4 v[4:7], v210, s[4:5] offset:16
	global_load_dwordx4 v[8:11], v210, s[4:5] offset:32
	global_load_dwordx4 v[12:15], v210, s[4:5] offset:48
	global_load_dwordx4 v[16:19], v210, s[4:5] offset:64
	global_load_dwordx4 v[20:23], v210, s[4:5] offset:80
	global_load_dwordx4 v[24:27], v210, s[4:5] offset:96
	global_load_dwordx4 v[28:31], v210, s[4:5] offset:112
	global_load_dwordx4 v[32:35], v210, s[4:5] offset:128
	global_load_dwordx4 v[36:39], v210, s[4:5] offset:144
	global_load_dwordx4 v[40:43], v210, s[4:5] offset:160
	global_load_dwordx4 v[44:47], v210, s[4:5] offset:176
	global_load_dwordx4 v[48:51], v210, s[4:5] offset:192
	global_load_dwordx4 v[52:55], v210, s[4:5] offset:208
	global_load_dwordx4 v[56:59], v210, s[4:5] offset:224
	global_load_dwordx4 v[60:63], v210, s[4:5] offset:240
	s_branch .Lmy_p2d0_init_done

; #define SB __builtin_amdgcn_sched_barrier(0)
; #define ST2(set, s) { DERIVE_BK(set); float sd[4]; ScanK<0>::dot(S, set.a, sd); float y0 = set.yo, y1 = 0.f; ScanK<0>::upd(S, set, -((sd[0] + sd[1]) + (sd[2] + sd[3])), __uint_as_float(set.v << 16), y0, y1); __builtin_amdgcn_raw_buffer_store_b32(__float_as_uint(y0 + y1), rY, lo4b, ob4 + (unsigned)((int)(s) * (int)stp * 4), 0); }
; #define TOUCH2(set) asm volatile("" :: "v"(set.w), "v"(set.a), "v"(set.b), "v"(set.kw), "v"(set.r), "v"(set.v), "v"(set.yo))
; __device__ __forceinline__ void scan_pass2(const Params& p, int d) {
;     ...
;         In2 i0, i1; LD2(i0, 0);
; #pragma unroll 1
;         for (int s = 0; s < LC; s += 2) { TOUCH2(i0); SB; LD2(i1, s + 1); SB; ST2(i0, s); TOUCH2(i1); SB; LD2(i0, s + 2); SB; ST2(i1, s + 1); }
.Lmy_p2d0_init_done:
	s_waitcnt vmcnt(0)
	v_sub_f32_e32 v192, 1.0, v188
	v_sub_f32_e32 v193, 1.0, v189
	v_sub_f32_e32 v194, 1.0, v190
	v_sub_f32_e32 v195, 1.0, v191
	v_mov_b32_e32 v216, 1.0
	v_mov_b32_e32 v217, 1.0
	v_mov_b32_e32 v218, 1.0
	v_mov_b32_e32 v219, 1.0
	s_movk_i32 s83, 64
	s_branch .Lmy_p2d0_loop
.Lmy_p2d0_renorm:
	v_mul_f32_dpp v0, v216, v0 row_newbcast:0 row_mask:0xf bank_mask:0xf
	v_mul_f32_dpp v1, v217, v1 row_newbcast:0 row_mask:0xf bank_mask:0xf
	v_mul_f32_dpp v2, v218, v2 row_newbcast:0 row_mask:0xf bank_mask:0xf
	v_mul_f32_dpp v3, v219, v3 row_newbcast:0 row_mask:0xf bank_mask:0xf
	v_mul_f32_dpp v4, v216, v4 row_newbcast:1 row_mask:0xf bank_mask:0xf
	v_mul_f32_dpp v5, v217, v5 row_newbcast:1 row_mask:0xf bank_mask:0xf
	v_mul_f32_dpp v6, v218, v6 row_newbcast:1 row_mask:0xf bank_mask:0xf
	v_mul_f32_dpp v7, v219, v7 row_newbcast:1 row_mask:0xf bank_mask:0xf
	v_mul_f32_dpp v8, v216, v8 row_newbcast:2 row_mask:0xf bank_mask:0xf
	v_mul_f32_dpp v9, v217, v9 row_newbcast:2 row_mask:0xf bank_mask:0xf
	v_mul_f32_dpp v10, v218, v10 row_newbcast:2 row_mask:0xf bank_mask:0xf
	v_mul_f32_dpp v11, v219, v11 row_newbcast:2 row_mask:0xf bank_mask:0xf
	v_mul_f32_dpp v12, v216, v12 row_newbcast:3 row_mask:0xf bank_mask:0xf
	v_mul_f32_dpp v13, v217, v13 row_newbcast:3 row_mask:0xf bank_mask:0xf
	v_mul_f32_dpp v14, v218, v14 row_newbcast:3 row_mask:0xf bank_mask:0xf
	v_mul_f32_dpp v15, v219, v15 row_newbcast:3 row_mask:0xf bank_mask:0xf
	v_mul_f32_dpp v16, v216, v16 row_newbcast:4 row_mask:0xf bank_mask:0xf
	v_mul_f32_dpp v17, v217, v17 row_newbcast:4 row_mask:0xf bank_mask:0xf
	v_mul_f32_dpp v18, v218, v18 row_newbcast:4 row_mask:0xf bank_mask:0xf
	v_mul_f32_dpp v19, v219, v19 row_newbcast:4 row_mask:0xf bank_mask:0xf
	v_mul_f32_dpp v20, v216, v20 row_newbcast:5 row_mask:0xf bank_mask:0xf
	v_mul_f32_dpp v21, v217, v21 row_newbcast:5 row_mask:0xf bank_mask:0xf
	v_mul_f32_dpp v22, v218, v22 row_newbcast:5 row_mask:0xf bank_mask:0xf
	v_mul_f32_dpp v23, v219, v23 row_newbcast:5 row_mask:0xf bank_mask:0xf
	v_mul_f32_dpp v24, v216, v24 row_newbcast:6 row_mask:0xf bank_mask:0xf
	v_mul_f32_dpp v25, v217, v25 row_newbcast:6 row_mask:0xf bank_mask:0xf
	v_mul_f32_dpp v26, v218, v26 row_newbcast:6 row_mask:0xf bank_mask:0xf
	v_mul_f32_dpp v27, v219, v27 row_newbcast:6 row_mask:0xf bank_mask:0xf
	v_mul_f32_dpp v28, v216, v28 row_newbcast:7 row_mask:0xf bank_mask:0xf
	v_mul_f32_dpp v29, v217, v29 row_newbcast:7 row_mask:0xf bank_mask:0xf
	v_mul_f32_dpp v30, v218, v30 row_newbcast:7 row_mask:0xf bank_mask:0xf
	v_mul_f32_dpp v31, v219, v31 row_newbcast:7 row_mask:0xf bank_mask:0xf
	v_mul_f32_dpp v32, v216, v32 row_newbcast:8 row_mask:0xf bank_mask:0xf
	v_mul_f32_dpp v33, v217, v33 row_newbcast:8 row_mask:0xf bank_mask:0xf
	v_mul_f32_dpp v34, v218, v34 row_newbcast:8 row_mask:0xf bank_mask:0xf
	v_mul_f32_dpp v35, v219, v35 row_newbcast:8 row_mask:0xf bank_mask:0xf
	v_mul_f32_dpp v36, v216, v36 row_newbcast:9 row_mask:0xf bank_mask:0xf
	v_mul_f32_dpp v37, v217, v37 row_newbcast:9 row_mask:0xf bank_mask:0xf
	v_mul_f32_dpp v38, v218, v38 row_newbcast:9 row_mask:0xf bank_mask:0xf
	v_mul_f32_dpp v39, v219, v39 row_newbcast:9 row_mask:0xf bank_mask:0xf
	v_mul_f32_dpp v40, v216, v40 row_newbcast:10 row_mask:0xf bank_mask:0xf
	v_mul_f32_dpp v41, v217, v41 row_newbcast:10 row_mask:0xf bank_mask:0xf
	v_mul_f32_dpp v42, v218, v42 row_newbcast:10 row_mask:0xf bank_mask:0xf
	v_mul_f32_dpp v43, v219, v43 row_newbcast:10 row_mask:0xf bank_mask:0xf
	v_mul_f32_dpp v44, v216, v44 row_newbcast:11 row_mask:0xf bank_mask:0xf
	v_mul_f32_dpp v45, v217, v45 row_newbcast:11 row_mask:0xf bank_mask:0xf
	v_mul_f32_dpp v46, v218, v46 row_newbcast:11 row_mask:0xf bank_mask:0xf
	v_mul_f32_dpp v47, v219, v47 row_newbcast:11 row_mask:0xf bank_mask:0xf
	v_mul_f32_dpp v48, v216, v48 row_newbcast:12 row_mask:0xf bank_mask:0xf
	v_mul_f32_dpp v49, v217, v49 row_newbcast:12 row_mask:0xf bank_mask:0xf
	v_mul_f32_dpp v50, v218, v50 row_newbcast:12 row_mask:0xf bank_mask:0xf
	v_mul_f32_dpp v51, v219, v51 row_newbcast:12 row_mask:0xf bank_mask:0xf
	v_mul_f32_dpp v52, v216, v52 row_newbcast:13 row_mask:0xf bank_mask:0xf
	v_mul_f32_dpp v53, v217, v53 row_newbcast:13 row_mask:0xf bank_mask:0xf
	v_mul_f32_dpp v54, v218, v54 row_newbcast:13 row_mask:0xf bank_mask:0xf
	v_mul_f32_dpp v55, v219, v55 row_newbcast:13 row_mask:0xf bank_mask:0xf
	v_mul_f32_dpp v56, v216, v56 row_newbcast:14 row_mask:0xf bank_mask:0xf
	v_mul_f32_dpp v57, v217, v57 row_newbcast:14 row_mask:0xf bank_mask:0xf
	v_mul_f32_dpp v58, v218, v58 row_newbcast:14 row_mask:0xf bank_mask:0xf
	v_mul_f32_dpp v59, v219, v59 row_newbcast:14 row_mask:0xf bank_mask:0xf
	v_mul_f32_dpp v60, v216, v60 row_newbcast:15 row_mask:0xf bank_mask:0xf
	v_mul_f32_dpp v61, v217, v61 row_newbcast:15 row_mask:0xf bank_mask:0xf
	v_mul_f32_dpp v62, v218, v62 row_newbcast:15 row_mask:0xf bank_mask:0xf
	v_mul_f32_dpp v63, v219, v63 row_newbcast:15 row_mask:0xf bank_mask:0xf
	v_mov_b32_e32 v216, 1.0
	v_mov_b32_e32 v217, 1.0
	v_mov_b32_e32 v218, 1.0
	v_mov_b32_e32 v219, 1.0
.Lmy_p2d0_loop:
	s_waitcnt vmcnt(12)
	s_cmp_eq_u32 s80, 3
	s_cbranch_scc1 .Lmy_p2d0_nost
	buffer_store_dword v200, v207, s[68:71], s79 offen
	s_add_u32 s79, s79, 0x1000
;     static __device__ __forceinline__ void dot(const float (&S)[64], const f32x4& a, float (&s)[4]) {
;         if constexpr (K == 0) {
;             asm volatile("v_mul_f32_dpp %0, %4, %8 row_newbcast:%16" DPPM "v_mul_f32_dpp %1, %5, %9 row_newbcast:%16" DPPM "v_mul_f32_dpp %2, %6, %10 row_newbcast:%16" DPPM "v_mul_f32_dpp %3, %7, %11 row_newbcast:%16" DPPM
;                          "v_fmac_f32_dpp %0, %4, %12 row_newbcast:%17" DPPM "v_fmac_f32_dpp %1, %5, %13 row_newbcast:%17" DPPM "v_fmac_f32_dpp %2, %6, %14 row_newbcast:%17" DPPM "v_fmac_f32_dpp %3, %7, %15 row_newbcast:%17" DPPM
;                          : "=&v"(s[0]), "=&v"(s[1]), "=&v"(s[2]), "=&v"(s[3])
;                          : "v"(a[0]), "v"(a[1]), "v"(a[2]), "v"(a[3]), "v"(S[K]), "v"(S[K + 1]), "v"(S[K + 2]), "v"(S[K + 3]), "v"(S[K + 4]), "v"(S[K + 5]), "v"(S[K + 6]), "v"(S[K + 7]), "n"(N0), "n"(N1));
;         } else
;         asm volatile("v_fmac_f32_dpp %0, %4, %8 row_newbcast:%16" DPPM "v_fmac_f32_dpp %1, %5, %9 row_newbcast:%16" DPPM "v_fmac_f32_dpp %2, %6, %10 row_newbcast:%16" DPPM "v_fmac_f32_dpp %3, %7, %11 row_newbcast:%16" DPPM
;                      "v_fmac_f32_dpp %0, %4, %12 row_newbcast:%17" DPPM "v_fmac_f32_dpp %1, %5, %13 row_newbcast:%17" DPPM "v_fmac_f32_dpp %2, %6, %14 row_newbcast:%17" DPPM "v_fmac_f32_dpp %3, %7, %15 row_newbcast:%17" DPPM
;                      : "+v"(s[0]), "+v"(s[1]), "+v"(s[2]), "+v"(s[3])
;                      : "v"(a[0]), "v"(a[1]), "v"(a[2]), "v"(a[3]), "v"(S[K]), "v"(S[K + 1]), "v"(S[K + 2]), "v"(S[K + 3]), "v"(S[K + 4]), "v"(S[K + 5]), "v"(S[K + 6]), "v"(S[K + 7]), "n"(N0), "n"(N1));
;         if constexpr (K + 8 < 64) ScanK<K + 8>::dot(S, a, s);
;     }
;     static __device__ __forceinline__ void upd(float (&S)[64], const In2& in, float sa, float vv, float& y0, float& y1) {
;         float t0, t1, t2, t3;
;         asm volatile("v_mul_f32_dpp %0, %10, %27 row_newbcast:%28" DPPM "v_mul_f32_dpp %1, %11, %27 row_newbcast:%28" DPPM "v_mul_f32_dpp %2, %12, %27 row_newbcast:%28" DPPM "v_mul_f32_dpp %3, %13, %27 row_newbcast:%28" DPPM
;                      "v_fmac_f32_dpp %0, %14, %6 row_newbcast:%28" DPPM "v_fmac_f32_dpp %1, %15, %7 row_newbcast:%28" DPPM "v_fmac_f32_dpp %2, %16, %8 row_newbcast:%28" DPPM "v_fmac_f32_dpp %3, %17, %9 row_newbcast:%28" DPPM
.Lmy_p2d0_nost:
	buffer_load_dwordx4 v[156:159], v204, s[64:67], s72 offen
	buffer_load_dwordx4 v[160:163], v204, s[64:67], s73 offen
	buffer_load_dwordx4 v[164:167], v204, s[64:67], s74 offen
	buffer_load_dwordx4 v[168:171], v204, s[64:67], s75 offen
	buffer_load_dwordx2 v[172:173], v205, s[64:67], s76 offen
	buffer_load_ushort v174, v206, s[64:67], s77 offen
	s_cmp_lt_u32 s80, 255
	s_cselect_b32 s81, 0x1000, 0
	s_cselect_b32 s82, 0x800, 0
	s_cselect_b32 s9, 1, 0
	s_add_u32 s80, s80, s9
	s_add_u32 s72, s72, s81
	s_add_u32 s73, s73, s81
	s_add_u32 s74, s74, s81
	s_add_u32 s75, s75, s81
	s_add_u32 s78, s78, s81
	s_add_u32 s76, s76, s82
	s_add_u32 s77, s77, s82
	v_pk_mul_f32 v[224:225], v[100:101], v[216:217]
	v_pk_mul_f32 v[226:227], v[102:103], v[218:219]
	v_pk_mul_f32 v[216:217], v[216:217], v[96:97]
	v_pk_mul_f32 v[218:219], v[218:219], v[98:99]
	v_pk_fma_f32 v[184:185], v[104:105], v[188:189], v[192:193]
	v_pk_fma_f32 v[186:187], v[106:107], v[190:191], v[194:195]
	v_pk_mul_f32 v[176:177], v[100:101], v[104:105]
	v_pk_mul_f32 v[178:179], v[102:103], v[106:107]
	v_rcp_f32_e32 v220, v216
	v_rcp_f32_e32 v221, v217
	v_rcp_f32_e32 v222, v218
	v_rcp_f32_e32 v223, v219
	v_lshlrev_b32_e32 v180, 16, v112
	v_and_b32_e32 v181, 0xffff0000, v112
	v_lshlrev_b32_e32 v182, 16, v113
	v_and_b32_e32 v183, 0xffff0000, v113
	v_pk_mul_f32 v[180:181], v[180:181], v[184:185]
	v_pk_mul_f32 v[182:183], v[182:183], v[186:187]
	v_pk_mul_f32 v[228:229], v[108:109], v[216:217]
	v_pk_mul_f32 v[230:231], v[110:111], v[218:219]
	v_pk_mul_f32 v[176:177], v[176:177], v[220:221]
	v_pk_mul_f32 v[178:179], v[178:179], v[222:223]
	v_pk_mul_f32 v[180:181], v[180:181], v[220:221]
	v_pk_mul_f32 v[182:183], v[182:183], v[222:223]
	v_lshlrev_b32_e32 v203, 16, v114
	ds_write_b128 v208, v[176:179]
	ds_write_b128 v208, v[180:183] offset:256
	ds_read2_b32 v[64:65], v209 offset0:0 offset1:4
	ds_read2_b32 v[66:67], v209 offset0:8 offset1:12
	ds_read2_b32 v[68:69], v209 offset0:16 offset1:20
	ds_read2_b32 v[70:71], v209 offset0:24 offset1:28
	ds_read2_b32 v[72:73], v209 offset0:32 offset1:36
	ds_read2_b32 v[74:75], v209 offset0:40 offset1:44
	ds_read2_b32 v[76:77], v209 offset0:48 offset1:52
	ds_read2_b32 v[78:79], v209 offset0:56 offset1:60
	ds_read2_b32 v[80:81], v209 offset0:64 offset1:68
	ds_read2_b32 v[82:83], v209 offset0:72 offset1:76
	ds_read2_b32 v[84:85], v209 offset0:80 offset1:84
	ds_read2_b32 v[86:87], v209 offset0:88 offset1:92
	ds_read2_b32 v[88:89], v209 offset0:96 offset1:100
	ds_read2_b32 v[90:91], v209 offset0:104 offset1:108
	ds_read2_b32 v[92:93], v209 offset0:112 offset1:116
	ds_read2_b32 v[94:95], v209 offset0:120 offset1:124
	v_mul_f32_dpp v196, v224, v0 row_newbcast:0 row_mask:0xf bank_mask:0xf
	v_mul_f32_dpp v197, v225, v1 row_newbcast:0 row_mask:0xf bank_mask:0xf
	v_mul_f32_dpp v198, v226, v2 row_newbcast:0 row_mask:0xf bank_mask:0xf
	v_mul_f32_dpp v199, v227, v3 row_newbcast:0 row_mask:0xf bank_mask:0xf
	v_fmac_f32_dpp v196, v224, v4 row_newbcast:1 row_mask:0xf bank_mask:0xf
	v_fmac_f32_dpp v197, v225, v5 row_newbcast:1 row_mask:0xf bank_mask:0xf
	v_fmac_f32_dpp v198, v226, v6 row_newbcast:1 row_mask:0xf bank_mask:0xf
	v_fmac_f32_dpp v199, v227, v7 row_newbcast:1 row_mask:0xf bank_mask:0xf
	v_fmac_f32_dpp v196, v224, v8 row_newbcast:2 row_mask:0xf bank_mask:0xf
	v_fmac_f32_dpp v197, v225, v9 row_newbcast:2 row_mask:0xf bank_mask:0xf
	v_fmac_f32_dpp v198, v226, v10 row_newbcast:2 row_mask:0xf bank_mask:0xf
	v_fmac_f32_dpp v199, v227, v11 row_newbcast:2 row_mask:0xf bank_mask:0xf
	v_fmac_f32_dpp v196, v224, v12 row_newbcast:3 row_mask:0xf bank_mask:0xf
	v_fmac_f32_dpp v197, v225, v13 row_newbcast:3 row_mask:0xf bank_mask:0xf
	v_fmac_f32_dpp v198, v226, v14 row_newbcast:3 row_mask:0xf bank_mask:0xf
	v_fmac_f32_dpp v199, v227, v15 row_newbcast:3 row_mask:0xf bank_mask:0xf
	v_fmac_f32_dpp v196, v224, v16 row_newbcast:4 row_mask:0xf bank_mask:0xf
	v_fmac_f32_dpp v197, v225, v17 row_newbcast:4 row_mask:0xf bank_mask:0xf
	v_fmac_f32_dpp v198, v226, v18 row_newbcast:4 row_mask:0xf bank_mask:0xf
	v_fmac_f32_dpp v199, v227, v19 row_newbcast:4 row_mask:0xf bank_mask:0xf
	v_fmac_f32_dpp v196, v224, v20 row_newbcast:5 row_mask:0xf bank_mask:0xf
	v_fmac_f32_dpp v197, v225, v21 row_newbcast:5 row_mask:0xf bank_mask:0xf
	v_fmac_f32_dpp v198, v226, v22 row_newbcast:5 row_mask:0xf bank_mask:0xf
	v_fmac_f32_dpp v199, v227, v23 row_newbcast:5 row_mask:0xf bank_mask:0xf
	v_fmac_f32_dpp v196, v224, v24 row_newbcast:6 row_mask:0xf bank_mask:0xf
	v_fmac_f32_dpp v197, v225, v25 row_newbcast:6 row_mask:0xf bank_mask:0xf
	v_fmac_f32_dpp v198, v226, v26 row_newbcast:6 row_mask:0xf bank_mask:0xf
	v_fmac_f32_dpp v199, v227, v27 row_newbcast:6 row_mask:0xf bank_mask:0xf
	v_fmac_f32_dpp v196, v224, v28 row_newbcast:7 row_mask:0xf bank_mask:0xf
	v_fmac_f32_dpp v197, v225, v29 row_newbcast:7 row_mask:0xf bank_mask:0xf
	v_fmac_f32_dpp v198, v226, v30 row_newbcast:7 row_mask:0xf bank_mask:0xf
	v_fmac_f32_dpp v199, v227, v31 row_newbcast:7 row_mask:0xf bank_mask:0xf
	v_fmac_f32_dpp v196, v224, v32 row_newbcast:8 row_mask:0xf bank_mask:0xf
	v_fmac_f32_dpp v197, v225, v33 row_newbcast:8 row_mask:0xf bank_mask:0xf
	v_fmac_f32_dpp v198, v226, v34 row_newbcast:8 row_mask:0xf bank_mask:0xf
	v_fmac_f32_dpp v199, v227, v35 row_newbcast:8 row_mask:0xf bank_mask:0xf
	v_fmac_f32_dpp v196, v224, v36 row_newbcast:9 row_mask:0xf bank_mask:0xf
	v_fmac_f32_dpp v197, v225, v37 row_newbcast:9 row_mask:0xf bank_mask:0xf
	v_fmac_f32_dpp v198, v226, v38 row_newbcast:9 row_mask:0xf bank_mask:0xf
	v_fmac_f32_dpp v199, v227, v39 row_newbcast:9 row_mask:0xf bank_mask:0xf
	v_fmac_f32_dpp v196, v224, v40 row_newbcast:10 row_mask:0xf bank_mask:0xf
;     static __device__ __forceinline__ void dot(const float (&S)[64], const f32x4& a, float (&s)[4]) {
;         if constexpr (K == 0) {
;             asm volatile("v_mul_f32_dpp %0, %4, %8 row_newbcast:%16" DPPM "v_mul_f32_dpp %1, %5, %9 row_newbcast:%16" DPPM "v_mul_f32_dpp %2, %6, %10 row_newbcast:%16" DPPM "v_mul_f32_dpp %3, %7, %11 row_newbcast:%16" DPPM
;                          "v_fmac_f32_dpp %0, %4, %12 row_newbcast:%17" DPPM "v_fmac_f32_dpp %1, %5, %13 row_newbcast:%17" DPPM "v_fmac_f32_dpp %2, %6, %14 row_newbcast:%17" DPPM "v_fmac_f32_dpp %3, %7, %15 row_newbcast:%17" DPPM
;                          : "=&v"(s[0]), "=&v"(s[1]), "=&v"(s[2]), "=&v"(s[3])
;                          : "v"(a[0]), "v"(a[1]), "v"(a[2]), "v"(a[3]), "v"(S[K]), "v"(S[K + 1]), "v"(S[K + 2]), "v"(S[K + 3]), "v"(S[K + 4]), "v"(S[K + 5]), "v"(S[K + 6]), "v"(S[K + 7]), "n"(N0), "n"(N1));
;         } else
;         asm volatile("v_fmac_f32_dpp %0, %4, %8 row_newbcast:%16" DPPM "v_fmac_f32_dpp %1, %5, %9 row_newbcast:%16" DPPM "v_fmac_f32_dpp %2, %6, %10 row_newbcast:%16" DPPM "v_fmac_f32_dpp %3, %7, %11 row_newbcast:%16" DPPM
;                      "v_fmac_f32_dpp %0, %4, %12 row_newbcast:%17" DPPM "v_fmac_f32_dpp %1, %5, %13 row_newbcast:%17" DPPM "v_fmac_f32_dpp %2, %6, %14 row_newbcast:%17" DPPM "v_fmac_f32_dpp %3, %7, %15 row_newbcast:%17" DPPM
;                      : "+v"(s[0]), "+v"(s[1]), "+v"(s[2]), "+v"(s[3])
;                      : "v"(a[0]), "v"(a[1]), "v"(a[2]), "v"(a[3]), "v"(S[K]), "v"(S[K + 1]), "v"(S[K + 2]), "v"(S[K + 3]), "v"(S[K + 4]), "v"(S[K + 5]), "v"(S[K + 6]), "v"(S[K + 7]), "n"(N0), "n"(N1));
;         if constexpr (K + 8 < 64) ScanK<K + 8>::dot(S, a, s);
;     }
;     static __device__ __forceinline__ void upd(float (&S)[64], const In2& in, float sa, float vv, float& y0, float& y1) {
;         float t0, t1, t2, t3;
;         asm volatile("v_mul_f32_dpp %0, %10, %27 row_newbcast:%28" DPPM "v_mul_f32_dpp %1, %11, %27 row_newbcast:%28" DPPM "v_mul_f32_dpp %2, %12, %27 row_newbcast:%28" DPPM "v_mul_f32_dpp %3, %13, %27 row_newbcast:%28" DPPM
;                      "v_fmac_f32_dpp %0, %14, %6 row_newbcast:%28" DPPM "v_fmac_f32_dpp %1, %15, %7 row_newbcast:%28" DPPM "v_fmac_f32_dpp %2, %16, %8 row_newbcast:%28" DPPM "v_fmac_f32_dpp %3, %17, %9 row_newbcast:%28" DPPM
	v_fmac_f32_dpp v197, v225, v41 row_newbcast:10 row_mask:0xf bank_mask:0xf
	v_fmac_f32_dpp v198, v226, v42 row_newbcast:10 row_mask:0xf bank_mask:0xf
	v_fmac_f32_dpp v199, v227, v43 row_newbcast:10 row_mask:0xf bank_mask:0xf
	v_fmac_f32_dpp v196, v224, v44 row_newbcast:11 row_mask:0xf bank_mask:0xf
	v_fmac_f32_dpp v197, v225, v45 row_newbcast:11 row_mask:0xf bank_mask:0xf
	v_fmac_f32_dpp v198, v226, v46 row_newbcast:11 row_mask:0xf bank_mask:0xf
	v_fmac_f32_dpp v199, v227, v47 row_newbcast:11 row_mask:0xf bank_mask:0xf
	v_fmac_f32_dpp v196, v224, v48 row_newbcast:12 row_mask:0xf bank_mask:0xf
	v_fmac_f32_dpp v197, v225, v49 row_newbcast:12 row_mask:0xf bank_mask:0xf
	v_fmac_f32_dpp v198, v226, v50 row_newbcast:12 row_mask:0xf bank_mask:0xf
	v_fmac_f32_dpp v199, v227, v51 row_newbcast:12 row_mask:0xf bank_mask:0xf
	v_fmac_f32_dpp v196, v224, v52 row_newbcast:13 row_mask:0xf bank_mask:0xf
	v_fmac_f32_dpp v197, v225, v53 row_newbcast:13 row_mask:0xf bank_mask:0xf
	v_fmac_f32_dpp v198, v226, v54 row_newbcast:13 row_mask:0xf bank_mask:0xf
	v_fmac_f32_dpp v199, v227, v55 row_newbcast:13 row_mask:0xf bank_mask:0xf
	v_fmac_f32_dpp v196, v224, v56 row_newbcast:14 row_mask:0xf bank_mask:0xf
	v_fmac_f32_dpp v197, v225, v57 row_newbcast:14 row_mask:0xf bank_mask:0xf
	v_fmac_f32_dpp v198, v226, v58 row_newbcast:14 row_mask:0xf bank_mask:0xf
	v_fmac_f32_dpp v199, v227, v59 row_newbcast:14 row_mask:0xf bank_mask:0xf
	v_fmac_f32_dpp v196, v224, v60 row_newbcast:15 row_mask:0xf bank_mask:0xf
	v_fmac_f32_dpp v197, v225, v61 row_newbcast:15 row_mask:0xf bank_mask:0xf
	v_fmac_f32_dpp v198, v226, v62 row_newbcast:15 row_mask:0xf bank_mask:0xf
	v_fmac_f32_dpp v199, v227, v63 row_newbcast:15 row_mask:0xf bank_mask:0xf
	v_add_f32_e32 v196, v196, v197
	v_add_f32_e32 v198, v198, v199
	v_add_f32_e32 v196, v196, v198
	v_xor_b32_e32 v202, 0x80000000, v196
	s_waitcnt lgkmcnt(0)
	s_nop 1
	v_mfma_f32_4x4x1_16b_f32 v[0:3], v64, v202, v[0:3]
	v_mfma_f32_4x4x1_16b_f32 v[4:7], v65, v202, v[4:7]
	v_mfma_f32_4x4x1_16b_f32 v[8:11], v66, v202, v[8:11]
	v_mfma_f32_4x4x1_16b_f32 v[12:15], v67, v202, v[12:15]
	v_mfma_f32_4x4x1_16b_f32 v[16:19], v68, v202, v[16:19]
	v_mfma_f32_4x4x1_16b_f32 v[20:23], v69, v202, v[20:23]
	v_mfma_f32_4x4x1_16b_f32 v[24:27], v70, v202, v[24:27]
	v_mfma_f32_4x4x1_16b_f32 v[28:31], v71, v202, v[28:31]
	v_mfma_f32_4x4x1_16b_f32 v[32:35], v72, v202, v[32:35]
	v_mfma_f32_4x4x1_16b_f32 v[36:39], v73, v202, v[36:39]
	v_mfma_f32_4x4x1_16b_f32 v[40:43], v74, v202, v[40:43]
	v_mfma_f32_4x4x1_16b_f32 v[44:47], v75, v202, v[44:47]
	v_mfma_f32_4x4x1_16b_f32 v[48:51], v76, v202, v[48:51]
	v_mfma_f32_4x4x1_16b_f32 v[52:55], v77, v202, v[52:55]
	v_mfma_f32_4x4x1_16b_f32 v[56:59], v78, v202, v[56:59]
	v_mfma_f32_4x4x1_16b_f32 v[60:63], v79, v202, v[60:63]
	v_mfma_f32_4x4x1_16b_f32 v[0:3], v80, v203, v[0:3]
	v_mfma_f32_4x4x1_16b_f32 v[4:7], v81, v203, v[4:7]
	v_mfma_f32_4x4x1_16b_f32 v[8:11], v82, v203, v[8:11]
	v_mfma_f32_4x4x1_16b_f32 v[12:15], v83, v203, v[12:15]
	v_mfma_f32_4x4x1_16b_f32 v[16:19], v84, v203, v[16:19]
	v_mfma_f32_4x4x1_16b_f32 v[20:23], v85, v203, v[20:23]
	v_mfma_f32_4x4x1_16b_f32 v[24:27], v86, v203, v[24:27]
	v_mfma_f32_4x4x1_16b_f32 v[28:31], v87, v203, v[28:31]
	v_mfma_f32_4x4x1_16b_f32 v[32:35], v88, v203, v[32:35]
	v_mfma_f32_4x4x1_16b_f32 v[36:39], v89, v203, v[36:39]
	v_mfma_f32_4x4x1_16b_f32 v[40:43], v90, v203, v[40:43]
	v_mfma_f32_4x4x1_16b_f32 v[44:47], v91, v203, v[44:47]
	v_mfma_f32_4x4x1_16b_f32 v[48:51], v92, v203, v[48:51]
	v_mfma_f32_4x4x1_16b_f32 v[52:55], v93, v203, v[52:55]
	v_mfma_f32_4x4x1_16b_f32 v[56:59], v94, v203, v[56:59]
	v_mfma_f32_4x4x1_16b_f32 v[60:63], v95, v203, v[60:63]
	v_mul_f32_dpp v200, v228, v0 row_newbcast:0 row_mask:0xf bank_mask:0xf
	v_mul_f32_dpp v201, v229, v1 row_newbcast:0 row_mask:0xf bank_mask:0xf
	v_fmac_f32_dpp v200, v230, v2 row_newbcast:0 row_mask:0xf bank_mask:0xf
	v_fmac_f32_dpp v201, v231, v3 row_newbcast:0 row_mask:0xf bank_mask:0xf
	v_fmac_f32_dpp v200, v228, v4 row_newbcast:1 row_mask:0xf bank_mask:0xf
	v_fmac_f32_dpp v201, v229, v5 row_newbcast:1 row_mask:0xf bank_mask:0xf
	v_fmac_f32_dpp v200, v230, v6 row_newbcast:1 row_mask:0xf bank_mask:0xf
	v_fmac_f32_dpp v201, v231, v7 row_newbcast:1 row_mask:0xf bank_mask:0xf
	v_fmac_f32_dpp v200, v228, v8 row_newbcast:2 row_mask:0xf bank_mask:0xf
	v_fmac_f32_dpp v201, v229, v9 row_newbcast:2 row_mask:0xf bank_mask:0xf
	v_fmac_f32_dpp v200, v230, v10 row_newbcast:2 row_mask:0xf bank_mask:0xf
	v_fmac_f32_dpp v201, v231, v11 row_newbcast:2 row_mask:0xf bank_mask:0xf
	v_fmac_f32_dpp v200, v228, v12 row_newbcast:3 row_mask:0xf bank_mask:0xf
	v_fmac_f32_dpp v201, v229, v13 row_newbcast:3 row_mask:0xf bank_mask:0xf
	v_fmac_f32_dpp v200, v230, v14 row_newbcast:3 row_mask:0xf bank_mask:0xf
	v_fmac_f32_dpp v201, v231, v15 row_newbcast:3 row_mask:0xf bank_mask:0xf
	v_fmac_f32_dpp v200, v228, v16 row_newbcast:4 row_mask:0xf bank_mask:0xf
	v_fmac_f32_dpp v201, v229, v17 row_newbcast:4 row_mask:0xf bank_mask:0xf
	v_fmac_f32_dpp v200, v230, v18 row_newbcast:4 row_mask:0xf bank_mask:0xf
	v_fmac_f32_dpp v201, v231, v19 row_newbcast:4 row_mask:0xf bank_mask:0xf
	v_fmac_f32_dpp v200, v228, v20 row_newbcast:5 row_mask:0xf bank_mask:0xf
	v_fmac_f32_dpp v201, v229, v21 row_newbcast:5 row_mask:0xf bank_mask:0xf
	v_fmac_f32_dpp v200, v230, v22 row_newbcast:5 row_mask:0xf bank_mask:0xf
	v_fmac_f32_dpp v201, v231, v23 row_newbcast:5 row_mask:0xf bank_mask:0xf
	v_fmac_f32_dpp v200, v228, v24 row_newbcast:6 row_mask:0xf bank_mask:0xf
	v_fmac_f32_dpp v201, v229, v25 row_newbcast:6 row_mask:0xf bank_mask:0xf
	v_fmac_f32_dpp v200, v230, v26 row_newbcast:6 row_mask:0xf bank_mask:0xf
; #define SB __builtin_amdgcn_sched_barrier(0)
; #define ST2(set, s) { DERIVE_BK(set); float sd[4]; ScanK<0>::dot(S, set.a, sd); float y0 = set.yo, y1 = 0.f; ScanK<0>::upd(S, set, -((sd[0] + sd[1]) + (sd[2] + sd[3])), __uint_as_float(set.v << 16), y0, y1); __builtin_amdgcn_raw_buffer_store_b32(__float_as_uint(y0 + y1), rY, lo4b, ob4 + (unsigned)((int)(s) * (int)stp * 4), 0); }
;     static __device__ __forceinline__ void upd(float (&S)[64], const In2& in, float sa, float vv, float& y0, float& y1) {
;         float t0, t1, t2, t3;
;         asm volatile("v_mul_f32_dpp %0, %10, %27 row_newbcast:%28" DPPM "v_mul_f32_dpp %1, %11, %27 row_newbcast:%28" DPPM "v_mul_f32_dpp %2, %12, %27 row_newbcast:%28" DPPM "v_mul_f32_dpp %3, %13, %27 row_newbcast:%28" DPPM
;                      "v_fmac_f32_dpp %0, %14, %6 row_newbcast:%28" DPPM "v_fmac_f32_dpp %1, %15, %7 row_newbcast:%28" DPPM "v_fmac_f32_dpp %2, %16, %8 row_newbcast:%28" DPPM "v_fmac_f32_dpp %3, %17, %9 row_newbcast:%28" DPPM
;                      "v_fmac_f32_dpp %0, %18, %26 row_newbcast:%28" DPPM "v_fmac_f32_dpp %1, %19, %26 row_newbcast:%28" DPPM "v_fmac_f32_dpp %2, %20, %26 row_newbcast:%28" DPPM "v_fmac_f32_dpp %3, %21, %26 row_newbcast:%28" DPPM
;                      "v_fmac_f32_dpp %4, %22, %0 row_newbcast:%28" DPPM "v_fmac_f32_dpp %5, %23, %1 row_newbcast:%28" DPPM "v_fmac_f32_dpp %4, %24, %2 row_newbcast:%28" DPPM "v_fmac_f32_dpp %5, %25, %3 row_newbcast:%28" DPPM
;                      : "=&v"(t0), "=&v"(t1), "=&v"(t2), "=&v"(t3), "+v"(y0), "+v"(y1)
;                      : "v"(S[K]), "v"(S[K + 1]), "v"(S[K + 2]), "v"(S[K + 3]), "v"(in.kd[0]), "v"(in.kd[1]), "v"(in.kd[2]), "v"(in.kd[3]), "v"(in.w[0]), "v"(in.w[1]), "v"(in.w[2]), "v"(in.w[3]),
;                        "v"(in.b[0]), "v"(in.b[1]), "v"(in.b[2]), "v"(in.b[3]), "v"(in.r[0]), "v"(in.r[1]), "v"(in.r[2]), "v"(in.r[3]), "v"(sa), "v"(vv), "n"(N0));
;         S[K] = t0; S[K + 1] = t1; S[K + 2] = t2; S[K + 3] = t3;
;         if constexpr (K + 4 < 64) ScanK<K + 4>::upd(S, in, sa, vv, y0, y1);
; __device__ __forceinline__ void scan_pass2(const Params& p, int d) {
;     ...
;         In2 i0, i1; LD2(i0, 0);
; #pragma unroll 1
;         for (int s = 0; s < LC; s += 2) { TOUCH2(i0); SB; LD2(i1, s + 1); SB; ST2(i0, s); TOUCH2(i1); SB; LD2(i0, s + 2); SB; ST2(i1, s + 1); }
	v_fmac_f32_dpp v201, v231, v27 row_newbcast:6 row_mask:0xf bank_mask:0xf
	v_fmac_f32_dpp v200, v228, v28 row_newbcast:7 row_mask:0xf bank_mask:0xf
	v_fmac_f32_dpp v201, v229, v29 row_newbcast:7 row_mask:0xf bank_mask:0xf
	v_fmac_f32_dpp v200, v230, v30 row_newbcast:7 row_mask:0xf bank_mask:0xf
	v_fmac_f32_dpp v201, v231, v31 row_newbcast:7 row_mask:0xf bank_mask:0xf
	v_fmac_f32_dpp v200, v228, v32 row_newbcast:8 row_mask:0xf bank_mask:0xf
	v_fmac_f32_dpp v201, v229, v33 row_newbcast:8 row_mask:0xf bank_mask:0xf
	v_fmac_f32_dpp v200, v230, v34 row_newbcast:8 row_mask:0xf bank_mask:0xf
	v_fmac_f32_dpp v201, v231, v35 row_newbcast:8 row_mask:0xf bank_mask:0xf
	v_fmac_f32_dpp v200, v228, v36 row_newbcast:9 row_mask:0xf bank_mask:0xf
	v_fmac_f32_dpp v201, v229, v37 row_newbcast:9 row_mask:0xf bank_mask:0xf
	v_fmac_f32_dpp v200, v230, v38 row_newbcast:9 row_mask:0xf bank_mask:0xf
	v_fmac_f32_dpp v201, v231, v39 row_newbcast:9 row_mask:0xf bank_mask:0xf
	v_fmac_f32_dpp v200, v228, v40 row_newbcast:10 row_mask:0xf bank_mask:0xf
	v_fmac_f32_dpp v201, v229, v41 row_newbcast:10 row_mask:0xf bank_mask:0xf
	v_fmac_f32_dpp v200, v230, v42 row_newbcast:10 row_mask:0xf bank_mask:0xf
	v_fmac_f32_dpp v201, v231, v43 row_newbcast:10 row_mask:0xf bank_mask:0xf
	v_fmac_f32_dpp v200, v228, v44 row_newbcast:11 row_mask:0xf bank_mask:0xf
	v_fmac_f32_dpp v201, v229, v45 row_newbcast:11 row_mask:0xf bank_mask:0xf
	v_fmac_f32_dpp v200, v230, v46 row_newbcast:11 row_mask:0xf bank_mask:0xf
	v_fmac_f32_dpp v201, v231, v47 row_newbcast:11 row_mask:0xf bank_mask:0xf
	v_fmac_f32_dpp v200, v228, v48 row_newbcast:12 row_mask:0xf bank_mask:0xf
	v_fmac_f32_dpp v201, v229, v49 row_newbcast:12 row_mask:0xf bank_mask:0xf
	v_fmac_f32_dpp v200, v230, v50 row_newbcast:12 row_mask:0xf bank_mask:0xf
	v_fmac_f32_dpp v201, v231, v51 row_newbcast:12 row_mask:0xf bank_mask:0xf
	v_fmac_f32_dpp v200, v228, v52 row_newbcast:13 row_mask:0xf bank_mask:0xf
	v_fmac_f32_dpp v201, v229, v53 row_newbcast:13 row_mask:0xf bank_mask:0xf
	v_fmac_f32_dpp v200, v230, v54 row_newbcast:13 row_mask:0xf bank_mask:0xf
	v_fmac_f32_dpp v201, v231, v55 row_newbcast:13 row_mask:0xf bank_mask:0xf
	v_fmac_f32_dpp v200, v228, v56 row_newbcast:14 row_mask:0xf bank_mask:0xf
	v_fmac_f32_dpp v201, v229, v57 row_newbcast:14 row_mask:0xf bank_mask:0xf
	v_fmac_f32_dpp v200, v230, v58 row_newbcast:14 row_mask:0xf bank_mask:0xf
	v_fmac_f32_dpp v201, v231, v59 row_newbcast:14 row_mask:0xf bank_mask:0xf
	v_fmac_f32_dpp v200, v228, v60 row_newbcast:15 row_mask:0xf bank_mask:0xf
	v_fmac_f32_dpp v201, v229, v61 row_newbcast:15 row_mask:0xf bank_mask:0xf
	v_fmac_f32_dpp v200, v230, v62 row_newbcast:15 row_mask:0xf bank_mask:0xf
	v_fmac_f32_dpp v201, v231, v63 row_newbcast:15 row_mask:0xf bank_mask:0xf
	v_add_f32_e32 v200, v200, v201
	s_waitcnt vmcnt(12)
	buffer_store_dword v200, v207, s[68:71], s79 offen
	s_add_u32 s79, s79, 0x1000
	buffer_load_dwordx4 v[96:99], v204, s[64:67], s72 offen
	buffer_load_dwordx4 v[100:103], v204, s[64:67], s73 offen
	buffer_load_dwordx4 v[104:107], v204, s[64:67], s74 offen
	buffer_load_dwordx4 v[108:111], v204, s[64:67], s75 offen
	buffer_load_dwordx2 v[112:113], v205, s[64:67], s76 offen
	buffer_load_ushort v114, v206, s[64:67], s77 offen
	s_cmp_lt_u32 s80, 255
	s_cselect_b32 s81, 0x1000, 0
	s_cselect_b32 s82, 0x800, 0
	s_cselect_b32 s9, 1, 0
	s_add_u32 s80, s80, s9
	s_add_u32 s72, s72, s81
	s_add_u32 s73, s73, s81
	s_add_u32 s74, s74, s81
	s_add_u32 s75, s75, s81
	s_add_u32 s78, s78, s81
	s_add_u32 s76, s76, s82
	s_add_u32 s77, s77, s82
	v_pk_mul_f32 v[224:225], v[120:121], v[216:217]
	v_pk_mul_f32 v[226:227], v[122:123], v[218:219]
	v_pk_mul_f32 v[216:217], v[216:217], v[116:117]
	v_pk_mul_f32 v[218:219], v[218:219], v[118:119]
	v_pk_fma_f32 v[184:185], v[124:125], v[188:189], v[192:193]
	v_pk_fma_f32 v[186:187], v[126:127], v[190:191], v[194:195]
	v_pk_mul_f32 v[176:177], v[120:121], v[124:125]
	v_pk_mul_f32 v[178:179], v[122:123], v[126:127]
	v_rcp_f32_e32 v220, v216
	v_rcp_f32_e32 v221, v217
	v_rcp_f32_e32 v222, v218
	v_rcp_f32_e32 v223, v219
	v_lshlrev_b32_e32 v180, 16, v132
	v_and_b32_e32 v181, 0xffff0000, v132
	v_lshlrev_b32_e32 v182, 16, v133
	v_and_b32_e32 v183, 0xffff0000, v133
	v_pk_mul_f32 v[180:181], v[180:181], v[184:185]
	v_pk_mul_f32 v[182:183], v[182:183], v[186:187]
	v_pk_mul_f32 v[228:229], v[128:129], v[216:217]
	v_pk_mul_f32 v[230:231], v[130:131], v[218:219]
	v_pk_mul_f32 v[176:177], v[176:177], v[220:221]
	v_pk_mul_f32 v[178:179], v[178:179], v[222:223]
	v_pk_mul_f32 v[180:181], v[180:181], v[220:221]
	v_pk_mul_f32 v[182:183], v[182:183], v[222:223]
	v_lshlrev_b32_e32 v203, 16, v134
	ds_write_b128 v208, v[176:179]
	ds_write_b128 v208, v[180:183] offset:256
	ds_read2_b32 v[64:65], v209 offset0:0 offset1:4
	ds_read2_b32 v[66:67], v209 offset0:8 offset1:12
	ds_read2_b32 v[68:69], v209 offset0:16 offset1:20
	ds_read2_b32 v[70:71], v209 offset0:24 offset1:28
	ds_read2_b32 v[72:73], v209 offset0:32 offset1:36
	ds_read2_b32 v[74:75], v209 offset0:40 offset1:44
	ds_read2_b32 v[76:77], v209 offset0:48 offset1:52
	ds_read2_b32 v[78:79], v209 offset0:56 offset1:60
	ds_read2_b32 v[80:81], v209 offset0:64 offset1:68
	ds_read2_b32 v[82:83], v209 offset0:72 offset1:76
	ds_read2_b32 v[84:85], v209 offset0:80 offset1:84
	ds_read2_b32 v[86:87], v209 offset0:88 offset1:92
	ds_read2_b32 v[88:89], v209 offset0:96 offset1:100
	ds_read2_b32 v[90:91], v209 offset0:104 offset1:108
	ds_read2_b32 v[92:93], v209 offset0:112 offset1:116
	ds_read2_b32 v[94:95], v209 offset0:120 offset1:124
	v_mul_f32_dpp v196, v224, v0 row_newbcast:0 row_mask:0xf bank_mask:0xf
	v_mul_f32_dpp v197, v225, v1 row_newbcast:0 row_mask:0xf bank_mask:0xf
;     static __device__ __forceinline__ void dot(const float (&S)[64], const f32x4& a, float (&s)[4]) {
;         if constexpr (K == 0) {
;             asm volatile("v_mul_f32_dpp %0, %4, %8 row_newbcast:%16" DPPM "v_mul_f32_dpp %1, %5, %9 row_newbcast:%16" DPPM "v_mul_f32_dpp %2, %6, %10 row_newbcast:%16" DPPM "v_mul_f32_dpp %3, %7, %11 row_newbcast:%16" DPPM
;                          "v_fmac_f32_dpp %0, %4, %12 row_newbcast:%17" DPPM "v_fmac_f32_dpp %1, %5, %13 row_newbcast:%17" DPPM "v_fmac_f32_dpp %2, %6, %14 row_newbcast:%17" DPPM "v_fmac_f32_dpp %3, %7, %15 row_newbcast:%17" DPPM
;                          : "=&v"(s[0]), "=&v"(s[1]), "=&v"(s[2]), "=&v"(s[3])
;                          : "v"(a[0]), "v"(a[1]), "v"(a[2]), "v"(a[3]), "v"(S[K]), "v"(S[K + 1]), "v"(S[K + 2]), "v"(S[K + 3]), "v"(S[K + 4]), "v"(S[K + 5]), "v"(S[K + 6]), "v"(S[K + 7]), "n"(N0), "n"(N1));
;         } else
;         asm volatile("v_fmac_f32_dpp %0, %4, %8 row_newbcast:%16" DPPM "v_fmac_f32_dpp %1, %5, %9 row_newbcast:%16" DPPM "v_fmac_f32_dpp %2, %6, %10 row_newbcast:%16" DPPM "v_fmac_f32_dpp %3, %7, %11 row_newbcast:%16" DPPM
;                      "v_fmac_f32_dpp %0, %4, %12 row_newbcast:%17" DPPM "v_fmac_f32_dpp %1, %5, %13 row_newbcast:%17" DPPM "v_fmac_f32_dpp %2, %6, %14 row_newbcast:%17" DPPM "v_fmac_f32_dpp %3, %7, %15 row_newbcast:%17" DPPM
;                      : "+v"(s[0]), "+v"(s[1]), "+v"(s[2]), "+v"(s[3])
;                      : "v"(a[0]), "v"(a[1]), "v"(a[2]), "v"(a[3]), "v"(S[K]), "v"(S[K + 1]), "v"(S[K + 2]), "v"(S[K + 3]), "v"(S[K + 4]), "v"(S[K + 5]), "v"(S[K + 6]), "v"(S[K + 7]), "n"(N0), "n"(N1));
;         if constexpr (K + 8 < 64) ScanK<K + 8>::dot(S, a, s);
;     }
	v_mul_f32_dpp v198, v226, v2 row_newbcast:0 row_mask:0xf bank_mask:0xf
	v_mul_f32_dpp v199, v227, v3 row_newbcast:0 row_mask:0xf bank_mask:0xf
	v_fmac_f32_dpp v196, v224, v4 row_newbcast:1 row_mask:0xf bank_mask:0xf
	v_fmac_f32_dpp v197, v225, v5 row_newbcast:1 row_mask:0xf bank_mask:0xf
	v_fmac_f32_dpp v198, v226, v6 row_newbcast:1 row_mask:0xf bank_mask:0xf
	v_fmac_f32_dpp v199, v227, v7 row_newbcast:1 row_mask:0xf bank_mask:0xf
	v_fmac_f32_dpp v196, v224, v8 row_newbcast:2 row_mask:0xf bank_mask:0xf
	v_fmac_f32_dpp v197, v225, v9 row_newbcast:2 row_mask:0xf bank_mask:0xf
	v_fmac_f32_dpp v198, v226, v10 row_newbcast:2 row_mask:0xf bank_mask:0xf
	v_fmac_f32_dpp v199, v227, v11 row_newbcast:2 row_mask:0xf bank_mask:0xf
	v_fmac_f32_dpp v196, v224, v12 row_newbcast:3 row_mask:0xf bank_mask:0xf
	v_fmac_f32_dpp v197, v225, v13 row_newbcast:3 row_mask:0xf bank_mask:0xf
	v_fmac_f32_dpp v198, v226, v14 row_newbcast:3 row_mask:0xf bank_mask:0xf
	v_fmac_f32_dpp v199, v227, v15 row_newbcast:3 row_mask:0xf bank_mask:0xf
	v_fmac_f32_dpp v196, v224, v16 row_newbcast:4 row_mask:0xf bank_mask:0xf
	v_fmac_f32_dpp v197, v225, v17 row_newbcast:4 row_mask:0xf bank_mask:0xf
	v_fmac_f32_dpp v198, v226, v18 row_newbcast:4 row_mask:0xf bank_mask:0xf
	v_fmac_f32_dpp v199, v227, v19 row_newbcast:4 row_mask:0xf bank_mask:0xf
	v_fmac_f32_dpp v196, v224, v20 row_newbcast:5 row_mask:0xf bank_mask:0xf
	v_fmac_f32_dpp v197, v225, v21 row_newbcast:5 row_mask:0xf bank_mask:0xf
	v_fmac_f32_dpp v198, v226, v22 row_newbcast:5 row_mask:0xf bank_mask:0xf
	v_fmac_f32_dpp v199, v227, v23 row_newbcast:5 row_mask:0xf bank_mask:0xf
	v_fmac_f32_dpp v196, v224, v24 row_newbcast:6 row_mask:0xf bank_mask:0xf
	v_fmac_f32_dpp v197, v225, v25 row_newbcast:6 row_mask:0xf bank_mask:0xf
	v_fmac_f32_dpp v198, v226, v26 row_newbcast:6 row_mask:0xf bank_mask:0xf
	v_fmac_f32_dpp v199, v227, v27 row_newbcast:6 row_mask:0xf bank_mask:0xf
	v_fmac_f32_dpp v196, v224, v28 row_newbcast:7 row_mask:0xf bank_mask:0xf
	v_fmac_f32_dpp v197, v225, v29 row_newbcast:7 row_mask:0xf bank_mask:0xf
	v_fmac_f32_dpp v198, v226, v30 row_newbcast:7 row_mask:0xf bank_mask:0xf
	v_fmac_f32_dpp v199, v227, v31 row_newbcast:7 row_mask:0xf bank_mask:0xf
	v_fmac_f32_dpp v196, v224, v32 row_newbcast:8 row_mask:0xf bank_mask:0xf
	v_fmac_f32_dpp v197, v225, v33 row_newbcast:8 row_mask:0xf bank_mask:0xf
	v_fmac_f32_dpp v198, v226, v34 row_newbcast:8 row_mask:0xf bank_mask:0xf
	v_fmac_f32_dpp v199, v227, v35 row_newbcast:8 row_mask:0xf bank_mask:0xf
	v_fmac_f32_dpp v196, v224, v36 row_newbcast:9 row_mask:0xf bank_mask:0xf
	v_fmac_f32_dpp v197, v225, v37 row_newbcast:9 row_mask:0xf bank_mask:0xf
	v_fmac_f32_dpp v198, v226, v38 row_newbcast:9 row_mask:0xf bank_mask:0xf
	v_fmac_f32_dpp v199, v227, v39 row_newbcast:9 row_mask:0xf bank_mask:0xf
	v_fmac_f32_dpp v196, v224, v40 row_newbcast:10 row_mask:0xf bank_mask:0xf
	v_fmac_f32_dpp v197, v225, v41 row_newbcast:10 row_mask:0xf bank_mask:0xf
	v_fmac_f32_dpp v198, v226, v42 row_newbcast:10 row_mask:0xf bank_mask:0xf
	v_fmac_f32_dpp v199, v227, v43 row_newbcast:10 row_mask:0xf bank_mask:0xf
	v_fmac_f32_dpp v196, v224, v44 row_newbcast:11 row_mask:0xf bank_mask:0xf
	v_fmac_f32_dpp v197, v225, v45 row_newbcast:11 row_mask:0xf bank_mask:0xf
	v_fmac_f32_dpp v198, v226, v46 row_newbcast:11 row_mask:0xf bank_mask:0xf
	v_fmac_f32_dpp v199, v227, v47 row_newbcast:11 row_mask:0xf bank_mask:0xf
	v_fmac_f32_dpp v196, v224, v48 row_newbcast:12 row_mask:0xf bank_mask:0xf
	v_fmac_f32_dpp v197, v225, v49 row_newbcast:12 row_mask:0xf bank_mask:0xf
	v_fmac_f32_dpp v198, v226, v50 row_newbcast:12 row_mask:0xf bank_mask:0xf
	v_fmac_f32_dpp v199, v227, v51 row_newbcast:12 row_mask:0xf bank_mask:0xf
	v_fmac_f32_dpp v196, v224, v52 row_newbcast:13 row_mask:0xf bank_mask:0xf
	v_fmac_f32_dpp v197, v225, v53 row_newbcast:13 row_mask:0xf bank_mask:0xf
	v_fmac_f32_dpp v198, v226, v54 row_newbcast:13 row_mask:0xf bank_mask:0xf
	v_fmac_f32_dpp v199, v227, v55 row_newbcast:13 row_mask:0xf bank_mask:0xf
	v_fmac_f32_dpp v196, v224, v56 row_newbcast:14 row_mask:0xf bank_mask:0xf
	v_fmac_f32_dpp v197, v225, v57 row_newbcast:14 row_mask:0xf bank_mask:0xf
	v_fmac_f32_dpp v198, v226, v58 row_newbcast:14 row_mask:0xf bank_mask:0xf
	v_fmac_f32_dpp v199, v227, v59 row_newbcast:14 row_mask:0xf bank_mask:0xf
	v_fmac_f32_dpp v196, v224, v60 row_newbcast:15 row_mask:0xf bank_mask:0xf
	v_fmac_f32_dpp v197, v225, v61 row_newbcast:15 row_mask:0xf bank_mask:0xf
	v_fmac_f32_dpp v198, v226, v62 row_newbcast:15 row_mask:0xf bank_mask:0xf
	v_fmac_f32_dpp v199, v227, v63 row_newbcast:15 row_mask:0xf bank_mask:0xf
	v_add_f32_e32 v196, v196, v197
	v_add_f32_e32 v198, v198, v199
	v_add_f32_e32 v196, v196, v198
	v_xor_b32_e32 v202, 0x80000000, v196
	s_waitcnt lgkmcnt(0)
;     static __device__ __forceinline__ void upd(float (&S)[64], const In2& in, float sa, float vv, float& y0, float& y1) {
;         float t0, t1, t2, t3;
;         asm volatile("v_mul_f32_dpp %0, %10, %27 row_newbcast:%28" DPPM "v_mul_f32_dpp %1, %11, %27 row_newbcast:%28" DPPM "v_mul_f32_dpp %2, %12, %27 row_newbcast:%28" DPPM "v_mul_f32_dpp %3, %13, %27 row_newbcast:%28" DPPM
;                      "v_fmac_f32_dpp %0, %14, %6 row_newbcast:%28" DPPM "v_fmac_f32_dpp %1, %15, %7 row_newbcast:%28" DPPM "v_fmac_f32_dpp %2, %16, %8 row_newbcast:%28" DPPM "v_fmac_f32_dpp %3, %17, %9 row_newbcast:%28" DPPM
;                      "v_fmac_f32_dpp %0, %18, %26 row_newbcast:%28" DPPM "v_fmac_f32_dpp %1, %19, %26 row_newbcast:%28" DPPM "v_fmac_f32_dpp %2, %20, %26 row_newbcast:%28" DPPM "v_fmac_f32_dpp %3, %21, %26 row_newbcast:%28" DPPM
;                      "v_fmac_f32_dpp %4, %22, %0 row_newbcast:%28" DPPM "v_fmac_f32_dpp %5, %23, %1 row_newbcast:%28" DPPM "v_fmac_f32_dpp %4, %24, %2 row_newbcast:%28" DPPM "v_fmac_f32_dpp %5, %25, %3 row_newbcast:%28" DPPM
;                      : "=&v"(t0), "=&v"(t1), "=&v"(t2), "=&v"(t3), "+v"(y0), "+v"(y1)
;                      : "v"(S[K]), "v"(S[K + 1]), "v"(S[K + 2]), "v"(S[K + 3]), "v"(in.kd[0]), "v"(in.kd[1]), "v"(in.kd[2]), "v"(in.kd[3]), "v"(in.w[0]), "v"(in.w[1]), "v"(in.w[2]), "v"(in.w[3]),
;                        "v"(in.b[0]), "v"(in.b[1]), "v"(in.b[2]), "v"(in.b[3]), "v"(in.r[0]), "v"(in.r[1]), "v"(in.r[2]), "v"(in.r[3]), "v"(sa), "v"(vv), "n"(N0));
;         S[K] = t0; S[K + 1] = t1; S[K + 2] = t2; S[K + 3] = t3;
;         if constexpr (K + 4 < 64) ScanK<K + 4>::upd(S, in, sa, vv, y0, y1);
	s_nop 1
	v_mfma_f32_4x4x1_16b_f32 v[0:3], v64, v202, v[0:3]
	v_mfma_f32_4x4x1_16b_f32 v[4:7], v65, v202, v[4:7]
	v_mfma_f32_4x4x1_16b_f32 v[8:11], v66, v202, v[8:11]
	v_mfma_f32_4x4x1_16b_f32 v[12:15], v67, v202, v[12:15]
	v_mfma_f32_4x4x1_16b_f32 v[16:19], v68, v202, v[16:19]
	v_mfma_f32_4x4x1_16b_f32 v[20:23], v69, v202, v[20:23]
	v_mfma_f32_4x4x1_16b_f32 v[24:27], v70, v202, v[24:27]
	v_mfma_f32_4x4x1_16b_f32 v[28:31], v71, v202, v[28:31]
	v_mfma_f32_4x4x1_16b_f32 v[32:35], v72, v202, v[32:35]
	v_mfma_f32_4x4x1_16b_f32 v[36:39], v73, v202, v[36:39]
	v_mfma_f32_4x4x1_16b_f32 v[40:43], v74, v202, v[40:43]
	v_mfma_f32_4x4x1_16b_f32 v[44:47], v75, v202, v[44:47]
	v_mfma_f32_4x4x1_16b_f32 v[48:51], v76, v202, v[48:51]
	v_mfma_f32_4x4x1_16b_f32 v[52:55], v77, v202, v[52:55]
	v_mfma_f32_4x4x1_16b_f32 v[56:59], v78, v202, v[56:59]
	v_mfma_f32_4x4x1_16b_f32 v[60:63], v79, v202, v[60:63]
	v_mfma_f32_4x4x1_16b_f32 v[0:3], v80, v203, v[0:3]
	v_mfma_f32_4x4x1_16b_f32 v[4:7], v81, v203, v[4:7]
	v_mfma_f32_4x4x1_16b_f32 v[8:11], v82, v203, v[8:11]
	v_mfma_f32_4x4x1_16b_f32 v[12:15], v83, v203, v[12:15]
	v_mfma_f32_4x4x1_16b_f32 v[16:19], v84, v203, v[16:19]
	v_mfma_f32_4x4x1_16b_f32 v[20:23], v85, v203, v[20:23]
	v_mfma_f32_4x4x1_16b_f32 v[24:27], v86, v203, v[24:27]
	v_mfma_f32_4x4x1_16b_f32 v[28:31], v87, v203, v[28:31]
	v_mfma_f32_4x4x1_16b_f32 v[32:35], v88, v203, v[32:35]
	v_mfma_f32_4x4x1_16b_f32 v[36:39], v89, v203, v[36:39]
	v_mfma_f32_4x4x1_16b_f32 v[40:43], v90, v203, v[40:43]
	v_mfma_f32_4x4x1_16b_f32 v[44:47], v91, v203, v[44:47]
	v_mfma_f32_4x4x1_16b_f32 v[48:51], v92, v203, v[48:51]
	v_mfma_f32_4x4x1_16b_f32 v[52:55], v93, v203, v[52:55]
	v_mfma_f32_4x4x1_16b_f32 v[56:59], v94, v203, v[56:59]
	v_mfma_f32_4x4x1_16b_f32 v[60:63], v95, v203, v[60:63]
	v_mul_f32_dpp v200, v228, v0 row_newbcast:0 row_mask:0xf bank_mask:0xf
	v_mul_f32_dpp v201, v229, v1 row_newbcast:0 row_mask:0xf bank_mask:0xf
	v_fmac_f32_dpp v200, v230, v2 row_newbcast:0 row_mask:0xf bank_mask:0xf
	v_fmac_f32_dpp v201, v231, v3 row_newbcast:0 row_mask:0xf bank_mask:0xf
	v_fmac_f32_dpp v200, v228, v4 row_newbcast:1 row_mask:0xf bank_mask:0xf
	v_fmac_f32_dpp v201, v229, v5 row_newbcast:1 row_mask:0xf bank_mask:0xf
	v_fmac_f32_dpp v200, v230, v6 row_newbcast:1 row_mask:0xf bank_mask:0xf
	v_fmac_f32_dpp v201, v231, v7 row_newbcast:1 row_mask:0xf bank_mask:0xf
	v_fmac_f32_dpp v200, v228, v8 row_newbcast:2 row_mask:0xf bank_mask:0xf
	v_fmac_f32_dpp v201, v229, v9 row_newbcast:2 row_mask:0xf bank_mask:0xf
	v_fmac_f32_dpp v200, v230, v10 row_newbcast:2 row_mask:0xf bank_mask:0xf
	v_fmac_f32_dpp v201, v231, v11 row_newbcast:2 row_mask:0xf bank_mask:0xf
	v_fmac_f32_dpp v200, v228, v12 row_newbcast:3 row_mask:0xf bank_mask:0xf
	v_fmac_f32_dpp v201, v229, v13 row_newbcast:3 row_mask:0xf bank_mask:0xf
	v_fmac_f32_dpp v200, v230, v14 row_newbcast:3 row_mask:0xf bank_mask:0xf
	v_fmac_f32_dpp v201, v231, v15 row_newbcast:3 row_mask:0xf bank_mask:0xf
	v_fmac_f32_dpp v200, v228, v16 row_newbcast:4 row_mask:0xf bank_mask:0xf
	v_fmac_f32_dpp v201, v229, v17 row_newbcast:4 row_mask:0xf bank_mask:0xf
	v_fmac_f32_dpp v200, v230, v18 row_newbcast:4 row_mask:0xf bank_mask:0xf
	v_fmac_f32_dpp v201, v231, v19 row_newbcast:4 row_mask:0xf bank_mask:0xf
	v_fmac_f32_dpp v200, v228, v20 row_newbcast:5 row_mask:0xf bank_mask:0xf
	v_fmac_f32_dpp v201, v229, v21 row_newbcast:5 row_mask:0xf bank_mask:0xf
	v_fmac_f32_dpp v200, v230, v22 row_newbcast:5 row_mask:0xf bank_mask:0xf
	v_fmac_f32_dpp v201, v231, v23 row_newbcast:5 row_mask:0xf bank_mask:0xf
	v_fmac_f32_dpp v200, v228, v24 row_newbcast:6 row_mask:0xf bank_mask:0xf
	v_fmac_f32_dpp v201, v229, v25 row_newbcast:6 row_mask:0xf bank_mask:0xf
	v_fmac_f32_dpp v200, v230, v26 row_newbcast:6 row_mask:0xf bank_mask:0xf
	v_fmac_f32_dpp v201, v231, v27 row_newbcast:6 row_mask:0xf bank_mask:0xf
	v_fmac_f32_dpp v200, v228, v28 row_newbcast:7 row_mask:0xf bank_mask:0xf
	v_fmac_f32_dpp v201, v229, v29 row_newbcast:7 row_mask:0xf bank_mask:0xf
	v_fmac_f32_dpp v200, v230, v30 row_newbcast:7 row_mask:0xf bank_mask:0xf
	v_fmac_f32_dpp v201, v231, v31 row_newbcast:7 row_mask:0xf bank_mask:0xf
	v_fmac_f32_dpp v200, v228, v32 row_newbcast:8 row_mask:0xf bank_mask:0xf
	v_fmac_f32_dpp v201, v229, v33 row_newbcast:8 row_mask:0xf bank_mask:0xf
	v_fmac_f32_dpp v200, v230, v34 row_newbcast:8 row_mask:0xf bank_mask:0xf
	v_fmac_f32_dpp v201, v231, v35 row_newbcast:8 row_mask:0xf bank_mask:0xf
	v_fmac_f32_dpp v200, v228, v36 row_newbcast:9 row_mask:0xf bank_mask:0xf
	v_fmac_f32_dpp v201, v229, v37 row_newbcast:9 row_mask:0xf bank_mask:0xf
	v_fmac_f32_dpp v200, v230, v38 row_newbcast:9 row_mask:0xf bank_mask:0xf
	v_fmac_f32_dpp v201, v231, v39 row_newbcast:9 row_mask:0xf bank_mask:0xf
	v_fmac_f32_dpp v200, v228, v40 row_newbcast:10 row_mask:0xf bank_mask:0xf
	v_fmac_f32_dpp v201, v229, v41 row_newbcast:10 row_mask:0xf bank_mask:0xf
	v_fmac_f32_dpp v200, v230, v42 row_newbcast:10 row_mask:0xf bank_mask:0xf
	v_fmac_f32_dpp v201, v231, v43 row_newbcast:10 row_mask:0xf bank_mask:0xf
	v_fmac_f32_dpp v200, v228, v44 row_newbcast:11 row_mask:0xf bank_mask:0xf
	v_fmac_f32_dpp v201, v229, v45 row_newbcast:11 row_mask:0xf bank_mask:0xf
	v_fmac_f32_dpp v200, v230, v46 row_newbcast:11 row_mask:0xf bank_mask:0xf
	v_fmac_f32_dpp v201, v231, v47 row_newbcast:11 row_mask:0xf bank_mask:0xf
	v_fmac_f32_dpp v200, v228, v48 row_newbcast:12 row_mask:0xf bank_mask:0xf
	v_fmac_f32_dpp v201, v229, v49 row_newbcast:12 row_mask:0xf bank_mask:0xf
	v_fmac_f32_dpp v200, v230, v50 row_newbcast:12 row_mask:0xf bank_mask:0xf
	v_fmac_f32_dpp v201, v231, v51 row_newbcast:12 row_mask:0xf bank_mask:0xf
	v_fmac_f32_dpp v200, v228, v52 row_newbcast:13 row_mask:0xf bank_mask:0xf
	v_fmac_f32_dpp v201, v229, v53 row_newbcast:13 row_mask:0xf bank_mask:0xf
	v_fmac_f32_dpp v200, v230, v54 row_newbcast:13 row_mask:0xf bank_mask:0xf
	v_fmac_f32_dpp v201, v231, v55 row_newbcast:13 row_mask:0xf bank_mask:0xf
	v_fmac_f32_dpp v200, v228, v56 row_newbcast:14 row_mask:0xf bank_mask:0xf
	v_fmac_f32_dpp v201, v229, v57 row_newbcast:14 row_mask:0xf bank_mask:0xf
	v_fmac_f32_dpp v200, v230, v58 row_newbcast:14 row_mask:0xf bank_mask:0xf
	v_fmac_f32_dpp v201, v231, v59 row_newbcast:14 row_mask:0xf bank_mask:0xf
	v_fmac_f32_dpp v200, v228, v60 row_newbcast:15 row_mask:0xf bank_mask:0xf
	v_fmac_f32_dpp v201, v229, v61 row_newbcast:15 row_mask:0xf bank_mask:0xf
	v_fmac_f32_dpp v200, v230, v62 row_newbcast:15 row_mask:0xf bank_mask:0xf
	v_fmac_f32_dpp v201, v231, v63 row_newbcast:15 row_mask:0xf bank_mask:0xf
	v_add_f32_e32 v200, v200, v201
	s_waitcnt vmcnt(12)
;     static __device__ __forceinline__ void dot(const float (&S)[64], const f32x4& a, float (&s)[4]) {
;         if constexpr (K == 0) {
;             asm volatile("v_mul_f32_dpp %0, %4, %8 row_newbcast:%16" DPPM "v_mul_f32_dpp %1, %5, %9 row_newbcast:%16" DPPM "v_mul_f32_dpp %2, %6, %10 row_newbcast:%16" DPPM "v_mul_f32_dpp %3, %7, %11 row_newbcast:%16" DPPM
;                          "v_fmac_f32_dpp %0, %4, %12 row_newbcast:%17" DPPM "v_fmac_f32_dpp %1, %5, %13 row_newbcast:%17" DPPM "v_fmac_f32_dpp %2, %6, %14 row_newbcast:%17" DPPM "v_fmac_f32_dpp %3, %7, %15 row_newbcast:%17" DPPM
;                          : "=&v"(s[0]), "=&v"(s[1]), "=&v"(s[2]), "=&v"(s[3])
;                          : "v"(a[0]), "v"(a[1]), "v"(a[2]), "v"(a[3]), "v"(S[K]), "v"(S[K + 1]), "v"(S[K + 2]), "v"(S[K + 3]), "v"(S[K + 4]), "v"(S[K + 5]), "v"(S[K + 6]), "v"(S[K + 7]), "n"(N0), "n"(N1));
;         } else
;         asm volatile("v_fmac_f32_dpp %0, %4, %8 row_newbcast:%16" DPPM "v_fmac_f32_dpp %1, %5, %9 row_newbcast:%16" DPPM "v_fmac_f32_dpp %2, %6, %10 row_newbcast:%16" DPPM "v_fmac_f32_dpp %3, %7, %11 row_newbcast:%16" DPPM
;                      "v_fmac_f32_dpp %0, %4, %12 row_newbcast:%17" DPPM "v_fmac_f32_dpp %1, %5, %13 row_newbcast:%17" DPPM "v_fmac_f32_dpp %2, %6, %14 row_newbcast:%17" DPPM "v_fmac_f32_dpp %3, %7, %15 row_newbcast:%17" DPPM
;                      : "+v"(s[0]), "+v"(s[1]), "+v"(s[2]), "+v"(s[3])
;                      : "v"(a[0]), "v"(a[1]), "v"(a[2]), "v"(a[3]), "v"(S[K]), "v"(S[K + 1]), "v"(S[K + 2]), "v"(S[K + 3]), "v"(S[K + 4]), "v"(S[K + 5]), "v"(S[K + 6]), "v"(S[K + 7]), "n"(N0), "n"(N1));
;         if constexpr (K + 8 < 64) ScanK<K + 8>::dot(S, a, s);
;     }
;     static __device__ __forceinline__ void upd(float (&S)[64], const In2& in, float sa, float vv, float& y0, float& y1) {
;         float t0, t1, t2, t3;
;         asm volatile("v_mul_f32_dpp %0, %10, %27 row_newbcast:%28" DPPM "v_mul_f32_dpp %1, %11, %27 row_newbcast:%28" DPPM "v_mul_f32_dpp %2, %12, %27 row_newbcast:%28" DPPM "v_mul_f32_dpp %3, %13, %27 row_newbcast:%28" DPPM
;                      "v_fmac_f32_dpp %0, %14, %6 row_newbcast:%28" DPPM "v_fmac_f32_dpp %1, %15, %7 row_newbcast:%28" DPPM "v_fmac_f32_dpp %2, %16, %8 row_newbcast:%28" DPPM "v_fmac_f32_dpp %3, %17, %9 row_newbcast:%28" DPPM
	buffer_store_dword v200, v207, s[68:71], s79 offen
	s_add_u32 s79, s79, 0x1000
	buffer_load_dwordx4 v[116:119], v204, s[64:67], s72 offen
	buffer_load_dwordx4 v[120:123], v204, s[64:67], s73 offen
	buffer_load_dwordx4 v[124:127], v204, s[64:67], s74 offen
	buffer_load_dwordx4 v[128:131], v204, s[64:67], s75 offen
	buffer_load_dwordx2 v[132:133], v205, s[64:67], s76 offen
	buffer_load_ushort v134, v206, s[64:67], s77 offen
	s_cmp_lt_u32 s80, 255
	s_cselect_b32 s81, 0x1000, 0
	s_cselect_b32 s82, 0x800, 0
	s_cselect_b32 s9, 1, 0
	s_add_u32 s80, s80, s9
	s_add_u32 s72, s72, s81
	s_add_u32 s73, s73, s81
	s_add_u32 s74, s74, s81
	s_add_u32 s75, s75, s81
	s_add_u32 s78, s78, s81
	s_add_u32 s76, s76, s82
	s_add_u32 s77, s77, s82
	v_pk_mul_f32 v[224:225], v[140:141], v[216:217]
	v_pk_mul_f32 v[226:227], v[142:143], v[218:219]
	v_pk_mul_f32 v[216:217], v[216:217], v[136:137]
	v_pk_mul_f32 v[218:219], v[218:219], v[138:139]
	v_pk_fma_f32 v[184:185], v[144:145], v[188:189], v[192:193]
	v_pk_fma_f32 v[186:187], v[146:147], v[190:191], v[194:195]
	v_pk_mul_f32 v[176:177], v[140:141], v[144:145]
	v_pk_mul_f32 v[178:179], v[142:143], v[146:147]
	v_rcp_f32_e32 v220, v216
	v_rcp_f32_e32 v221, v217
	v_rcp_f32_e32 v222, v218
	v_rcp_f32_e32 v223, v219
	v_lshlrev_b32_e32 v180, 16, v152
	v_and_b32_e32 v181, 0xffff0000, v152
	v_lshlrev_b32_e32 v182, 16, v153
	v_and_b32_e32 v183, 0xffff0000, v153
	v_pk_mul_f32 v[180:181], v[180:181], v[184:185]
	v_pk_mul_f32 v[182:183], v[182:183], v[186:187]
	v_pk_mul_f32 v[228:229], v[148:149], v[216:217]
	v_pk_mul_f32 v[230:231], v[150:151], v[218:219]
	v_pk_mul_f32 v[176:177], v[176:177], v[220:221]
	v_pk_mul_f32 v[178:179], v[178:179], v[222:223]
	v_pk_mul_f32 v[180:181], v[180:181], v[220:221]
	v_pk_mul_f32 v[182:183], v[182:183], v[222:223]
	v_lshlrev_b32_e32 v203, 16, v154
	ds_write_b128 v208, v[176:179]
	ds_write_b128 v208, v[180:183] offset:256
	ds_read2_b32 v[64:65], v209 offset0:0 offset1:4
	ds_read2_b32 v[66:67], v209 offset0:8 offset1:12
	ds_read2_b32 v[68:69], v209 offset0:16 offset1:20
	ds_read2_b32 v[70:71], v209 offset0:24 offset1:28
	ds_read2_b32 v[72:73], v209 offset0:32 offset1:36
	ds_read2_b32 v[74:75], v209 offset0:40 offset1:44
	ds_read2_b32 v[76:77], v209 offset0:48 offset1:52
	ds_read2_b32 v[78:79], v209 offset0:56 offset1:60
	ds_read2_b32 v[80:81], v209 offset0:64 offset1:68
	ds_read2_b32 v[82:83], v209 offset0:72 offset1:76
	ds_read2_b32 v[84:85], v209 offset0:80 offset1:84
	ds_read2_b32 v[86:87], v209 offset0:88 offset1:92
	ds_read2_b32 v[88:89], v209 offset0:96 offset1:100
	ds_read2_b32 v[90:91], v209 offset0:104 offset1:108
	ds_read2_b32 v[92:93], v209 offset0:112 offset1:116
	ds_read2_b32 v[94:95], v209 offset0:120 offset1:124
	v_mul_f32_dpp v196, v224, v0 row_newbcast:0 row_mask:0xf bank_mask:0xf
	v_mul_f32_dpp v197, v225, v1 row_newbcast:0 row_mask:0xf bank_mask:0xf
	v_mul_f32_dpp v198, v226, v2 row_newbcast:0 row_mask:0xf bank_mask:0xf
	v_mul_f32_dpp v199, v227, v3 row_newbcast:0 row_mask:0xf bank_mask:0xf
	v_fmac_f32_dpp v196, v224, v4 row_newbcast:1 row_mask:0xf bank_mask:0xf
	v_fmac_f32_dpp v197, v225, v5 row_newbcast:1 row_mask:0xf bank_mask:0xf
	v_fmac_f32_dpp v198, v226, v6 row_newbcast:1 row_mask:0xf bank_mask:0xf
	v_fmac_f32_dpp v199, v227, v7 row_newbcast:1 row_mask:0xf bank_mask:0xf
	v_fmac_f32_dpp v196, v224, v8 row_newbcast:2 row_mask:0xf bank_mask:0xf
	v_fmac_f32_dpp v197, v225, v9 row_newbcast:2 row_mask:0xf bank_mask:0xf
	v_fmac_f32_dpp v198, v226, v10 row_newbcast:2 row_mask:0xf bank_mask:0xf
	v_fmac_f32_dpp v199, v227, v11 row_newbcast:2 row_mask:0xf bank_mask:0xf
	v_fmac_f32_dpp v196, v224, v12 row_newbcast:3 row_mask:0xf bank_mask:0xf
	v_fmac_f32_dpp v197, v225, v13 row_newbcast:3 row_mask:0xf bank_mask:0xf
	v_fmac_f32_dpp v198, v226, v14 row_newbcast:3 row_mask:0xf bank_mask:0xf
	v_fmac_f32_dpp v199, v227, v15 row_newbcast:3 row_mask:0xf bank_mask:0xf
	v_fmac_f32_dpp v196, v224, v16 row_newbcast:4 row_mask:0xf bank_mask:0xf
	v_fmac_f32_dpp v197, v225, v17 row_newbcast:4 row_mask:0xf bank_mask:0xf
	v_fmac_f32_dpp v198, v226, v18 row_newbcast:4 row_mask:0xf bank_mask:0xf
	v_fmac_f32_dpp v199, v227, v19 row_newbcast:4 row_mask:0xf bank_mask:0xf
	v_fmac_f32_dpp v196, v224, v20 row_newbcast:5 row_mask:0xf bank_mask:0xf
	v_fmac_f32_dpp v197, v225, v21 row_newbcast:5 row_mask:0xf bank_mask:0xf
	v_fmac_f32_dpp v198, v226, v22 row_newbcast:5 row_mask:0xf bank_mask:0xf
	v_fmac_f32_dpp v199, v227, v23 row_newbcast:5 row_mask:0xf bank_mask:0xf
	v_fmac_f32_dpp v196, v224, v24 row_newbcast:6 row_mask:0xf bank_mask:0xf
	v_fmac_f32_dpp v197, v225, v25 row_newbcast:6 row_mask:0xf bank_mask:0xf
	v_fmac_f32_dpp v198, v226, v26 row_newbcast:6 row_mask:0xf bank_mask:0xf
	v_fmac_f32_dpp v199, v227, v27 row_newbcast:6 row_mask:0xf bank_mask:0xf
	v_fmac_f32_dpp v196, v224, v28 row_newbcast:7 row_mask:0xf bank_mask:0xf
	v_fmac_f32_dpp v197, v225, v29 row_newbcast:7 row_mask:0xf bank_mask:0xf
	v_fmac_f32_dpp v198, v226, v30 row_newbcast:7 row_mask:0xf bank_mask:0xf
	v_fmac_f32_dpp v199, v227, v31 row_newbcast:7 row_mask:0xf bank_mask:0xf
	v_fmac_f32_dpp v196, v224, v32 row_newbcast:8 row_mask:0xf bank_mask:0xf
	v_fmac_f32_dpp v197, v225, v33 row_newbcast:8 row_mask:0xf bank_mask:0xf
	v_fmac_f32_dpp v198, v226, v34 row_newbcast:8 row_mask:0xf bank_mask:0xf
	v_fmac_f32_dpp v199, v227, v35 row_newbcast:8 row_mask:0xf bank_mask:0xf
	v_fmac_f32_dpp v196, v224, v36 row_newbcast:9 row_mask:0xf bank_mask:0xf
	v_fmac_f32_dpp v197, v225, v37 row_newbcast:9 row_mask:0xf bank_mask:0xf
	v_fmac_f32_dpp v198, v226, v38 row_newbcast:9 row_mask:0xf bank_mask:0xf
	v_fmac_f32_dpp v199, v227, v39 row_newbcast:9 row_mask:0xf bank_mask:0xf
;     static __device__ __forceinline__ void dot(const float (&S)[64], const f32x4& a, float (&s)[4]) {
;         if constexpr (K == 0) {
;             asm volatile("v_mul_f32_dpp %0, %4, %8 row_newbcast:%16" DPPM "v_mul_f32_dpp %1, %5, %9 row_newbcast:%16" DPPM "v_mul_f32_dpp %2, %6, %10 row_newbcast:%16" DPPM "v_mul_f32_dpp %3, %7, %11 row_newbcast:%16" DPPM
;                          "v_fmac_f32_dpp %0, %4, %12 row_newbcast:%17" DPPM "v_fmac_f32_dpp %1, %5, %13 row_newbcast:%17" DPPM "v_fmac_f32_dpp %2, %6, %14 row_newbcast:%17" DPPM "v_fmac_f32_dpp %3, %7, %15 row_newbcast:%17" DPPM
;                          : "=&v"(s[0]), "=&v"(s[1]), "=&v"(s[2]), "=&v"(s[3])
;                          : "v"(a[0]), "v"(a[1]), "v"(a[2]), "v"(a[3]), "v"(S[K]), "v"(S[K + 1]), "v"(S[K + 2]), "v"(S[K + 3]), "v"(S[K + 4]), "v"(S[K + 5]), "v"(S[K + 6]), "v"(S[K + 7]), "n"(N0), "n"(N1));
;         } else
;         asm volatile("v_fmac_f32_dpp %0, %4, %8 row_newbcast:%16" DPPM "v_fmac_f32_dpp %1, %5, %9 row_newbcast:%16" DPPM "v_fmac_f32_dpp %2, %6, %10 row_newbcast:%16" DPPM "v_fmac_f32_dpp %3, %7, %11 row_newbcast:%16" DPPM
;                      "v_fmac_f32_dpp %0, %4, %12 row_newbcast:%17" DPPM "v_fmac_f32_dpp %1, %5, %13 row_newbcast:%17" DPPM "v_fmac_f32_dpp %2, %6, %14 row_newbcast:%17" DPPM "v_fmac_f32_dpp %3, %7, %15 row_newbcast:%17" DPPM
;                      : "+v"(s[0]), "+v"(s[1]), "+v"(s[2]), "+v"(s[3])
;                      : "v"(a[0]), "v"(a[1]), "v"(a[2]), "v"(a[3]), "v"(S[K]), "v"(S[K + 1]), "v"(S[K + 2]), "v"(S[K + 3]), "v"(S[K + 4]), "v"(S[K + 5]), "v"(S[K + 6]), "v"(S[K + 7]), "n"(N0), "n"(N1));
;         if constexpr (K + 8 < 64) ScanK<K + 8>::dot(S, a, s);
;     }
;     static __device__ __forceinline__ void upd(float (&S)[64], const In2& in, float sa, float vv, float& y0, float& y1) {
;         float t0, t1, t2, t3;
;         asm volatile("v_mul_f32_dpp %0, %10, %27 row_newbcast:%28" DPPM "v_mul_f32_dpp %1, %11, %27 row_newbcast:%28" DPPM "v_mul_f32_dpp %2, %12, %27 row_newbcast:%28" DPPM "v_mul_f32_dpp %3, %13, %27 row_newbcast:%28" DPPM
;                      "v_fmac_f32_dpp %0, %14, %6 row_newbcast:%28" DPPM "v_fmac_f32_dpp %1, %15, %7 row_newbcast:%28" DPPM "v_fmac_f32_dpp %2, %16, %8 row_newbcast:%28" DPPM "v_fmac_f32_dpp %3, %17, %9 row_newbcast:%28" DPPM
	v_fmac_f32_dpp v196, v224, v40 row_newbcast:10 row_mask:0xf bank_mask:0xf
	v_fmac_f32_dpp v197, v225, v41 row_newbcast:10 row_mask:0xf bank_mask:0xf
	v_fmac_f32_dpp v198, v226, v42 row_newbcast:10 row_mask:0xf bank_mask:0xf
	v_fmac_f32_dpp v199, v227, v43 row_newbcast:10 row_mask:0xf bank_mask:0xf
	v_fmac_f32_dpp v196, v224, v44 row_newbcast:11 row_mask:0xf bank_mask:0xf
	v_fmac_f32_dpp v197, v225, v45 row_newbcast:11 row_mask:0xf bank_mask:0xf
	v_fmac_f32_dpp v198, v226, v46 row_newbcast:11 row_mask:0xf bank_mask:0xf
	v_fmac_f32_dpp v199, v227, v47 row_newbcast:11 row_mask:0xf bank_mask:0xf
	v_fmac_f32_dpp v196, v224, v48 row_newbcast:12 row_mask:0xf bank_mask:0xf
	v_fmac_f32_dpp v197, v225, v49 row_newbcast:12 row_mask:0xf bank_mask:0xf
	v_fmac_f32_dpp v198, v226, v50 row_newbcast:12 row_mask:0xf bank_mask:0xf
	v_fmac_f32_dpp v199, v227, v51 row_newbcast:12 row_mask:0xf bank_mask:0xf
	v_fmac_f32_dpp v196, v224, v52 row_newbcast:13 row_mask:0xf bank_mask:0xf
	v_fmac_f32_dpp v197, v225, v53 row_newbcast:13 row_mask:0xf bank_mask:0xf
	v_fmac_f32_dpp v198, v226, v54 row_newbcast:13 row_mask:0xf bank_mask:0xf
	v_fmac_f32_dpp v199, v227, v55 row_newbcast:13 row_mask:0xf bank_mask:0xf
	v_fmac_f32_dpp v196, v224, v56 row_newbcast:14 row_mask:0xf bank_mask:0xf
	v_fmac_f32_dpp v197, v225, v57 row_newbcast:14 row_mask:0xf bank_mask:0xf
	v_fmac_f32_dpp v198, v226, v58 row_newbcast:14 row_mask:0xf bank_mask:0xf
	v_fmac_f32_dpp v199, v227, v59 row_newbcast:14 row_mask:0xf bank_mask:0xf
	v_fmac_f32_dpp v196, v224, v60 row_newbcast:15 row_mask:0xf bank_mask:0xf
	v_fmac_f32_dpp v197, v225, v61 row_newbcast:15 row_mask:0xf bank_mask:0xf
	v_fmac_f32_dpp v198, v226, v62 row_newbcast:15 row_mask:0xf bank_mask:0xf
	v_fmac_f32_dpp v199, v227, v63 row_newbcast:15 row_mask:0xf bank_mask:0xf
	v_add_f32_e32 v196, v196, v197
	v_add_f32_e32 v198, v198, v199
	v_add_f32_e32 v196, v196, v198
	v_xor_b32_e32 v202, 0x80000000, v196
	s_waitcnt lgkmcnt(0)
	s_nop 1
	v_mfma_f32_4x4x1_16b_f32 v[0:3], v64, v202, v[0:3]
	v_mfma_f32_4x4x1_16b_f32 v[4:7], v65, v202, v[4:7]
	v_mfma_f32_4x4x1_16b_f32 v[8:11], v66, v202, v[8:11]
	v_mfma_f32_4x4x1_16b_f32 v[12:15], v67, v202, v[12:15]
	v_mfma_f32_4x4x1_16b_f32 v[16:19], v68, v202, v[16:19]
	v_mfma_f32_4x4x1_16b_f32 v[20:23], v69, v202, v[20:23]
	v_mfma_f32_4x4x1_16b_f32 v[24:27], v70, v202, v[24:27]
	v_mfma_f32_4x4x1_16b_f32 v[28:31], v71, v202, v[28:31]
	v_mfma_f32_4x4x1_16b_f32 v[32:35], v72, v202, v[32:35]
	v_mfma_f32_4x4x1_16b_f32 v[36:39], v73, v202, v[36:39]
	v_mfma_f32_4x4x1_16b_f32 v[40:43], v74, v202, v[40:43]
	v_mfma_f32_4x4x1_16b_f32 v[44:47], v75, v202, v[44:47]
	v_mfma_f32_4x4x1_16b_f32 v[48:51], v76, v202, v[48:51]
	v_mfma_f32_4x4x1_16b_f32 v[52:55], v77, v202, v[52:55]
	v_mfma_f32_4x4x1_16b_f32 v[56:59], v78, v202, v[56:59]
	v_mfma_f32_4x4x1_16b_f32 v[60:63], v79, v202, v[60:63]
	v_mfma_f32_4x4x1_16b_f32 v[0:3], v80, v203, v[0:3]
	v_mfma_f32_4x4x1_16b_f32 v[4:7], v81, v203, v[4:7]
	v_mfma_f32_4x4x1_16b_f32 v[8:11], v82, v203, v[8:11]
	v_mfma_f32_4x4x1_16b_f32 v[12:15], v83, v203, v[12:15]
	v_mfma_f32_4x4x1_16b_f32 v[16:19], v84, v203, v[16:19]
	v_mfma_f32_4x4x1_16b_f32 v[20:23], v85, v203, v[20:23]
	v_mfma_f32_4x4x1_16b_f32 v[24:27], v86, v203, v[24:27]
	v_mfma_f32_4x4x1_16b_f32 v[28:31], v87, v203, v[28:31]
	v_mfma_f32_4x4x1_16b_f32 v[32:35], v88, v203, v[32:35]
	v_mfma_f32_4x4x1_16b_f32 v[36:39], v89, v203, v[36:39]
	v_mfma_f32_4x4x1_16b_f32 v[40:43], v90, v203, v[40:43]
	v_mfma_f32_4x4x1_16b_f32 v[44:47], v91, v203, v[44:47]
	v_mfma_f32_4x4x1_16b_f32 v[48:51], v92, v203, v[48:51]
	v_mfma_f32_4x4x1_16b_f32 v[52:55], v93, v203, v[52:55]
	v_mfma_f32_4x4x1_16b_f32 v[56:59], v94, v203, v[56:59]
	v_mfma_f32_4x4x1_16b_f32 v[60:63], v95, v203, v[60:63]
	v_mul_f32_dpp v200, v228, v0 row_newbcast:0 row_mask:0xf bank_mask:0xf
	v_mul_f32_dpp v201, v229, v1 row_newbcast:0 row_mask:0xf bank_mask:0xf
	v_fmac_f32_dpp v200, v230, v2 row_newbcast:0 row_mask:0xf bank_mask:0xf
	v_fmac_f32_dpp v201, v231, v3 row_newbcast:0 row_mask:0xf bank_mask:0xf
	v_fmac_f32_dpp v200, v228, v4 row_newbcast:1 row_mask:0xf bank_mask:0xf
	v_fmac_f32_dpp v201, v229, v5 row_newbcast:1 row_mask:0xf bank_mask:0xf
	v_fmac_f32_dpp v200, v230, v6 row_newbcast:1 row_mask:0xf bank_mask:0xf
	v_fmac_f32_dpp v201, v231, v7 row_newbcast:1 row_mask:0xf bank_mask:0xf
	v_fmac_f32_dpp v200, v228, v8 row_newbcast:2 row_mask:0xf bank_mask:0xf
	v_fmac_f32_dpp v201, v229, v9 row_newbcast:2 row_mask:0xf bank_mask:0xf
	v_fmac_f32_dpp v200, v230, v10 row_newbcast:2 row_mask:0xf bank_mask:0xf
	v_fmac_f32_dpp v201, v231, v11 row_newbcast:2 row_mask:0xf bank_mask:0xf
	v_fmac_f32_dpp v200, v228, v12 row_newbcast:3 row_mask:0xf bank_mask:0xf
	v_fmac_f32_dpp v201, v229, v13 row_newbcast:3 row_mask:0xf bank_mask:0xf
	v_fmac_f32_dpp v200, v230, v14 row_newbcast:3 row_mask:0xf bank_mask:0xf
	v_fmac_f32_dpp v201, v231, v15 row_newbcast:3 row_mask:0xf bank_mask:0xf
	v_fmac_f32_dpp v200, v228, v16 row_newbcast:4 row_mask:0xf bank_mask:0xf
	v_fmac_f32_dpp v201, v229, v17 row_newbcast:4 row_mask:0xf bank_mask:0xf
	v_fmac_f32_dpp v200, v230, v18 row_newbcast:4 row_mask:0xf bank_mask:0xf
	v_fmac_f32_dpp v201, v231, v19 row_newbcast:4 row_mask:0xf bank_mask:0xf
	v_fmac_f32_dpp v200, v228, v20 row_newbcast:5 row_mask:0xf bank_mask:0xf
	v_fmac_f32_dpp v201, v229, v21 row_newbcast:5 row_mask:0xf bank_mask:0xf
	v_fmac_f32_dpp v200, v230, v22 row_newbcast:5 row_mask:0xf bank_mask:0xf
	v_fmac_f32_dpp v201, v231, v23 row_newbcast:5 row_mask:0xf bank_mask:0xf
	v_fmac_f32_dpp v200, v228, v24 row_newbcast:6 row_mask:0xf bank_mask:0xf
	v_fmac_f32_dpp v201, v229, v25 row_newbcast:6 row_mask:0xf bank_mask:0xf
; #define SB __builtin_amdgcn_sched_barrier(0)
; #define ST2(set, s) { DERIVE_BK(set); float sd[4]; ScanK<0>::dot(S, set.a, sd); float y0 = set.yo, y1 = 0.f; ScanK<0>::upd(S, set, -((sd[0] + sd[1]) + (sd[2] + sd[3])), __uint_as_float(set.v << 16), y0, y1); __builtin_amdgcn_raw_buffer_store_b32(__float_as_uint(y0 + y1), rY, lo4b, ob4 + (unsigned)((int)(s) * (int)stp * 4), 0); }
;     static __device__ __forceinline__ void upd(float (&S)[64], const In2& in, float sa, float vv, float& y0, float& y1) {
;         float t0, t1, t2, t3;
;         asm volatile("v_mul_f32_dpp %0, %10, %27 row_newbcast:%28" DPPM "v_mul_f32_dpp %1, %11, %27 row_newbcast:%28" DPPM "v_mul_f32_dpp %2, %12, %27 row_newbcast:%28" DPPM "v_mul_f32_dpp %3, %13, %27 row_newbcast:%28" DPPM
;                      "v_fmac_f32_dpp %0, %14, %6 row_newbcast:%28" DPPM "v_fmac_f32_dpp %1, %15, %7 row_newbcast:%28" DPPM "v_fmac_f32_dpp %2, %16, %8 row_newbcast:%28" DPPM "v_fmac_f32_dpp %3, %17, %9 row_newbcast:%28" DPPM
;                      "v_fmac_f32_dpp %0, %18, %26 row_newbcast:%28" DPPM "v_fmac_f32_dpp %1, %19, %26 row_newbcast:%28" DPPM "v_fmac_f32_dpp %2, %20, %26 row_newbcast:%28" DPPM "v_fmac_f32_dpp %3, %21, %26 row_newbcast:%28" DPPM
;                      "v_fmac_f32_dpp %4, %22, %0 row_newbcast:%28" DPPM "v_fmac_f32_dpp %5, %23, %1 row_newbcast:%28" DPPM "v_fmac_f32_dpp %4, %24, %2 row_newbcast:%28" DPPM "v_fmac_f32_dpp %5, %25, %3 row_newbcast:%28" DPPM
;                      : "=&v"(t0), "=&v"(t1), "=&v"(t2), "=&v"(t3), "+v"(y0), "+v"(y1)
;                      : "v"(S[K]), "v"(S[K + 1]), "v"(S[K + 2]), "v"(S[K + 3]), "v"(in.kd[0]), "v"(in.kd[1]), "v"(in.kd[2]), "v"(in.kd[3]), "v"(in.w[0]), "v"(in.w[1]), "v"(in.w[2]), "v"(in.w[3]),
;                        "v"(in.b[0]), "v"(in.b[1]), "v"(in.b[2]), "v"(in.b[3]), "v"(in.r[0]), "v"(in.r[1]), "v"(in.r[2]), "v"(in.r[3]), "v"(sa), "v"(vv), "n"(N0));
;         S[K] = t0; S[K + 1] = t1; S[K + 2] = t2; S[K + 3] = t3;
;         if constexpr (K + 4 < 64) ScanK<K + 4>::upd(S, in, sa, vv, y0, y1);
; __device__ __forceinline__ void scan_pass2(const Params& p, int d) {
;     ...
;         In2 i0, i1; LD2(i0, 0);
; #pragma unroll 1
;         for (int s = 0; s < LC; s += 2) { TOUCH2(i0); SB; LD2(i1, s + 1); SB; ST2(i0, s); TOUCH2(i1); SB; LD2(i0, s + 2); SB; ST2(i1, s + 1); }
	v_fmac_f32_dpp v200, v230, v26 row_newbcast:6 row_mask:0xf bank_mask:0xf
	v_fmac_f32_dpp v201, v231, v27 row_newbcast:6 row_mask:0xf bank_mask:0xf
	v_fmac_f32_dpp v200, v228, v28 row_newbcast:7 row_mask:0xf bank_mask:0xf
	v_fmac_f32_dpp v201, v229, v29 row_newbcast:7 row_mask:0xf bank_mask:0xf
	v_fmac_f32_dpp v200, v230, v30 row_newbcast:7 row_mask:0xf bank_mask:0xf
	v_fmac_f32_dpp v201, v231, v31 row_newbcast:7 row_mask:0xf bank_mask:0xf
	v_fmac_f32_dpp v200, v228, v32 row_newbcast:8 row_mask:0xf bank_mask:0xf
	v_fmac_f32_dpp v201, v229, v33 row_newbcast:8 row_mask:0xf bank_mask:0xf
	v_fmac_f32_dpp v200, v230, v34 row_newbcast:8 row_mask:0xf bank_mask:0xf
	v_fmac_f32_dpp v201, v231, v35 row_newbcast:8 row_mask:0xf bank_mask:0xf
	v_fmac_f32_dpp v200, v228, v36 row_newbcast:9 row_mask:0xf bank_mask:0xf
	v_fmac_f32_dpp v201, v229, v37 row_newbcast:9 row_mask:0xf bank_mask:0xf
	v_fmac_f32_dpp v200, v230, v38 row_newbcast:9 row_mask:0xf bank_mask:0xf
	v_fmac_f32_dpp v201, v231, v39 row_newbcast:9 row_mask:0xf bank_mask:0xf
	v_fmac_f32_dpp v200, v228, v40 row_newbcast:10 row_mask:0xf bank_mask:0xf
	v_fmac_f32_dpp v201, v229, v41 row_newbcast:10 row_mask:0xf bank_mask:0xf
	v_fmac_f32_dpp v200, v230, v42 row_newbcast:10 row_mask:0xf bank_mask:0xf
	v_fmac_f32_dpp v201, v231, v43 row_newbcast:10 row_mask:0xf bank_mask:0xf
	v_fmac_f32_dpp v200, v228, v44 row_newbcast:11 row_mask:0xf bank_mask:0xf
	v_fmac_f32_dpp v201, v229, v45 row_newbcast:11 row_mask:0xf bank_mask:0xf
	v_fmac_f32_dpp v200, v230, v46 row_newbcast:11 row_mask:0xf bank_mask:0xf
	v_fmac_f32_dpp v201, v231, v47 row_newbcast:11 row_mask:0xf bank_mask:0xf
	v_fmac_f32_dpp v200, v228, v48 row_newbcast:12 row_mask:0xf bank_mask:0xf
	v_fmac_f32_dpp v201, v229, v49 row_newbcast:12 row_mask:0xf bank_mask:0xf
	v_fmac_f32_dpp v200, v230, v50 row_newbcast:12 row_mask:0xf bank_mask:0xf
	v_fmac_f32_dpp v201, v231, v51 row_newbcast:12 row_mask:0xf bank_mask:0xf
	v_fmac_f32_dpp v200, v228, v52 row_newbcast:13 row_mask:0xf bank_mask:0xf
	v_fmac_f32_dpp v201, v229, v53 row_newbcast:13 row_mask:0xf bank_mask:0xf
	v_fmac_f32_dpp v200, v230, v54 row_newbcast:13 row_mask:0xf bank_mask:0xf
	v_fmac_f32_dpp v201, v231, v55 row_newbcast:13 row_mask:0xf bank_mask:0xf
	v_fmac_f32_dpp v200, v228, v56 row_newbcast:14 row_mask:0xf bank_mask:0xf
	v_fmac_f32_dpp v201, v229, v57 row_newbcast:14 row_mask:0xf bank_mask:0xf
	v_fmac_f32_dpp v200, v230, v58 row_newbcast:14 row_mask:0xf bank_mask:0xf
	v_fmac_f32_dpp v201, v231, v59 row_newbcast:14 row_mask:0xf bank_mask:0xf
	v_fmac_f32_dpp v200, v228, v60 row_newbcast:15 row_mask:0xf bank_mask:0xf
	v_fmac_f32_dpp v201, v229, v61 row_newbcast:15 row_mask:0xf bank_mask:0xf
	v_fmac_f32_dpp v200, v230, v62 row_newbcast:15 row_mask:0xf bank_mask:0xf
	v_fmac_f32_dpp v201, v231, v63 row_newbcast:15 row_mask:0xf bank_mask:0xf
	v_add_f32_e32 v200, v200, v201
	s_waitcnt vmcnt(12)
	buffer_store_dword v200, v207, s[68:71], s79 offen
	s_add_u32 s79, s79, 0x1000
	buffer_load_dwordx4 v[136:139], v204, s[64:67], s72 offen
	buffer_load_dwordx4 v[140:143], v204, s[64:67], s73 offen
	buffer_load_dwordx4 v[144:147], v204, s[64:67], s74 offen
	buffer_load_dwordx4 v[148:151], v204, s[64:67], s75 offen
	buffer_load_dwordx2 v[152:153], v205, s[64:67], s76 offen
	buffer_load_ushort v154, v206, s[64:67], s77 offen
	s_cmp_lt_u32 s80, 255
	s_cselect_b32 s81, 0x1000, 0
	s_cselect_b32 s82, 0x800, 0
	s_cselect_b32 s9, 1, 0
	s_add_u32 s80, s80, s9
	s_add_u32 s72, s72, s81
	s_add_u32 s73, s73, s81
	s_add_u32 s74, s74, s81
	s_add_u32 s75, s75, s81
	s_add_u32 s78, s78, s81
	s_add_u32 s76, s76, s82
	s_add_u32 s77, s77, s82
	v_pk_mul_f32 v[224:225], v[160:161], v[216:217]
	v_pk_mul_f32 v[226:227], v[162:163], v[218:219]
	v_pk_mul_f32 v[216:217], v[216:217], v[156:157]
	v_pk_mul_f32 v[218:219], v[218:219], v[158:159]
	v_pk_fma_f32 v[184:185], v[164:165], v[188:189], v[192:193]
	v_pk_fma_f32 v[186:187], v[166:167], v[190:191], v[194:195]
	v_pk_mul_f32 v[176:177], v[160:161], v[164:165]
	v_pk_mul_f32 v[178:179], v[162:163], v[166:167]
	v_rcp_f32_e32 v220, v216
	v_rcp_f32_e32 v221, v217
	v_rcp_f32_e32 v222, v218
	v_rcp_f32_e32 v223, v219
	v_lshlrev_b32_e32 v180, 16, v172
	v_and_b32_e32 v181, 0xffff0000, v172
	v_lshlrev_b32_e32 v182, 16, v173
	v_and_b32_e32 v183, 0xffff0000, v173
	v_pk_mul_f32 v[180:181], v[180:181], v[184:185]
	v_pk_mul_f32 v[182:183], v[182:183], v[186:187]
	v_pk_mul_f32 v[228:229], v[168:169], v[216:217]
	v_pk_mul_f32 v[230:231], v[170:171], v[218:219]
	v_pk_mul_f32 v[176:177], v[176:177], v[220:221]
	v_pk_mul_f32 v[178:179], v[178:179], v[222:223]
	v_pk_mul_f32 v[180:181], v[180:181], v[220:221]
	v_pk_mul_f32 v[182:183], v[182:183], v[222:223]
	v_lshlrev_b32_e32 v203, 16, v174
	ds_write_b128 v208, v[176:179]
	ds_write_b128 v208, v[180:183] offset:256
	ds_read2_b32 v[64:65], v209 offset0:0 offset1:4
	ds_read2_b32 v[66:67], v209 offset0:8 offset1:12
	ds_read2_b32 v[68:69], v209 offset0:16 offset1:20
	ds_read2_b32 v[70:71], v209 offset0:24 offset1:28
	ds_read2_b32 v[72:73], v209 offset0:32 offset1:36
	ds_read2_b32 v[74:75], v209 offset0:40 offset1:44
	ds_read2_b32 v[76:77], v209 offset0:48 offset1:52
	ds_read2_b32 v[78:79], v209 offset0:56 offset1:60
	ds_read2_b32 v[80:81], v209 offset0:64 offset1:68
	ds_read2_b32 v[82:83], v209 offset0:72 offset1:76
	ds_read2_b32 v[84:85], v209 offset0:80 offset1:84
	ds_read2_b32 v[86:87], v209 offset0:88 offset1:92
	ds_read2_b32 v[88:89], v209 offset0:96 offset1:100
	ds_read2_b32 v[90:91], v209 offset0:104 offset1:108
	ds_read2_b32 v[92:93], v209 offset0:112 offset1:116
	ds_read2_b32 v[94:95], v209 offset0:120 offset1:124
;     static __device__ __forceinline__ void dot(const float (&S)[64], const f32x4& a, float (&s)[4]) {
;         if constexpr (K == 0) {
;             asm volatile("v_mul_f32_dpp %0, %4, %8 row_newbcast:%16" DPPM "v_mul_f32_dpp %1, %5, %9 row_newbcast:%16" DPPM "v_mul_f32_dpp %2, %6, %10 row_newbcast:%16" DPPM "v_mul_f32_dpp %3, %7, %11 row_newbcast:%16" DPPM
;                          "v_fmac_f32_dpp %0, %4, %12 row_newbcast:%17" DPPM "v_fmac_f32_dpp %1, %5, %13 row_newbcast:%17" DPPM "v_fmac_f32_dpp %2, %6, %14 row_newbcast:%17" DPPM "v_fmac_f32_dpp %3, %7, %15 row_newbcast:%17" DPPM
;                          : "=&v"(s[0]), "=&v"(s[1]), "=&v"(s[2]), "=&v"(s[3])
;                          : "v"(a[0]), "v"(a[1]), "v"(a[2]), "v"(a[3]), "v"(S[K]), "v"(S[K + 1]), "v"(S[K + 2]), "v"(S[K + 3]), "v"(S[K + 4]), "v"(S[K + 5]), "v"(S[K + 6]), "v"(S[K + 7]), "n"(N0), "n"(N1));
;         } else
;         asm volatile("v_fmac_f32_dpp %0, %4, %8 row_newbcast:%16" DPPM "v_fmac_f32_dpp %1, %5, %9 row_newbcast:%16" DPPM "v_fmac_f32_dpp %2, %6, %10 row_newbcast:%16" DPPM "v_fmac_f32_dpp %3, %7, %11 row_newbcast:%16" DPPM
;                      "v_fmac_f32_dpp %0, %4, %12 row_newbcast:%17" DPPM "v_fmac_f32_dpp %1, %5, %13 row_newbcast:%17" DPPM "v_fmac_f32_dpp %2, %6, %14 row_newbcast:%17" DPPM "v_fmac_f32_dpp %3, %7, %15 row_newbcast:%17" DPPM
;                      : "+v"(s[0]), "+v"(s[1]), "+v"(s[2]), "+v"(s[3])
;                      : "v"(a[0]), "v"(a[1]), "v"(a[2]), "v"(a[3]), "v"(S[K]), "v"(S[K + 1]), "v"(S[K + 2]), "v"(S[K + 3]), "v"(S[K + 4]), "v"(S[K + 5]), "v"(S[K + 6]), "v"(S[K + 7]), "n"(N0), "n"(N1));
;         if constexpr (K + 8 < 64) ScanK<K + 8>::dot(S, a, s);
;     }
	v_mul_f32_dpp v196, v224, v0 row_newbcast:0 row_mask:0xf bank_mask:0xf
	v_mul_f32_dpp v197, v225, v1 row_newbcast:0 row_mask:0xf bank_mask:0xf
	v_mul_f32_dpp v198, v226, v2 row_newbcast:0 row_mask:0xf bank_mask:0xf
	v_mul_f32_dpp v199, v227, v3 row_newbcast:0 row_mask:0xf bank_mask:0xf
	v_fmac_f32_dpp v196, v224, v4 row_newbcast:1 row_mask:0xf bank_mask:0xf
	v_fmac_f32_dpp v197, v225, v5 row_newbcast:1 row_mask:0xf bank_mask:0xf
	v_fmac_f32_dpp v198, v226, v6 row_newbcast:1 row_mask:0xf bank_mask:0xf
	v_fmac_f32_dpp v199, v227, v7 row_newbcast:1 row_mask:0xf bank_mask:0xf
	v_fmac_f32_dpp v196, v224, v8 row_newbcast:2 row_mask:0xf bank_mask:0xf
	v_fmac_f32_dpp v197, v225, v9 row_newbcast:2 row_mask:0xf bank_mask:0xf
	v_fmac_f32_dpp v198, v226, v10 row_newbcast:2 row_mask:0xf bank_mask:0xf
	v_fmac_f32_dpp v199, v227, v11 row_newbcast:2 row_mask:0xf bank_mask:0xf
	v_fmac_f32_dpp v196, v224, v12 row_newbcast:3 row_mask:0xf bank_mask:0xf
	v_fmac_f32_dpp v197, v225, v13 row_newbcast:3 row_mask:0xf bank_mask:0xf
	v_fmac_f32_dpp v198, v226, v14 row_newbcast:3 row_mask:0xf bank_mask:0xf
	v_fmac_f32_dpp v199, v227, v15 row_newbcast:3 row_mask:0xf bank_mask:0xf
	v_fmac_f32_dpp v196, v224, v16 row_newbcast:4 row_mask:0xf bank_mask:0xf
	v_fmac_f32_dpp v197, v225, v17 row_newbcast:4 row_mask:0xf bank_mask:0xf
	v_fmac_f32_dpp v198, v226, v18 row_newbcast:4 row_mask:0xf bank_mask:0xf
	v_fmac_f32_dpp v199, v227, v19 row_newbcast:4 row_mask:0xf bank_mask:0xf
	v_fmac_f32_dpp v196, v224, v20 row_newbcast:5 row_mask:0xf bank_mask:0xf
	v_fmac_f32_dpp v197, v225, v21 row_newbcast:5 row_mask:0xf bank_mask:0xf
	v_fmac_f32_dpp v198, v226, v22 row_newbcast:5 row_mask:0xf bank_mask:0xf
	v_fmac_f32_dpp v199, v227, v23 row_newbcast:5 row_mask:0xf bank_mask:0xf
	v_fmac_f32_dpp v196, v224, v24 row_newbcast:6 row_mask:0xf bank_mask:0xf
	v_fmac_f32_dpp v197, v225, v25 row_newbcast:6 row_mask:0xf bank_mask:0xf
	v_fmac_f32_dpp v198, v226, v26 row_newbcast:6 row_mask:0xf bank_mask:0xf
	v_fmac_f32_dpp v199, v227, v27 row_newbcast:6 row_mask:0xf bank_mask:0xf
	v_fmac_f32_dpp v196, v224, v28 row_newbcast:7 row_mask:0xf bank_mask:0xf
	v_fmac_f32_dpp v197, v225, v29 row_newbcast:7 row_mask:0xf bank_mask:0xf
	v_fmac_f32_dpp v198, v226, v30 row_newbcast:7 row_mask:0xf bank_mask:0xf
	v_fmac_f32_dpp v199, v227, v31 row_newbcast:7 row_mask:0xf bank_mask:0xf
	v_fmac_f32_dpp v196, v224, v32 row_newbcast:8 row_mask:0xf bank_mask:0xf
	v_fmac_f32_dpp v197, v225, v33 row_newbcast:8 row_mask:0xf bank_mask:0xf
	v_fmac_f32_dpp v198, v226, v34 row_newbcast:8 row_mask:0xf bank_mask:0xf
	v_fmac_f32_dpp v199, v227, v35 row_newbcast:8 row_mask:0xf bank_mask:0xf
	v_fmac_f32_dpp v196, v224, v36 row_newbcast:9 row_mask:0xf bank_mask:0xf
	v_fmac_f32_dpp v197, v225, v37 row_newbcast:9 row_mask:0xf bank_mask:0xf
	v_fmac_f32_dpp v198, v226, v38 row_newbcast:9 row_mask:0xf bank_mask:0xf
	v_fmac_f32_dpp v199, v227, v39 row_newbcast:9 row_mask:0xf bank_mask:0xf
	v_fmac_f32_dpp v196, v224, v40 row_newbcast:10 row_mask:0xf bank_mask:0xf
	v_fmac_f32_dpp v197, v225, v41 row_newbcast:10 row_mask:0xf bank_mask:0xf
	v_fmac_f32_dpp v198, v226, v42 row_newbcast:10 row_mask:0xf bank_mask:0xf
	v_fmac_f32_dpp v199, v227, v43 row_newbcast:10 row_mask:0xf bank_mask:0xf
	v_fmac_f32_dpp v196, v224, v44 row_newbcast:11 row_mask:0xf bank_mask:0xf
	v_fmac_f32_dpp v197, v225, v45 row_newbcast:11 row_mask:0xf bank_mask:0xf
	v_fmac_f32_dpp v198, v226, v46 row_newbcast:11 row_mask:0xf bank_mask:0xf
	v_fmac_f32_dpp v199, v227, v47 row_newbcast:11 row_mask:0xf bank_mask:0xf
	v_fmac_f32_dpp v196, v224, v48 row_newbcast:12 row_mask:0xf bank_mask:0xf
	v_fmac_f32_dpp v197, v225, v49 row_newbcast:12 row_mask:0xf bank_mask:0xf
	v_fmac_f32_dpp v198, v226, v50 row_newbcast:12 row_mask:0xf bank_mask:0xf
	v_fmac_f32_dpp v199, v227, v51 row_newbcast:12 row_mask:0xf bank_mask:0xf
	v_fmac_f32_dpp v196, v224, v52 row_newbcast:13 row_mask:0xf bank_mask:0xf
	v_fmac_f32_dpp v197, v225, v53 row_newbcast:13 row_mask:0xf bank_mask:0xf
	v_fmac_f32_dpp v198, v226, v54 row_newbcast:13 row_mask:0xf bank_mask:0xf
	v_fmac_f32_dpp v199, v227, v55 row_newbcast:13 row_mask:0xf bank_mask:0xf
	v_fmac_f32_dpp v196, v224, v56 row_newbcast:14 row_mask:0xf bank_mask:0xf
	v_fmac_f32_dpp v197, v225, v57 row_newbcast:14 row_mask:0xf bank_mask:0xf
	v_fmac_f32_dpp v198, v226, v58 row_newbcast:14 row_mask:0xf bank_mask:0xf
	v_fmac_f32_dpp v199, v227, v59 row_newbcast:14 row_mask:0xf bank_mask:0xf
	v_fmac_f32_dpp v196, v224, v60 row_newbcast:15 row_mask:0xf bank_mask:0xf
	v_fmac_f32_dpp v197, v225, v61 row_newbcast:15 row_mask:0xf bank_mask:0xf
	v_fmac_f32_dpp v198, v226, v62 row_newbcast:15 row_mask:0xf bank_mask:0xf
	v_fmac_f32_dpp v199, v227, v63 row_newbcast:15 row_mask:0xf bank_mask:0xf
	v_add_f32_e32 v196, v196, v197
	v_add_f32_e32 v198, v198, v199
	v_add_f32_e32 v196, v196, v198
	v_xor_b32_e32 v202, 0x80000000, v196
	s_waitcnt lgkmcnt(0)
; #define SB __builtin_amdgcn_sched_barrier(0)
; #define ST2(set, s) { DERIVE_BK(set); float sd[4]; ScanK<0>::dot(S, set.a, sd); float y0 = set.yo, y1 = 0.f; ScanK<0>::upd(S, set, -((sd[0] + sd[1]) + (sd[2] + sd[3])), __uint_as_float(set.v << 16), y0, y1); __builtin_amdgcn_raw_buffer_store_b32(__float_as_uint(y0 + y1), rY, lo4b, ob4 + (unsigned)((int)(s) * (int)stp * 4), 0); }
;     static __device__ __forceinline__ void upd(float (&S)[64], const In2& in, float sa, float vv, float& y0, float& y1) {
;         float t0, t1, t2, t3;
;         asm volatile("v_mul_f32_dpp %0, %10, %27 row_newbcast:%28" DPPM "v_mul_f32_dpp %1, %11, %27 row_newbcast:%28" DPPM "v_mul_f32_dpp %2, %12, %27 row_newbcast:%28" DPPM "v_mul_f32_dpp %3, %13, %27 row_newbcast:%28" DPPM
;                      "v_fmac_f32_dpp %0, %14, %6 row_newbcast:%28" DPPM "v_fmac_f32_dpp %1, %15, %7 row_newbcast:%28" DPPM "v_fmac_f32_dpp %2, %16, %8 row_newbcast:%28" DPPM "v_fmac_f32_dpp %3, %17, %9 row_newbcast:%28" DPPM
;                      "v_fmac_f32_dpp %0, %18, %26 row_newbcast:%28" DPPM "v_fmac_f32_dpp %1, %19, %26 row_newbcast:%28" DPPM "v_fmac_f32_dpp %2, %20, %26 row_newbcast:%28" DPPM "v_fmac_f32_dpp %3, %21, %26 row_newbcast:%28" DPPM
;                      "v_fmac_f32_dpp %4, %22, %0 row_newbcast:%28" DPPM "v_fmac_f32_dpp %5, %23, %1 row_newbcast:%28" DPPM "v_fmac_f32_dpp %4, %24, %2 row_newbcast:%28" DPPM "v_fmac_f32_dpp %5, %25, %3 row_newbcast:%28" DPPM
;                      : "=&v"(t0), "=&v"(t1), "=&v"(t2), "=&v"(t3), "+v"(y0), "+v"(y1)
;                      : "v"(S[K]), "v"(S[K + 1]), "v"(S[K + 2]), "v"(S[K + 3]), "v"(in.kd[0]), "v"(in.kd[1]), "v"(in.kd[2]), "v"(in.kd[3]), "v"(in.w[0]), "v"(in.w[1]), "v"(in.w[2]), "v"(in.w[3]),
;                        "v"(in.b[0]), "v"(in.b[1]), "v"(in.b[2]), "v"(in.b[3]), "v"(in.r[0]), "v"(in.r[1]), "v"(in.r[2]), "v"(in.r[3]), "v"(sa), "v"(vv), "n"(N0));
;         S[K] = t0; S[K + 1] = t1; S[K + 2] = t2; S[K + 3] = t3;
;         if constexpr (K + 4 < 64) ScanK<K + 4>::upd(S, in, sa, vv, y0, y1);
; __device__ __forceinline__ void scan_pass2(const Params& p, int d) {
;     ...
;         In2 i0, i1; LD2(i0, 0);
; #pragma unroll 1
;         for (int s = 0; s < LC; s += 2) { TOUCH2(i0); SB; LD2(i1, s + 1); SB; ST2(i0, s); TOUCH2(i1); SB; LD2(i0, s + 2); SB; ST2(i1, s + 1); }
	s_nop 1
	v_mfma_f32_4x4x1_16b_f32 v[0:3], v64, v202, v[0:3]
	v_mfma_f32_4x4x1_16b_f32 v[4:7], v65, v202, v[4:7]
	v_mfma_f32_4x4x1_16b_f32 v[8:11], v66, v202, v[8:11]
	v_mfma_f32_4x4x1_16b_f32 v[12:15], v67, v202, v[12:15]
	v_mfma_f32_4x4x1_16b_f32 v[16:19], v68, v202, v[16:19]
	v_mfma_f32_4x4x1_16b_f32 v[20:23], v69, v202, v[20:23]
	v_mfma_f32_4x4x1_16b_f32 v[24:27], v70, v202, v[24:27]
	v_mfma_f32_4x4x1_16b_f32 v[28:31], v71, v202, v[28:31]
	v_mfma_f32_4x4x1_16b_f32 v[32:35], v72, v202, v[32:35]
	v_mfma_f32_4x4x1_16b_f32 v[36:39], v73, v202, v[36:39]
	v_mfma_f32_4x4x1_16b_f32 v[40:43], v74, v202, v[40:43]
	v_mfma_f32_4x4x1_16b_f32 v[44:47], v75, v202, v[44:47]
	v_mfma_f32_4x4x1_16b_f32 v[48:51], v76, v202, v[48:51]
	v_mfma_f32_4x4x1_16b_f32 v[52:55], v77, v202, v[52:55]
	v_mfma_f32_4x4x1_16b_f32 v[56:59], v78, v202, v[56:59]
	v_mfma_f32_4x4x1_16b_f32 v[60:63], v79, v202, v[60:63]
	v_mfma_f32_4x4x1_16b_f32 v[0:3], v80, v203, v[0:3]
	v_mfma_f32_4x4x1_16b_f32 v[4:7], v81, v203, v[4:7]
	v_mfma_f32_4x4x1_16b_f32 v[8:11], v82, v203, v[8:11]
	v_mfma_f32_4x4x1_16b_f32 v[12:15], v83, v203, v[12:15]
	v_mfma_f32_4x4x1_16b_f32 v[16:19], v84, v203, v[16:19]
	v_mfma_f32_4x4x1_16b_f32 v[20:23], v85, v203, v[20:23]
	v_mfma_f32_4x4x1_16b_f32 v[24:27], v86, v203, v[24:27]
	v_mfma_f32_4x4x1_16b_f32 v[28:31], v87, v203, v[28:31]
	v_mfma_f32_4x4x1_16b_f32 v[32:35], v88, v203, v[32:35]
	v_mfma_f32_4x4x1_16b_f32 v[36:39], v89, v203, v[36:39]
	v_mfma_f32_4x4x1_16b_f32 v[40:43], v90, v203, v[40:43]
	v_mfma_f32_4x4x1_16b_f32 v[44:47], v91, v203, v[44:47]
	v_mfma_f32_4x4x1_16b_f32 v[48:51], v92, v203, v[48:51]
	v_mfma_f32_4x4x1_16b_f32 v[52:55], v93, v203, v[52:55]
	v_mfma_f32_4x4x1_16b_f32 v[56:59], v94, v203, v[56:59]
	v_mfma_f32_4x4x1_16b_f32 v[60:63], v95, v203, v[60:63]
	v_mul_f32_dpp v200, v228, v0 row_newbcast:0 row_mask:0xf bank_mask:0xf
	v_mul_f32_dpp v201, v229, v1 row_newbcast:0 row_mask:0xf bank_mask:0xf
	v_fmac_f32_dpp v200, v230, v2 row_newbcast:0 row_mask:0xf bank_mask:0xf
	v_fmac_f32_dpp v201, v231, v3 row_newbcast:0 row_mask:0xf bank_mask:0xf
	v_fmac_f32_dpp v200, v228, v4 row_newbcast:1 row_mask:0xf bank_mask:0xf
	v_fmac_f32_dpp v201, v229, v5 row_newbcast:1 row_mask:0xf bank_mask:0xf
	v_fmac_f32_dpp v200, v230, v6 row_newbcast:1 row_mask:0xf bank_mask:0xf
	v_fmac_f32_dpp v201, v231, v7 row_newbcast:1 row_mask:0xf bank_mask:0xf
	v_fmac_f32_dpp v200, v228, v8 row_newbcast:2 row_mask:0xf bank_mask:0xf
	v_fmac_f32_dpp v201, v229, v9 row_newbcast:2 row_mask:0xf bank_mask:0xf
	v_fmac_f32_dpp v200, v230, v10 row_newbcast:2 row_mask:0xf bank_mask:0xf
	v_fmac_f32_dpp v201, v231, v11 row_newbcast:2 row_mask:0xf bank_mask:0xf
	v_fmac_f32_dpp v200, v228, v12 row_newbcast:3 row_mask:0xf bank_mask:0xf
	v_fmac_f32_dpp v201, v229, v13 row_newbcast:3 row_mask:0xf bank_mask:0xf
	v_fmac_f32_dpp v200, v230, v14 row_newbcast:3 row_mask:0xf bank_mask:0xf
	v_fmac_f32_dpp v201, v231, v15 row_newbcast:3 row_mask:0xf bank_mask:0xf
	v_fmac_f32_dpp v200, v228, v16 row_newbcast:4 row_mask:0xf bank_mask:0xf
	v_fmac_f32_dpp v201, v229, v17 row_newbcast:4 row_mask:0xf bank_mask:0xf
	v_fmac_f32_dpp v200, v230, v18 row_newbcast:4 row_mask:0xf bank_mask:0xf
	v_fmac_f32_dpp v201, v231, v19 row_newbcast:4 row_mask:0xf bank_mask:0xf
	v_fmac_f32_dpp v200, v228, v20 row_newbcast:5 row_mask:0xf bank_mask:0xf
	v_fmac_f32_dpp v201, v229, v21 row_newbcast:5 row_mask:0xf bank_mask:0xf
	v_fmac_f32_dpp v200, v230, v22 row_newbcast:5 row_mask:0xf bank_mask:0xf
	v_fmac_f32_dpp v201, v231, v23 row_newbcast:5 row_mask:0xf bank_mask:0xf
	v_fmac_f32_dpp v200, v228, v24 row_newbcast:6 row_mask:0xf bank_mask:0xf
	v_fmac_f32_dpp v201, v229, v25 row_newbcast:6 row_mask:0xf bank_mask:0xf
	v_fmac_f32_dpp v200, v230, v26 row_newbcast:6 row_mask:0xf bank_mask:0xf
	v_fmac_f32_dpp v201, v231, v27 row_newbcast:6 row_mask:0xf bank_mask:0xf
	v_fmac_f32_dpp v200, v228, v28 row_newbcast:7 row_mask:0xf bank_mask:0xf
	v_fmac_f32_dpp v201, v229, v29 row_newbcast:7 row_mask:0xf bank_mask:0xf
	v_fmac_f32_dpp v200, v230, v30 row_newbcast:7 row_mask:0xf bank_mask:0xf
	v_fmac_f32_dpp v201, v231, v31 row_newbcast:7 row_mask:0xf bank_mask:0xf
	v_fmac_f32_dpp v200, v228, v32 row_newbcast:8 row_mask:0xf bank_mask:0xf
	v_fmac_f32_dpp v201, v229, v33 row_newbcast:8 row_mask:0xf bank_mask:0xf
	v_fmac_f32_dpp v200, v230, v34 row_newbcast:8 row_mask:0xf bank_mask:0xf
	v_fmac_f32_dpp v201, v231, v35 row_newbcast:8 row_mask:0xf bank_mask:0xf
	v_fmac_f32_dpp v200, v228, v36 row_newbcast:9 row_mask:0xf bank_mask:0xf
	v_fmac_f32_dpp v201, v229, v37 row_newbcast:9 row_mask:0xf bank_mask:0xf
	v_fmac_f32_dpp v200, v230, v38 row_newbcast:9 row_mask:0xf bank_mask:0xf
	v_fmac_f32_dpp v201, v231, v39 row_newbcast:9 row_mask:0xf bank_mask:0xf
	v_fmac_f32_dpp v200, v228, v40 row_newbcast:10 row_mask:0xf bank_mask:0xf
	v_fmac_f32_dpp v201, v229, v41 row_newbcast:10 row_mask:0xf bank_mask:0xf
	v_fmac_f32_dpp v200, v230, v42 row_newbcast:10 row_mask:0xf bank_mask:0xf
	v_fmac_f32_dpp v201, v231, v43 row_newbcast:10 row_mask:0xf bank_mask:0xf
	v_fmac_f32_dpp v200, v228, v44 row_newbcast:11 row_mask:0xf bank_mask:0xf
	v_fmac_f32_dpp v201, v229, v45 row_newbcast:11 row_mask:0xf bank_mask:0xf
	v_fmac_f32_dpp v200, v230, v46 row_newbcast:11 row_mask:0xf bank_mask:0xf
	v_fmac_f32_dpp v201, v231, v47 row_newbcast:11 row_mask:0xf bank_mask:0xf
	v_fmac_f32_dpp v200, v228, v48 row_newbcast:12 row_mask:0xf bank_mask:0xf
	v_fmac_f32_dpp v201, v229, v49 row_newbcast:12 row_mask:0xf bank_mask:0xf
	v_fmac_f32_dpp v200, v230, v50 row_newbcast:12 row_mask:0xf bank_mask:0xf
	v_fmac_f32_dpp v201, v231, v51 row_newbcast:12 row_mask:0xf bank_mask:0xf
	v_fmac_f32_dpp v200, v228, v52 row_newbcast:13 row_mask:0xf bank_mask:0xf
	v_fmac_f32_dpp v201, v229, v53 row_newbcast:13 row_mask:0xf bank_mask:0xf
	v_fmac_f32_dpp v200, v230, v54 row_newbcast:13 row_mask:0xf bank_mask:0xf
	v_fmac_f32_dpp v201, v231, v55 row_newbcast:13 row_mask:0xf bank_mask:0xf
	v_fmac_f32_dpp v200, v228, v56 row_newbcast:14 row_mask:0xf bank_mask:0xf
	v_fmac_f32_dpp v201, v229, v57 row_newbcast:14 row_mask:0xf bank_mask:0xf
	v_fmac_f32_dpp v200, v230, v58 row_newbcast:14 row_mask:0xf bank_mask:0xf
	v_fmac_f32_dpp v201, v231, v59 row_newbcast:14 row_mask:0xf bank_mask:0xf
	v_fmac_f32_dpp v200, v228, v60 row_newbcast:15 row_mask:0xf bank_mask:0xf
	v_fmac_f32_dpp v201, v229, v61 row_newbcast:15 row_mask:0xf bank_mask:0xf
	v_fmac_f32_dpp v200, v230, v62 row_newbcast:15 row_mask:0xf bank_mask:0xf
	v_fmac_f32_dpp v201, v231, v63 row_newbcast:15 row_mask:0xf bank_mask:0xf
	v_add_f32_e32 v200, v200, v201
	s_sub_u32 s83, s83, 1
	s_cmp_eq_u32 s83, 0
	s_cbranch_scc1 .Lmy_p2d0_ldone
	s_and_b32 s9, s83, 7
	s_cmp_eq_u32 s9, 0
	s_cbranch_scc1 .Lmy_p2d0_renorm
	s_branch .Lmy_p2d0_loop
.Lmy_p2d0_ldone:
	buffer_store_dword v200, v207, s[68:71], s79 offen
	s_add_u32 s79, s79, 0x1000
	s_lshl_b32 s6, s96, 3
	s_add_i32 s0, s0, s6
	s_branch .Lmy_p2d0_item

; #define MKR(ptr) __builtin_amdgcn_make_buffer_rsrc((void*)(ptr), 0, 0x7fffffff, 0x00027000)
; __device__ __forceinline__ void scan_pass2(const Params& p, int d) {
;     const int lane = threadIdx.x & 63, wid = __builtin_amdgcn_readfirstlane(threadIdx.x >> 6); const unsigned lo16 = (lane & 15) * 16, lo2 = lane * 2, lo4b = lane * 4;
;     const float* Wd = (const float*)(p.ws + O_KD); const float* Bd = (const float*)(p.ws + O_Y); const u16* KB = (const u16*)(p.ws + O_K); const float* A = (const float*)(p.ws + O_A); const float* R = (const float*)(p.ws + O_R); const unsigned lo8 = (lane & 15) * 8;
;     const u16* V = (const u16*)(p.ws + O_V); const float* SIT = (const float*)(p.ws + O_SIT); float* Y = p.out;
;     for (int item = blockIdx.x * 8 + wid; item < 32 * NC; item += gridDim.x * 8) {
;         const int bh = item / NC, c = item - bh * NC, b = bh >> 4, h = bh & 15;
;         const int t0 = d ? (SEQ - 1 - c * LC) : c * LC;
;         const size_t off0 = ((size_t)(b * SEQ + t0)) * RW + h * 64; const long stp = d ? -(long)RW : (long)RW;
;         const unsigned ob4 = (unsigned)(off0 * 4), ob2 = (unsigned)(off0 * 2);
;         const __amdgpu_buffer_rsrc_t rW = MKR(Wd), rA = MKR(A), rB = MKR(Bd), rK = MKR(KB), rV = MKR(V), rR = MKR(R), rY = MKR(Y);
;         const f32x4 ka4 = *(const f32x4*)(p.k_a + h * 64 + (lane & 15) * 4), c04 = 1.0f - ka4;
;         float S[64];
;         if (c == 0) {
; #pragma unroll
;             for (int i = 0; i < 64; ++i) S[i] = 0.f;
;         } else { const float* si = SIT + ((size_t)(bh * NC + c)) * 4096 + lane * 64;
; #pragma unroll
;             for (int i = 0; i < 16; ++i) { const f32x4 q = *(const f32x4*)(si + 4 * i); S[4 * i] = q[0]; S[4 * i + 1] = q[1]; S[4 * i + 2] = q[2]; S[4 * i + 3] = q[3]; } }
;     ...
;         In2 i0, i1; LD2(i0, 0);
.LBB0_953:
	s_cmp_lt_i32 s58, 11
	s_cselect_b64 s[0:1], -1, 0
	s_cmp_gt_i32 s59, 10
	s_cselect_b64 s[4:5], -1, 0
	s_and_b64 s[0:1], s[0:1], s[4:5]
	s_andn2_b64 vcc, exec, s[0:1]
	s_cbranch_vccnz .LBB0_1015
	v_readfirstlane_b32 s0, v254
	s_nop 3
	s_lshr_b32 s1, s0, 6
	s_lshl_b32 s0, s2, 3
	s_add_i32 s0, s1, s0
	s_mov_b32 s64, s56
	s_and_b32 s65, s57, 0xffff
	s_brev_b32 s66, -2
	s_mov_b32 s67, 0x27000
	s_mov_b32 s68, s54
	s_and_b32 s69, s55, 0xffff
	s_mov_b32 s70, s66
	s_mov_b32 s71, s67
	v_and_b32_e32 v212, 63, v254
	v_and_b32_e32 v213, 15, v254
	v_lshlrev_b32_e32 v204, 4, v213
	v_lshlrev_b32_e32 v205, 3, v213
	v_lshlrev_b32_e32 v206, 1, v212
	v_lshlrev_b32_e32 v207, 2, v212
	v_lshlrev_b32_e32 v210, 8, v212
	s_lshl_b32 s3, s1, 10
	s_add_u32 s3, s3, 0x10000
	v_add_u32_e32 v208, s3, v204
	v_and_b32_e32 v209, 3, v254
	v_lshlrev_b32_e32 v209, 2, v209
	v_add_u32_e32 v209, s3, v209
.Lmy_p2d1_item:
	s_cmpk_gt_i32 s0, 0x7ff
	s_cbranch_scc1 .Lmy_p2d1_end
	s_lshr_b32 s86, s0, 6
	s_and_b32 s85, s0, 63
	s_and_b32 s87, s86, 15
	s_lshr_b32 s6, s86, 4
	s_lshl_b32 s6, s6, 14
	s_lshl_b32 s7, s85, 8
	s_sub_u32 s7, 0x3fff, s7
	s_add_u32 s6, s6, s7
	s_lshl_b32 s6, s6, 10
	s_lshl_b32 s7, s87, 6
	s_add_u32 s84, s6, s7
	s_lshl_b32 s6, s84, 2
	s_lshl_b32 s7, s84, 1
	s_add_u32 s72, s6, 0xb800000
	s_add_u32 s73, s6, 0x24800000
	s_add_u32 s74, s6, 0x35a00000
	s_add_u32 s75, s6, 0x1c800000
	s_add_u32 s76, s7, 0x30800000
	s_add_u32 s77, s7, 0x2c800000
	s_mov_b32 s78, s6
	s_mov_b32 s79, s6
	s_mov_b32 s80, 0
	s_lshl_b32 s8, s87, 8
	s_add_u32 s4, s42, s8
	s_addc_u32 s5, s43, 0
	global_load_dwordx4 v[188:191], v204, s[4:5]
	buffer_load_dwordx4 v[96:99], v204, s[64:67], s72 offen
	buffer_load_dwordx4 v[100:103], v204, s[64:67], s73 offen
	buffer_load_dwordx4 v[104:107], v204, s[64:67], s74 offen
	buffer_load_dwordx4 v[108:111], v204, s[64:67], s75 offen
	buffer_load_dwordx2 v[112:113], v205, s[64:67], s76 offen
	buffer_load_ushort v114, v206, s[64:67], s77 offen
	buffer_load_dword v115, v207, s[68:71], s78 offen
	s_add_u32 s72, s72, 0xfffff000
	s_add_u32 s73, s73, 0xfffff000
	s_add_u32 s74, s74, 0xfffff000
	s_add_u32 s75, s75, 0xfffff000
	s_add_u32 s78, s78, 0xfffff000
	s_add_u32 s76, s76, 0xfffff800
	s_add_u32 s77, s77, 0xfffff800
	buffer_load_dwordx4 v[116:119], v204, s[64:67], s72 offen
	buffer_load_dwordx4 v[120:123], v204, s[64:67], s73 offen
	buffer_load_dwordx4 v[124:127], v204, s[64:67], s74 offen
	buffer_load_dwordx4 v[128:131], v204, s[64:67], s75 offen
	buffer_load_dwordx2 v[132:133], v205, s[64:67], s76 offen
	buffer_load_ushort v134, v206, s[64:67], s77 offen
	buffer_load_dword v135, v207, s[68:71], s78 offen
	s_add_u32 s72, s72, 0xfffff000
	s_add_u32 s73, s73, 0xfffff000
	s_add_u32 s74, s74, 0xfffff000
	s_add_u32 s75, s75, 0xfffff000
	s_add_u32 s78, s78, 0xfffff000
	s_add_u32 s76, s76, 0xfffff800
	s_add_u32 s77, s77, 0xfffff800
	buffer_load_dwordx4 v[136:139], v204, s[64:67], s72 offen
	buffer_load_dwordx4 v[140:143], v204, s[64:67], s73 offen
	buffer_load_dwordx4 v[144:147], v204, s[64:67], s74 offen
	buffer_load_dwordx4 v[148:151], v204, s[64:67], s75 offen
	buffer_load_dwordx2 v[152:153], v205, s[64:67], s76 offen
	buffer_load_ushort v154, v206, s[64:67], s77 offen
	buffer_load_dword v155, v207, s[68:71], s78 offen
	s_add_u32 s72, s72, 0xfffff000
	s_add_u32 s73, s73, 0xfffff000
	s_add_u32 s74, s74, 0xfffff000
	s_add_u32 s75, s75, 0xfffff000
	s_add_u32 s78, s78, 0xfffff000
	s_add_u32 s76, s76, 0xfffff800
	s_add_u32 s77, s77, 0xfffff800
	s_mov_b32 s80, 3
	s_cmp_eq_u32 s85, 0
	s_cbranch_scc1 .Lmy_p2d1_zero
	s_lshl_b32 s8, s0, 14
	s_add_u32 s8, s8, 0x3da00000
	s_add_u32 s4, s56, s8
	s_addc_u32 s5, s57, 0
	global_load_dwordx4 v[0:3], v210, s[4:5] offset:0
	global_load_dwordx4 v[4:7], v210, s[4:5] offset:16
	global_load_dwordx4 v[8:11], v210, s[4:5] offset:32
	global_load_dwordx4 v[12:15], v210, s[4:5] offset:48
	global_load_dwordx4 v[16:19], v210, s[4:5] offset:64
	global_load_dwordx4 v[20:23], v210, s[4:5] offset:80
	global_load_dwordx4 v[24:27], v210, s[4:5] offset:96
	global_load_dwordx4 v[28:31], v210, s[4:5] offset:112
	global_load_dwordx4 v[32:35], v210, s[4:5] offset:128
	global_load_dwordx4 v[36:39], v210, s[4:5] offset:144
	global_load_dwordx4 v[40:43], v210, s[4:5] offset:160
	global_load_dwordx4 v[44:47], v210, s[4:5] offset:176
	global_load_dwordx4 v[48:51], v210, s[4:5] offset:192
	global_load_dwordx4 v[52:55], v210, s[4:5] offset:208
	global_load_dwordx4 v[56:59], v210, s[4:5] offset:224
	global_load_dwordx4 v[60:63], v210, s[4:5] offset:240
	s_branch .Lmy_p2d1_init_done

; #define SB __builtin_amdgcn_sched_barrier(0)
; #define ST2(set, s) { DERIVE_BK(set); float sd[4]; ScanK<0>::dot(S, set.a, sd); float y0 = set.yo, y1 = 0.f; ScanK<0>::upd(S, set, -((sd[0] + sd[1]) + (sd[2] + sd[3])), __uint_as_float(set.v << 16), y0, y1); __builtin_amdgcn_raw_buffer_store_b32(__float_as_uint(y0 + y1), rY, lo4b, ob4 + (unsigned)((int)(s) * (int)stp * 4), 0); }
;     static __device__ __forceinline__ void dot(const float (&S)[64], const f32x4& a, float (&s)[4]) {
;         if constexpr (K == 0) {
;             asm volatile("v_mul_f32_dpp %0, %4, %8 row_newbcast:%16" DPPM "v_mul_f32_dpp %1, %5, %9 row_newbcast:%16" DPPM "v_mul_f32_dpp %2, %6, %10 row_newbcast:%16" DPPM "v_mul_f32_dpp %3, %7, %11 row_newbcast:%16" DPPM
;                          "v_fmac_f32_dpp %0, %4, %12 row_newbcast:%17" DPPM "v_fmac_f32_dpp %1, %5, %13 row_newbcast:%17" DPPM "v_fmac_f32_dpp %2, %6, %14 row_newbcast:%17" DPPM "v_fmac_f32_dpp %3, %7, %15 row_newbcast:%17" DPPM
;                          : "=&v"(s[0]), "=&v"(s[1]), "=&v"(s[2]), "=&v"(s[3])
;                          : "v"(a[0]), "v"(a[1]), "v"(a[2]), "v"(a[3]), "v"(S[K]), "v"(S[K + 1]), "v"(S[K + 2]), "v"(S[K + 3]), "v"(S[K + 4]), "v"(S[K + 5]), "v"(S[K + 6]), "v"(S[K + 7]), "n"(N0), "n"(N1));
;         } else
;         asm volatile("v_fmac_f32_dpp %0, %4, %8 row_newbcast:%16" DPPM "v_fmac_f32_dpp %1, %5, %9 row_newbcast:%16" DPPM "v_fmac_f32_dpp %2, %6, %10 row_newbcast:%16" DPPM "v_fmac_f32_dpp %3, %7, %11 row_newbcast:%16" DPPM
;                      "v_fmac_f32_dpp %0, %4, %12 row_newbcast:%17" DPPM "v_fmac_f32_dpp %1, %5, %13 row_newbcast:%17" DPPM "v_fmac_f32_dpp %2, %6, %14 row_newbcast:%17" DPPM "v_fmac_f32_dpp %3, %7, %15 row_newbcast:%17" DPPM
;                      : "+v"(s[0]), "+v"(s[1]), "+v"(s[2]), "+v"(s[3])
;                      : "v"(a[0]), "v"(a[1]), "v"(a[2]), "v"(a[3]), "v"(S[K]), "v"(S[K + 1]), "v"(S[K + 2]), "v"(S[K + 3]), "v"(S[K + 4]), "v"(S[K + 5]), "v"(S[K + 6]), "v"(S[K + 7]), "n"(N0), "n"(N1));
;         if constexpr (K + 8 < 64) ScanK<K + 8>::dot(S, a, s);
;     }
; __device__ __forceinline__ void scan_pass2(const Params& p, int d) {
;     ...
;         In2 i0, i1; LD2(i0, 0);
; #pragma unroll 1
;         for (int s = 0; s < LC; s += 2) { TOUCH2(i0); SB; LD2(i1, s + 1); SB; ST2(i0, s); TOUCH2(i1); SB; LD2(i0, s + 2); SB; ST2(i1, s + 1); }
.Lmy_p2d1_loop:
	s_waitcnt vmcnt(14)
	s_cmp_eq_u32 s80, 3
	s_cbranch_scc1 .Lmy_p2d1_nost
	buffer_store_dword v200, v207, s[68:71], s79 offen
	s_add_u32 s79, s79, 0xfffff000
.Lmy_p2d1_nost:
	buffer_load_dwordx4 v[156:159], v204, s[64:67], s72 offen
	buffer_load_dwordx4 v[160:163], v204, s[64:67], s73 offen
	buffer_load_dwordx4 v[164:167], v204, s[64:67], s74 offen
	buffer_load_dwordx4 v[168:171], v204, s[64:67], s75 offen
	buffer_load_dwordx2 v[172:173], v205, s[64:67], s76 offen
	buffer_load_ushort v174, v206, s[64:67], s77 offen
	buffer_load_dword v175, v207, s[68:71], s78 offen
	s_cmp_lt_u32 s80, 255
	s_cselect_b32 s81, 0xfffff000, 0
	s_cselect_b32 s82, 0xfffff800, 0
	s_cselect_b32 s9, 1, 0
	s_add_u32 s80, s80, s9
	s_add_u32 s72, s72, s81
	s_add_u32 s73, s73, s81
	s_add_u32 s74, s74, s81
	s_add_u32 s75, s75, s81
	s_add_u32 s78, s78, s81
	s_add_u32 s76, s76, s82
	s_add_u32 s77, s77, s82
	v_pk_mul_f32 v[224:225], v[100:101], v[216:217]
	v_pk_mul_f32 v[226:227], v[102:103], v[218:219]
	v_pk_mul_f32 v[216:217], v[216:217], v[96:97]
	v_pk_mul_f32 v[218:219], v[218:219], v[98:99]
	v_pk_fma_f32 v[184:185], v[104:105], v[188:189], v[192:193]
	v_pk_fma_f32 v[186:187], v[106:107], v[190:191], v[194:195]
	v_pk_mul_f32 v[176:177], v[100:101], v[104:105]
	v_pk_mul_f32 v[178:179], v[102:103], v[106:107]
	v_rcp_f32_e32 v220, v216
	v_rcp_f32_e32 v221, v217
	v_rcp_f32_e32 v222, v218
	v_rcp_f32_e32 v223, v219
	v_lshlrev_b32_e32 v180, 16, v112
	v_and_b32_e32 v181, 0xffff0000, v112
	v_lshlrev_b32_e32 v182, 16, v113
	v_and_b32_e32 v183, 0xffff0000, v113
	v_pk_mul_f32 v[180:181], v[180:181], v[184:185]
	v_pk_mul_f32 v[182:183], v[182:183], v[186:187]
	v_pk_mul_f32 v[228:229], v[108:109], v[216:217]
	v_pk_mul_f32 v[230:231], v[110:111], v[218:219]
	v_pk_mul_f32 v[176:177], v[176:177], v[220:221]
	v_pk_mul_f32 v[178:179], v[178:179], v[222:223]
	v_pk_mul_f32 v[180:181], v[180:181], v[220:221]
	v_pk_mul_f32 v[182:183], v[182:183], v[222:223]
	v_lshlrev_b32_e32 v203, 16, v114
	ds_write_b128 v208, v[176:179]
	ds_write_b128 v208, v[180:183] offset:256
	ds_read2_b32 v[64:65], v209 offset0:0 offset1:4
	ds_read2_b32 v[66:67], v209 offset0:8 offset1:12
	ds_read2_b32 v[68:69], v209 offset0:16 offset1:20
	ds_read2_b32 v[70:71], v209 offset0:24 offset1:28
	ds_read2_b32 v[72:73], v209 offset0:32 offset1:36
	ds_read2_b32 v[74:75], v209 offset0:40 offset1:44
	ds_read2_b32 v[76:77], v209 offset0:48 offset1:52
	ds_read2_b32 v[78:79], v209 offset0:56 offset1:60
	ds_read2_b32 v[80:81], v209 offset0:64 offset1:68
	ds_read2_b32 v[82:83], v209 offset0:72 offset1:76
	ds_read2_b32 v[84:85], v209 offset0:80 offset1:84
	ds_read2_b32 v[86:87], v209 offset0:88 offset1:92
	ds_read2_b32 v[88:89], v209 offset0:96 offset1:100
	ds_read2_b32 v[90:91], v209 offset0:104 offset1:108
	ds_read2_b32 v[92:93], v209 offset0:112 offset1:116
	ds_read2_b32 v[94:95], v209 offset0:120 offset1:124
	v_mul_f32_dpp v196, v224, v0 row_newbcast:0 row_mask:0xf bank_mask:0xf
	v_mul_f32_dpp v197, v225, v1 row_newbcast:0 row_mask:0xf bank_mask:0xf
	v_mul_f32_dpp v198, v226, v2 row_newbcast:0 row_mask:0xf bank_mask:0xf
	v_mul_f32_dpp v199, v227, v3 row_newbcast:0 row_mask:0xf bank_mask:0xf
	v_fmac_f32_dpp v196, v224, v4 row_newbcast:1 row_mask:0xf bank_mask:0xf
	v_fmac_f32_dpp v197, v225, v5 row_newbcast:1 row_mask:0xf bank_mask:0xf
	v_fmac_f32_dpp v198, v226, v6 row_newbcast:1 row_mask:0xf bank_mask:0xf
	v_fmac_f32_dpp v199, v227, v7 row_newbcast:1 row_mask:0xf bank_mask:0xf
	v_fmac_f32_dpp v196, v224, v8 row_newbcast:2 row_mask:0xf bank_mask:0xf
	v_fmac_f32_dpp v197, v225, v9 row_newbcast:2 row_mask:0xf bank_mask:0xf
	v_fmac_f32_dpp v198, v226, v10 row_newbcast:2 row_mask:0xf bank_mask:0xf
	v_fmac_f32_dpp v199, v227, v11 row_newbcast:2 row_mask:0xf bank_mask:0xf
	v_fmac_f32_dpp v196, v224, v12 row_newbcast:3 row_mask:0xf bank_mask:0xf
	v_fmac_f32_dpp v197, v225, v13 row_newbcast:3 row_mask:0xf bank_mask:0xf
	v_fmac_f32_dpp v198, v226, v14 row_newbcast:3 row_mask:0xf bank_mask:0xf
	v_fmac_f32_dpp v199, v227, v15 row_newbcast:3 row_mask:0xf bank_mask:0xf
	v_fmac_f32_dpp v196, v224, v16 row_newbcast:4 row_mask:0xf bank_mask:0xf
	v_fmac_f32_dpp v197, v225, v17 row_newbcast:4 row_mask:0xf bank_mask:0xf
	v_fmac_f32_dpp v198, v226, v18 row_newbcast:4 row_mask:0xf bank_mask:0xf
	v_fmac_f32_dpp v199, v227, v19 row_newbcast:4 row_mask:0xf bank_mask:0xf
	v_fmac_f32_dpp v196, v224, v20 row_newbcast:5 row_mask:0xf bank_mask:0xf
	v_fmac_f32_dpp v197, v225, v21 row_newbcast:5 row_mask:0xf bank_mask:0xf
	v_fmac_f32_dpp v198, v226, v22 row_newbcast:5 row_mask:0xf bank_mask:0xf
	v_fmac_f32_dpp v199, v227, v23 row_newbcast:5 row_mask:0xf bank_mask:0xf
	v_fmac_f32_dpp v196, v224, v24 row_newbcast:6 row_mask:0xf bank_mask:0xf
	v_fmac_f32_dpp v197, v225, v25 row_newbcast:6 row_mask:0xf bank_mask:0xf
	v_fmac_f32_dpp v198, v226, v26 row_newbcast:6 row_mask:0xf bank_mask:0xf
	v_fmac_f32_dpp v199, v227, v27 row_newbcast:6 row_mask:0xf bank_mask:0xf
	v_fmac_f32_dpp v196, v224, v28 row_newbcast:7 row_mask:0xf bank_mask:0xf
	v_fmac_f32_dpp v197, v225, v29 row_newbcast:7 row_mask:0xf bank_mask:0xf
	v_fmac_f32_dpp v198, v226, v30 row_newbcast:7 row_mask:0xf bank_mask:0xf
	v_fmac_f32_dpp v199, v227, v31 row_newbcast:7 row_mask:0xf bank_mask:0xf
	v_fmac_f32_dpp v196, v224, v32 row_newbcast:8 row_mask:0xf bank_mask:0xf
	v_fmac_f32_dpp v197, v225, v33 row_newbcast:8 row_mask:0xf bank_mask:0xf
	v_fmac_f32_dpp v198, v226, v34 row_newbcast:8 row_mask:0xf bank_mask:0xf
	v_fmac_f32_dpp v199, v227, v35 row_newbcast:8 row_mask:0xf bank_mask:0xf
	v_fmac_f32_dpp v196, v224, v36 row_newbcast:9 row_mask:0xf bank_mask:0xf
;     static __device__ __forceinline__ void dot(const float (&S)[64], const f32x4& a, float (&s)[4]) {
;         if constexpr (K == 0) {
;             asm volatile("v_mul_f32_dpp %0, %4, %8 row_newbcast:%16" DPPM "v_mul_f32_dpp %1, %5, %9 row_newbcast:%16" DPPM "v_mul_f32_dpp %2, %6, %10 row_newbcast:%16" DPPM "v_mul_f32_dpp %3, %7, %11 row_newbcast:%16" DPPM
;                          "v_fmac_f32_dpp %0, %4, %12 row_newbcast:%17" DPPM "v_fmac_f32_dpp %1, %5, %13 row_newbcast:%17" DPPM "v_fmac_f32_dpp %2, %6, %14 row_newbcast:%17" DPPM "v_fmac_f32_dpp %3, %7, %15 row_newbcast:%17" DPPM
;                          : "=&v"(s[0]), "=&v"(s[1]), "=&v"(s[2]), "=&v"(s[3])
;                          : "v"(a[0]), "v"(a[1]), "v"(a[2]), "v"(a[3]), "v"(S[K]), "v"(S[K + 1]), "v"(S[K + 2]), "v"(S[K + 3]), "v"(S[K + 4]), "v"(S[K + 5]), "v"(S[K + 6]), "v"(S[K + 7]), "n"(N0), "n"(N1));
;         } else
;         asm volatile("v_fmac_f32_dpp %0, %4, %8 row_newbcast:%16" DPPM "v_fmac_f32_dpp %1, %5, %9 row_newbcast:%16" DPPM "v_fmac_f32_dpp %2, %6, %10 row_newbcast:%16" DPPM "v_fmac_f32_dpp %3, %7, %11 row_newbcast:%16" DPPM
;                      "v_fmac_f32_dpp %0, %4, %12 row_newbcast:%17" DPPM "v_fmac_f32_dpp %1, %5, %13 row_newbcast:%17" DPPM "v_fmac_f32_dpp %2, %6, %14 row_newbcast:%17" DPPM "v_fmac_f32_dpp %3, %7, %15 row_newbcast:%17" DPPM
;                      : "+v"(s[0]), "+v"(s[1]), "+v"(s[2]), "+v"(s[3])
;                      : "v"(a[0]), "v"(a[1]), "v"(a[2]), "v"(a[3]), "v"(S[K]), "v"(S[K + 1]), "v"(S[K + 2]), "v"(S[K + 3]), "v"(S[K + 4]), "v"(S[K + 5]), "v"(S[K + 6]), "v"(S[K + 7]), "n"(N0), "n"(N1));
;         if constexpr (K + 8 < 64) ScanK<K + 8>::dot(S, a, s);
;     }
;     static __device__ __forceinline__ void upd(float (&S)[64], const In2& in, float sa, float vv, float& y0, float& y1) {
;         float t0, t1, t2, t3;
;         asm volatile("v_mul_f32_dpp %0, %10, %27 row_newbcast:%28" DPPM "v_mul_f32_dpp %1, %11, %27 row_newbcast:%28" DPPM "v_mul_f32_dpp %2, %12, %27 row_newbcast:%28" DPPM "v_mul_f32_dpp %3, %13, %27 row_newbcast:%28" DPPM
;                      "v_fmac_f32_dpp %0, %14, %6 row_newbcast:%28" DPPM "v_fmac_f32_dpp %1, %15, %7 row_newbcast:%28" DPPM "v_fmac_f32_dpp %2, %16, %8 row_newbcast:%28" DPPM "v_fmac_f32_dpp %3, %17, %9 row_newbcast:%28" DPPM
	v_fmac_f32_dpp v197, v225, v37 row_newbcast:9 row_mask:0xf bank_mask:0xf
	v_fmac_f32_dpp v198, v226, v38 row_newbcast:9 row_mask:0xf bank_mask:0xf
	v_fmac_f32_dpp v199, v227, v39 row_newbcast:9 row_mask:0xf bank_mask:0xf
	v_fmac_f32_dpp v196, v224, v40 row_newbcast:10 row_mask:0xf bank_mask:0xf
	v_fmac_f32_dpp v197, v225, v41 row_newbcast:10 row_mask:0xf bank_mask:0xf
	v_fmac_f32_dpp v198, v226, v42 row_newbcast:10 row_mask:0xf bank_mask:0xf
	v_fmac_f32_dpp v199, v227, v43 row_newbcast:10 row_mask:0xf bank_mask:0xf
	v_fmac_f32_dpp v196, v224, v44 row_newbcast:11 row_mask:0xf bank_mask:0xf
	v_fmac_f32_dpp v197, v225, v45 row_newbcast:11 row_mask:0xf bank_mask:0xf
	v_fmac_f32_dpp v198, v226, v46 row_newbcast:11 row_mask:0xf bank_mask:0xf
	v_fmac_f32_dpp v199, v227, v47 row_newbcast:11 row_mask:0xf bank_mask:0xf
	v_fmac_f32_dpp v196, v224, v48 row_newbcast:12 row_mask:0xf bank_mask:0xf
	v_fmac_f32_dpp v197, v225, v49 row_newbcast:12 row_mask:0xf bank_mask:0xf
	v_fmac_f32_dpp v198, v226, v50 row_newbcast:12 row_mask:0xf bank_mask:0xf
	v_fmac_f32_dpp v199, v227, v51 row_newbcast:12 row_mask:0xf bank_mask:0xf
	v_fmac_f32_dpp v196, v224, v52 row_newbcast:13 row_mask:0xf bank_mask:0xf
	v_fmac_f32_dpp v197, v225, v53 row_newbcast:13 row_mask:0xf bank_mask:0xf
	v_fmac_f32_dpp v198, v226, v54 row_newbcast:13 row_mask:0xf bank_mask:0xf
	v_fmac_f32_dpp v199, v227, v55 row_newbcast:13 row_mask:0xf bank_mask:0xf
	v_fmac_f32_dpp v196, v224, v56 row_newbcast:14 row_mask:0xf bank_mask:0xf
	v_fmac_f32_dpp v197, v225, v57 row_newbcast:14 row_mask:0xf bank_mask:0xf
	v_fmac_f32_dpp v198, v226, v58 row_newbcast:14 row_mask:0xf bank_mask:0xf
	v_fmac_f32_dpp v199, v227, v59 row_newbcast:14 row_mask:0xf bank_mask:0xf
	v_fmac_f32_dpp v196, v224, v60 row_newbcast:15 row_mask:0xf bank_mask:0xf
	v_fmac_f32_dpp v197, v225, v61 row_newbcast:15 row_mask:0xf bank_mask:0xf
	v_fmac_f32_dpp v198, v226, v62 row_newbcast:15 row_mask:0xf bank_mask:0xf
	v_fmac_f32_dpp v199, v227, v63 row_newbcast:15 row_mask:0xf bank_mask:0xf
	v_add_f32_e32 v196, v196, v197
	v_add_f32_e32 v198, v198, v199
	v_add_f32_e32 v196, v196, v198
	v_xor_b32_e32 v202, 0x80000000, v196
	s_waitcnt lgkmcnt(0)
	s_nop 1
	v_mfma_f32_4x4x1_16b_f32 v[0:3], v64, v202, v[0:3]
	v_mfma_f32_4x4x1_16b_f32 v[4:7], v65, v202, v[4:7]
	v_mfma_f32_4x4x1_16b_f32 v[8:11], v66, v202, v[8:11]
	v_mfma_f32_4x4x1_16b_f32 v[12:15], v67, v202, v[12:15]
	v_mfma_f32_4x4x1_16b_f32 v[16:19], v68, v202, v[16:19]
	v_mfma_f32_4x4x1_16b_f32 v[20:23], v69, v202, v[20:23]
	v_mfma_f32_4x4x1_16b_f32 v[24:27], v70, v202, v[24:27]
	v_mfma_f32_4x4x1_16b_f32 v[28:31], v71, v202, v[28:31]
	v_mfma_f32_4x4x1_16b_f32 v[32:35], v72, v202, v[32:35]
	v_mfma_f32_4x4x1_16b_f32 v[36:39], v73, v202, v[36:39]
	v_mfma_f32_4x4x1_16b_f32 v[40:43], v74, v202, v[40:43]
	v_mfma_f32_4x4x1_16b_f32 v[44:47], v75, v202, v[44:47]
	v_mfma_f32_4x4x1_16b_f32 v[48:51], v76, v202, v[48:51]
	v_mfma_f32_4x4x1_16b_f32 v[52:55], v77, v202, v[52:55]
	v_mfma_f32_4x4x1_16b_f32 v[56:59], v78, v202, v[56:59]
	v_mfma_f32_4x4x1_16b_f32 v[60:63], v79, v202, v[60:63]
	v_mfma_f32_4x4x1_16b_f32 v[0:3], v80, v203, v[0:3]
	v_mfma_f32_4x4x1_16b_f32 v[4:7], v81, v203, v[4:7]
	v_mfma_f32_4x4x1_16b_f32 v[8:11], v82, v203, v[8:11]
	v_mfma_f32_4x4x1_16b_f32 v[12:15], v83, v203, v[12:15]
	v_mfma_f32_4x4x1_16b_f32 v[16:19], v84, v203, v[16:19]
	v_mfma_f32_4x4x1_16b_f32 v[20:23], v85, v203, v[20:23]
	v_mfma_f32_4x4x1_16b_f32 v[24:27], v86, v203, v[24:27]
	v_mfma_f32_4x4x1_16b_f32 v[28:31], v87, v203, v[28:31]
	v_mfma_f32_4x4x1_16b_f32 v[32:35], v88, v203, v[32:35]
	v_mfma_f32_4x4x1_16b_f32 v[36:39], v89, v203, v[36:39]
	v_mfma_f32_4x4x1_16b_f32 v[40:43], v90, v203, v[40:43]
	v_mfma_f32_4x4x1_16b_f32 v[44:47], v91, v203, v[44:47]
	v_mfma_f32_4x4x1_16b_f32 v[48:51], v92, v203, v[48:51]
	v_mfma_f32_4x4x1_16b_f32 v[52:55], v93, v203, v[52:55]
	v_mfma_f32_4x4x1_16b_f32 v[56:59], v94, v203, v[56:59]
	v_mfma_f32_4x4x1_16b_f32 v[60:63], v95, v203, v[60:63]
	v_fmac_f32_dpp v115, v228, v0 row_newbcast:0 row_mask:0xf bank_mask:0xf
	v_mul_f32_dpp v201, v229, v1 row_newbcast:0 row_mask:0xf bank_mask:0xf
	v_fmac_f32_dpp v115, v230, v2 row_newbcast:0 row_mask:0xf bank_mask:0xf
	v_fmac_f32_dpp v201, v231, v3 row_newbcast:0 row_mask:0xf bank_mask:0xf
	v_fmac_f32_dpp v115, v228, v4 row_newbcast:1 row_mask:0xf bank_mask:0xf
	v_fmac_f32_dpp v201, v229, v5 row_newbcast:1 row_mask:0xf bank_mask:0xf
	v_fmac_f32_dpp v115, v230, v6 row_newbcast:1 row_mask:0xf bank_mask:0xf
	v_fmac_f32_dpp v201, v231, v7 row_newbcast:1 row_mask:0xf bank_mask:0xf
	v_fmac_f32_dpp v115, v228, v8 row_newbcast:2 row_mask:0xf bank_mask:0xf
	v_fmac_f32_dpp v201, v229, v9 row_newbcast:2 row_mask:0xf bank_mask:0xf
	v_fmac_f32_dpp v115, v230, v10 row_newbcast:2 row_mask:0xf bank_mask:0xf
	v_fmac_f32_dpp v201, v231, v11 row_newbcast:2 row_mask:0xf bank_mask:0xf
	v_fmac_f32_dpp v115, v228, v12 row_newbcast:3 row_mask:0xf bank_mask:0xf
	v_fmac_f32_dpp v201, v229, v13 row_newbcast:3 row_mask:0xf bank_mask:0xf
	v_fmac_f32_dpp v115, v230, v14 row_newbcast:3 row_mask:0xf bank_mask:0xf
	v_fmac_f32_dpp v201, v231, v15 row_newbcast:3 row_mask:0xf bank_mask:0xf
	v_fmac_f32_dpp v115, v228, v16 row_newbcast:4 row_mask:0xf bank_mask:0xf
	v_fmac_f32_dpp v201, v229, v17 row_newbcast:4 row_mask:0xf bank_mask:0xf
	v_fmac_f32_dpp v115, v230, v18 row_newbcast:4 row_mask:0xf bank_mask:0xf
	v_fmac_f32_dpp v201, v231, v19 row_newbcast:4 row_mask:0xf bank_mask:0xf
	v_fmac_f32_dpp v115, v228, v20 row_newbcast:5 row_mask:0xf bank_mask:0xf
	v_fmac_f32_dpp v201, v229, v21 row_newbcast:5 row_mask:0xf bank_mask:0xf
	v_fmac_f32_dpp v115, v230, v22 row_newbcast:5 row_mask:0xf bank_mask:0xf
; #define SB __builtin_amdgcn_sched_barrier(0)
; #define ST2(set, s) { DERIVE_BK(set); float sd[4]; ScanK<0>::dot(S, set.a, sd); float y0 = set.yo, y1 = 0.f; ScanK<0>::upd(S, set, -((sd[0] + sd[1]) + (sd[2] + sd[3])), __uint_as_float(set.v << 16), y0, y1); __builtin_amdgcn_raw_buffer_store_b32(__float_as_uint(y0 + y1), rY, lo4b, ob4 + (unsigned)((int)(s) * (int)stp * 4), 0); }
; #define TOUCH2(set) asm volatile("" :: "v"(set.w), "v"(set.a), "v"(set.b), "v"(set.kw), "v"(set.r), "v"(set.v), "v"(set.yo))
; __device__ __forceinline__ void scan_pass2(const Params& p, int d) {
;     ...
;         In2 i0, i1; LD2(i0, 0);
; #pragma unroll 1
;         for (int s = 0; s < LC; s += 2) { TOUCH2(i0); SB; LD2(i1, s + 1); SB; ST2(i0, s); TOUCH2(i1); SB; LD2(i0, s + 2); SB; ST2(i1, s + 1); }
	v_fmac_f32_dpp v201, v231, v23 row_newbcast:5 row_mask:0xf bank_mask:0xf
	v_fmac_f32_dpp v115, v228, v24 row_newbcast:6 row_mask:0xf bank_mask:0xf
	v_fmac_f32_dpp v201, v229, v25 row_newbcast:6 row_mask:0xf bank_mask:0xf
	v_fmac_f32_dpp v115, v230, v26 row_newbcast:6 row_mask:0xf bank_mask:0xf
	v_fmac_f32_dpp v201, v231, v27 row_newbcast:6 row_mask:0xf bank_mask:0xf
	v_fmac_f32_dpp v115, v228, v28 row_newbcast:7 row_mask:0xf bank_mask:0xf
	v_fmac_f32_dpp v201, v229, v29 row_newbcast:7 row_mask:0xf bank_mask:0xf
	v_fmac_f32_dpp v115, v230, v30 row_newbcast:7 row_mask:0xf bank_mask:0xf
	v_fmac_f32_dpp v201, v231, v31 row_newbcast:7 row_mask:0xf bank_mask:0xf
	v_fmac_f32_dpp v115, v228, v32 row_newbcast:8 row_mask:0xf bank_mask:0xf
	v_fmac_f32_dpp v201, v229, v33 row_newbcast:8 row_mask:0xf bank_mask:0xf
	v_fmac_f32_dpp v115, v230, v34 row_newbcast:8 row_mask:0xf bank_mask:0xf
	v_fmac_f32_dpp v201, v231, v35 row_newbcast:8 row_mask:0xf bank_mask:0xf
	v_fmac_f32_dpp v115, v228, v36 row_newbcast:9 row_mask:0xf bank_mask:0xf
	v_fmac_f32_dpp v201, v229, v37 row_newbcast:9 row_mask:0xf bank_mask:0xf
	v_fmac_f32_dpp v115, v230, v38 row_newbcast:9 row_mask:0xf bank_mask:0xf
	v_fmac_f32_dpp v201, v231, v39 row_newbcast:9 row_mask:0xf bank_mask:0xf
	v_fmac_f32_dpp v115, v228, v40 row_newbcast:10 row_mask:0xf bank_mask:0xf
	v_fmac_f32_dpp v201, v229, v41 row_newbcast:10 row_mask:0xf bank_mask:0xf
	v_fmac_f32_dpp v115, v230, v42 row_newbcast:10 row_mask:0xf bank_mask:0xf
	v_fmac_f32_dpp v201, v231, v43 row_newbcast:10 row_mask:0xf bank_mask:0xf
	v_fmac_f32_dpp v115, v228, v44 row_newbcast:11 row_mask:0xf bank_mask:0xf
	v_fmac_f32_dpp v201, v229, v45 row_newbcast:11 row_mask:0xf bank_mask:0xf
	v_fmac_f32_dpp v115, v230, v46 row_newbcast:11 row_mask:0xf bank_mask:0xf
	v_fmac_f32_dpp v201, v231, v47 row_newbcast:11 row_mask:0xf bank_mask:0xf
	v_fmac_f32_dpp v115, v228, v48 row_newbcast:12 row_mask:0xf bank_mask:0xf
	v_fmac_f32_dpp v201, v229, v49 row_newbcast:12 row_mask:0xf bank_mask:0xf
	v_fmac_f32_dpp v115, v230, v50 row_newbcast:12 row_mask:0xf bank_mask:0xf
	v_fmac_f32_dpp v201, v231, v51 row_newbcast:12 row_mask:0xf bank_mask:0xf
	v_fmac_f32_dpp v115, v228, v52 row_newbcast:13 row_mask:0xf bank_mask:0xf
	v_fmac_f32_dpp v201, v229, v53 row_newbcast:13 row_mask:0xf bank_mask:0xf
	v_fmac_f32_dpp v115, v230, v54 row_newbcast:13 row_mask:0xf bank_mask:0xf
	v_fmac_f32_dpp v201, v231, v55 row_newbcast:13 row_mask:0xf bank_mask:0xf
	v_fmac_f32_dpp v115, v228, v56 row_newbcast:14 row_mask:0xf bank_mask:0xf
	v_fmac_f32_dpp v201, v229, v57 row_newbcast:14 row_mask:0xf bank_mask:0xf
	v_fmac_f32_dpp v115, v230, v58 row_newbcast:14 row_mask:0xf bank_mask:0xf
	v_fmac_f32_dpp v201, v231, v59 row_newbcast:14 row_mask:0xf bank_mask:0xf
	v_fmac_f32_dpp v115, v228, v60 row_newbcast:15 row_mask:0xf bank_mask:0xf
	v_fmac_f32_dpp v201, v229, v61 row_newbcast:15 row_mask:0xf bank_mask:0xf
	v_fmac_f32_dpp v115, v230, v62 row_newbcast:15 row_mask:0xf bank_mask:0xf
	v_fmac_f32_dpp v201, v231, v63 row_newbcast:15 row_mask:0xf bank_mask:0xf
	v_add_f32_e32 v200, v115, v201
	s_waitcnt vmcnt(14)
	buffer_store_dword v200, v207, s[68:71], s79 offen
	s_add_u32 s79, s79, 0xfffff000
	buffer_load_dwordx4 v[96:99], v204, s[64:67], s72 offen
	buffer_load_dwordx4 v[100:103], v204, s[64:67], s73 offen
	buffer_load_dwordx4 v[104:107], v204, s[64:67], s74 offen
	buffer_load_dwordx4 v[108:111], v204, s[64:67], s75 offen
	buffer_load_dwordx2 v[112:113], v205, s[64:67], s76 offen
	buffer_load_ushort v114, v206, s[64:67], s77 offen
	buffer_load_dword v115, v207, s[68:71], s78 offen
	s_cmp_lt_u32 s80, 255
	s_cselect_b32 s81, 0xfffff000, 0
	s_cselect_b32 s82, 0xfffff800, 0
	s_cselect_b32 s9, 1, 0
	s_add_u32 s80, s80, s9
	s_add_u32 s72, s72, s81
	s_add_u32 s73, s73, s81
	s_add_u32 s74, s74, s81
	s_add_u32 s75, s75, s81
	s_add_u32 s78, s78, s81
	s_add_u32 s76, s76, s82
	s_add_u32 s77, s77, s82
	v_pk_mul_f32 v[224:225], v[120:121], v[216:217]
	v_pk_mul_f32 v[226:227], v[122:123], v[218:219]
	v_pk_mul_f32 v[216:217], v[216:217], v[116:117]
	v_pk_mul_f32 v[218:219], v[218:219], v[118:119]
	v_pk_fma_f32 v[184:185], v[124:125], v[188:189], v[192:193]
	v_pk_fma_f32 v[186:187], v[126:127], v[190:191], v[194:195]
	v_pk_mul_f32 v[176:177], v[120:121], v[124:125]
	v_pk_mul_f32 v[178:179], v[122:123], v[126:127]
	v_rcp_f32_e32 v220, v216
	v_rcp_f32_e32 v221, v217
	v_rcp_f32_e32 v222, v218
	v_rcp_f32_e32 v223, v219
	v_lshlrev_b32_e32 v180, 16, v132
	v_and_b32_e32 v181, 0xffff0000, v132
	v_lshlrev_b32_e32 v182, 16, v133
	v_and_b32_e32 v183, 0xffff0000, v133
	v_pk_mul_f32 v[180:181], v[180:181], v[184:185]
	v_pk_mul_f32 v[182:183], v[182:183], v[186:187]
	v_pk_mul_f32 v[228:229], v[128:129], v[216:217]
	v_pk_mul_f32 v[230:231], v[130:131], v[218:219]
	v_pk_mul_f32 v[176:177], v[176:177], v[220:221]
	v_pk_mul_f32 v[178:179], v[178:179], v[222:223]
	v_pk_mul_f32 v[180:181], v[180:181], v[220:221]
	v_pk_mul_f32 v[182:183], v[182:183], v[222:223]
	v_lshlrev_b32_e32 v203, 16, v134
	ds_write_b128 v208, v[176:179]
	ds_write_b128 v208, v[180:183] offset:256
	ds_read2_b32 v[64:65], v209 offset0:0 offset1:4
	ds_read2_b32 v[66:67], v209 offset0:8 offset1:12
	ds_read2_b32 v[68:69], v209 offset0:16 offset1:20
	ds_read2_b32 v[70:71], v209 offset0:24 offset1:28
	ds_read2_b32 v[72:73], v209 offset0:32 offset1:36
	ds_read2_b32 v[74:75], v209 offset0:40 offset1:44
	ds_read2_b32 v[76:77], v209 offset0:48 offset1:52
	ds_read2_b32 v[78:79], v209 offset0:56 offset1:60
	ds_read2_b32 v[80:81], v209 offset0:64 offset1:68
	ds_read2_b32 v[82:83], v209 offset0:72 offset1:76
	ds_read2_b32 v[84:85], v209 offset0:80 offset1:84
;     static __device__ __forceinline__ void dot(const float (&S)[64], const f32x4& a, float (&s)[4]) {
;         if constexpr (K == 0) {
;             asm volatile("v_mul_f32_dpp %0, %4, %8 row_newbcast:%16" DPPM "v_mul_f32_dpp %1, %5, %9 row_newbcast:%16" DPPM "v_mul_f32_dpp %2, %6, %10 row_newbcast:%16" DPPM "v_mul_f32_dpp %3, %7, %11 row_newbcast:%16" DPPM
;                          "v_fmac_f32_dpp %0, %4, %12 row_newbcast:%17" DPPM "v_fmac_f32_dpp %1, %5, %13 row_newbcast:%17" DPPM "v_fmac_f32_dpp %2, %6, %14 row_newbcast:%17" DPPM "v_fmac_f32_dpp %3, %7, %15 row_newbcast:%17" DPPM
;                          : "=&v"(s[0]), "=&v"(s[1]), "=&v"(s[2]), "=&v"(s[3])
;                          : "v"(a[0]), "v"(a[1]), "v"(a[2]), "v"(a[3]), "v"(S[K]), "v"(S[K + 1]), "v"(S[K + 2]), "v"(S[K + 3]), "v"(S[K + 4]), "v"(S[K + 5]), "v"(S[K + 6]), "v"(S[K + 7]), "n"(N0), "n"(N1));
;         } else
;         asm volatile("v_fmac_f32_dpp %0, %4, %8 row_newbcast:%16" DPPM "v_fmac_f32_dpp %1, %5, %9 row_newbcast:%16" DPPM "v_fmac_f32_dpp %2, %6, %10 row_newbcast:%16" DPPM "v_fmac_f32_dpp %3, %7, %11 row_newbcast:%16" DPPM
;                      "v_fmac_f32_dpp %0, %4, %12 row_newbcast:%17" DPPM "v_fmac_f32_dpp %1, %5, %13 row_newbcast:%17" DPPM "v_fmac_f32_dpp %2, %6, %14 row_newbcast:%17" DPPM "v_fmac_f32_dpp %3, %7, %15 row_newbcast:%17" DPPM
;                      : "+v"(s[0]), "+v"(s[1]), "+v"(s[2]), "+v"(s[3])
;                      : "v"(a[0]), "v"(a[1]), "v"(a[2]), "v"(a[3]), "v"(S[K]), "v"(S[K + 1]), "v"(S[K + 2]), "v"(S[K + 3]), "v"(S[K + 4]), "v"(S[K + 5]), "v"(S[K + 6]), "v"(S[K + 7]), "n"(N0), "n"(N1));
;         if constexpr (K + 8 < 64) ScanK<K + 8>::dot(S, a, s);
;     }
	ds_read2_b32 v[86:87], v209 offset0:88 offset1:92
	ds_read2_b32 v[88:89], v209 offset0:96 offset1:100
	ds_read2_b32 v[90:91], v209 offset0:104 offset1:108
	ds_read2_b32 v[92:93], v209 offset0:112 offset1:116
	ds_read2_b32 v[94:95], v209 offset0:120 offset1:124
	v_mul_f32_dpp v196, v224, v0 row_newbcast:0 row_mask:0xf bank_mask:0xf
	v_mul_f32_dpp v197, v225, v1 row_newbcast:0 row_mask:0xf bank_mask:0xf
	v_mul_f32_dpp v198, v226, v2 row_newbcast:0 row_mask:0xf bank_mask:0xf
	v_mul_f32_dpp v199, v227, v3 row_newbcast:0 row_mask:0xf bank_mask:0xf
	v_fmac_f32_dpp v196, v224, v4 row_newbcast:1 row_mask:0xf bank_mask:0xf
	v_fmac_f32_dpp v197, v225, v5 row_newbcast:1 row_mask:0xf bank_mask:0xf
	v_fmac_f32_dpp v198, v226, v6 row_newbcast:1 row_mask:0xf bank_mask:0xf
	v_fmac_f32_dpp v199, v227, v7 row_newbcast:1 row_mask:0xf bank_mask:0xf
	v_fmac_f32_dpp v196, v224, v8 row_newbcast:2 row_mask:0xf bank_mask:0xf
	v_fmac_f32_dpp v197, v225, v9 row_newbcast:2 row_mask:0xf bank_mask:0xf
	v_fmac_f32_dpp v198, v226, v10 row_newbcast:2 row_mask:0xf bank_mask:0xf
	v_fmac_f32_dpp v199, v227, v11 row_newbcast:2 row_mask:0xf bank_mask:0xf
	v_fmac_f32_dpp v196, v224, v12 row_newbcast:3 row_mask:0xf bank_mask:0xf
	v_fmac_f32_dpp v197, v225, v13 row_newbcast:3 row_mask:0xf bank_mask:0xf
	v_fmac_f32_dpp v198, v226, v14 row_newbcast:3 row_mask:0xf bank_mask:0xf
	v_fmac_f32_dpp v199, v227, v15 row_newbcast:3 row_mask:0xf bank_mask:0xf
	v_fmac_f32_dpp v196, v224, v16 row_newbcast:4 row_mask:0xf bank_mask:0xf
	v_fmac_f32_dpp v197, v225, v17 row_newbcast:4 row_mask:0xf bank_mask:0xf
	v_fmac_f32_dpp v198, v226, v18 row_newbcast:4 row_mask:0xf bank_mask:0xf
	v_fmac_f32_dpp v199, v227, v19 row_newbcast:4 row_mask:0xf bank_mask:0xf
	v_fmac_f32_dpp v196, v224, v20 row_newbcast:5 row_mask:0xf bank_mask:0xf
	v_fmac_f32_dpp v197, v225, v21 row_newbcast:5 row_mask:0xf bank_mask:0xf
	v_fmac_f32_dpp v198, v226, v22 row_newbcast:5 row_mask:0xf bank_mask:0xf
	v_fmac_f32_dpp v199, v227, v23 row_newbcast:5 row_mask:0xf bank_mask:0xf
	v_fmac_f32_dpp v196, v224, v24 row_newbcast:6 row_mask:0xf bank_mask:0xf
	v_fmac_f32_dpp v197, v225, v25 row_newbcast:6 row_mask:0xf bank_mask:0xf
	v_fmac_f32_dpp v198, v226, v26 row_newbcast:6 row_mask:0xf bank_mask:0xf
	v_fmac_f32_dpp v199, v227, v27 row_newbcast:6 row_mask:0xf bank_mask:0xf
	v_fmac_f32_dpp v196, v224, v28 row_newbcast:7 row_mask:0xf bank_mask:0xf
	v_fmac_f32_dpp v197, v225, v29 row_newbcast:7 row_mask:0xf bank_mask:0xf
	v_fmac_f32_dpp v198, v226, v30 row_newbcast:7 row_mask:0xf bank_mask:0xf
	v_fmac_f32_dpp v199, v227, v31 row_newbcast:7 row_mask:0xf bank_mask:0xf
	v_fmac_f32_dpp v196, v224, v32 row_newbcast:8 row_mask:0xf bank_mask:0xf
	v_fmac_f32_dpp v197, v225, v33 row_newbcast:8 row_mask:0xf bank_mask:0xf
	v_fmac_f32_dpp v198, v226, v34 row_newbcast:8 row_mask:0xf bank_mask:0xf
	v_fmac_f32_dpp v199, v227, v35 row_newbcast:8 row_mask:0xf bank_mask:0xf
	v_fmac_f32_dpp v196, v224, v36 row_newbcast:9 row_mask:0xf bank_mask:0xf
	v_fmac_f32_dpp v197, v225, v37 row_newbcast:9 row_mask:0xf bank_mask:0xf
	v_fmac_f32_dpp v198, v226, v38 row_newbcast:9 row_mask:0xf bank_mask:0xf
	v_fmac_f32_dpp v199, v227, v39 row_newbcast:9 row_mask:0xf bank_mask:0xf
	v_fmac_f32_dpp v196, v224, v40 row_newbcast:10 row_mask:0xf bank_mask:0xf
	v_fmac_f32_dpp v197, v225, v41 row_newbcast:10 row_mask:0xf bank_mask:0xf
	v_fmac_f32_dpp v198, v226, v42 row_newbcast:10 row_mask:0xf bank_mask:0xf
	v_fmac_f32_dpp v199, v227, v43 row_newbcast:10 row_mask:0xf bank_mask:0xf
	v_fmac_f32_dpp v196, v224, v44 row_newbcast:11 row_mask:0xf bank_mask:0xf
	v_fmac_f32_dpp v197, v225, v45 row_newbcast:11 row_mask:0xf bank_mask:0xf
	v_fmac_f32_dpp v198, v226, v46 row_newbcast:11 row_mask:0xf bank_mask:0xf
	v_fmac_f32_dpp v199, v227, v47 row_newbcast:11 row_mask:0xf bank_mask:0xf
	v_fmac_f32_dpp v196, v224, v48 row_newbcast:12 row_mask:0xf bank_mask:0xf
	v_fmac_f32_dpp v197, v225, v49 row_newbcast:12 row_mask:0xf bank_mask:0xf
	v_fmac_f32_dpp v198, v226, v50 row_newbcast:12 row_mask:0xf bank_mask:0xf
	v_fmac_f32_dpp v199, v227, v51 row_newbcast:12 row_mask:0xf bank_mask:0xf
	v_fmac_f32_dpp v196, v224, v52 row_newbcast:13 row_mask:0xf bank_mask:0xf
	v_fmac_f32_dpp v197, v225, v53 row_newbcast:13 row_mask:0xf bank_mask:0xf
	v_fmac_f32_dpp v198, v226, v54 row_newbcast:13 row_mask:0xf bank_mask:0xf
	v_fmac_f32_dpp v199, v227, v55 row_newbcast:13 row_mask:0xf bank_mask:0xf
	v_fmac_f32_dpp v196, v224, v56 row_newbcast:14 row_mask:0xf bank_mask:0xf
	v_fmac_f32_dpp v197, v225, v57 row_newbcast:14 row_mask:0xf bank_mask:0xf
	v_fmac_f32_dpp v198, v226, v58 row_newbcast:14 row_mask:0xf bank_mask:0xf
	v_fmac_f32_dpp v199, v227, v59 row_newbcast:14 row_mask:0xf bank_mask:0xf
	v_fmac_f32_dpp v196, v224, v60 row_newbcast:15 row_mask:0xf bank_mask:0xf
	v_fmac_f32_dpp v197, v225, v61 row_newbcast:15 row_mask:0xf bank_mask:0xf
	v_fmac_f32_dpp v198, v226, v62 row_newbcast:15 row_mask:0xf bank_mask:0xf
	v_fmac_f32_dpp v199, v227, v63 row_newbcast:15 row_mask:0xf bank_mask:0xf
	v_add_f32_e32 v196, v196, v197
	v_add_f32_e32 v198, v198, v199
	v_add_f32_e32 v196, v196, v198
	v_xor_b32_e32 v202, 0x80000000, v196
	s_waitcnt lgkmcnt(0)
;     static __device__ __forceinline__ void upd(float (&S)[64], const In2& in, float sa, float vv, float& y0, float& y1) {
;         float t0, t1, t2, t3;
;         asm volatile("v_mul_f32_dpp %0, %10, %27 row_newbcast:%28" DPPM "v_mul_f32_dpp %1, %11, %27 row_newbcast:%28" DPPM "v_mul_f32_dpp %2, %12, %27 row_newbcast:%28" DPPM "v_mul_f32_dpp %3, %13, %27 row_newbcast:%28" DPPM
;                      "v_fmac_f32_dpp %0, %14, %6 row_newbcast:%28" DPPM "v_fmac_f32_dpp %1, %15, %7 row_newbcast:%28" DPPM "v_fmac_f32_dpp %2, %16, %8 row_newbcast:%28" DPPM "v_fmac_f32_dpp %3, %17, %9 row_newbcast:%28" DPPM
;                      "v_fmac_f32_dpp %0, %18, %26 row_newbcast:%28" DPPM "v_fmac_f32_dpp %1, %19, %26 row_newbcast:%28" DPPM "v_fmac_f32_dpp %2, %20, %26 row_newbcast:%28" DPPM "v_fmac_f32_dpp %3, %21, %26 row_newbcast:%28" DPPM
;                      "v_fmac_f32_dpp %4, %22, %0 row_newbcast:%28" DPPM "v_fmac_f32_dpp %5, %23, %1 row_newbcast:%28" DPPM "v_fmac_f32_dpp %4, %24, %2 row_newbcast:%28" DPPM "v_fmac_f32_dpp %5, %25, %3 row_newbcast:%28" DPPM
;                      : "=&v"(t0), "=&v"(t1), "=&v"(t2), "=&v"(t3), "+v"(y0), "+v"(y1)
;                      : "v"(S[K]), "v"(S[K + 1]), "v"(S[K + 2]), "v"(S[K + 3]), "v"(in.kd[0]), "v"(in.kd[1]), "v"(in.kd[2]), "v"(in.kd[3]), "v"(in.w[0]), "v"(in.w[1]), "v"(in.w[2]), "v"(in.w[3]),
;                        "v"(in.b[0]), "v"(in.b[1]), "v"(in.b[2]), "v"(in.b[3]), "v"(in.r[0]), "v"(in.r[1]), "v"(in.r[2]), "v"(in.r[3]), "v"(sa), "v"(vv), "n"(N0));
;         S[K] = t0; S[K + 1] = t1; S[K + 2] = t2; S[K + 3] = t3;
;         if constexpr (K + 4 < 64) ScanK<K + 4>::upd(S, in, sa, vv, y0, y1);
;     }
	s_nop 1
	v_mfma_f32_4x4x1_16b_f32 v[0:3], v64, v202, v[0:3]
	v_mfma_f32_4x4x1_16b_f32 v[4:7], v65, v202, v[4:7]
	v_mfma_f32_4x4x1_16b_f32 v[8:11], v66, v202, v[8:11]
	v_mfma_f32_4x4x1_16b_f32 v[12:15], v67, v202, v[12:15]
	v_mfma_f32_4x4x1_16b_f32 v[16:19], v68, v202, v[16:19]
	v_mfma_f32_4x4x1_16b_f32 v[20:23], v69, v202, v[20:23]
	v_mfma_f32_4x4x1_16b_f32 v[24:27], v70, v202, v[24:27]
	v_mfma_f32_4x4x1_16b_f32 v[28:31], v71, v202, v[28:31]
	v_mfma_f32_4x4x1_16b_f32 v[32:35], v72, v202, v[32:35]
	v_mfma_f32_4x4x1_16b_f32 v[36:39], v73, v202, v[36:39]
	v_mfma_f32_4x4x1_16b_f32 v[40:43], v74, v202, v[40:43]
	v_mfma_f32_4x4x1_16b_f32 v[44:47], v75, v202, v[44:47]
	v_mfma_f32_4x4x1_16b_f32 v[48:51], v76, v202, v[48:51]
	v_mfma_f32_4x4x1_16b_f32 v[52:55], v77, v202, v[52:55]
	v_mfma_f32_4x4x1_16b_f32 v[56:59], v78, v202, v[56:59]
	v_mfma_f32_4x4x1_16b_f32 v[60:63], v79, v202, v[60:63]
	v_mfma_f32_4x4x1_16b_f32 v[0:3], v80, v203, v[0:3]
	v_mfma_f32_4x4x1_16b_f32 v[4:7], v81, v203, v[4:7]
	v_mfma_f32_4x4x1_16b_f32 v[8:11], v82, v203, v[8:11]
	v_mfma_f32_4x4x1_16b_f32 v[12:15], v83, v203, v[12:15]
	v_mfma_f32_4x4x1_16b_f32 v[16:19], v84, v203, v[16:19]
	v_mfma_f32_4x4x1_16b_f32 v[20:23], v85, v203, v[20:23]
	v_mfma_f32_4x4x1_16b_f32 v[24:27], v86, v203, v[24:27]
	v_mfma_f32_4x4x1_16b_f32 v[28:31], v87, v203, v[28:31]
	v_mfma_f32_4x4x1_16b_f32 v[32:35], v88, v203, v[32:35]
	v_mfma_f32_4x4x1_16b_f32 v[36:39], v89, v203, v[36:39]
	v_mfma_f32_4x4x1_16b_f32 v[40:43], v90, v203, v[40:43]
	v_mfma_f32_4x4x1_16b_f32 v[44:47], v91, v203, v[44:47]
	v_mfma_f32_4x4x1_16b_f32 v[48:51], v92, v203, v[48:51]
	v_mfma_f32_4x4x1_16b_f32 v[52:55], v93, v203, v[52:55]
	v_mfma_f32_4x4x1_16b_f32 v[56:59], v94, v203, v[56:59]
	v_mfma_f32_4x4x1_16b_f32 v[60:63], v95, v203, v[60:63]
	v_fmac_f32_dpp v135, v228, v0 row_newbcast:0 row_mask:0xf bank_mask:0xf
	v_mul_f32_dpp v201, v229, v1 row_newbcast:0 row_mask:0xf bank_mask:0xf
	v_fmac_f32_dpp v135, v230, v2 row_newbcast:0 row_mask:0xf bank_mask:0xf
	v_fmac_f32_dpp v201, v231, v3 row_newbcast:0 row_mask:0xf bank_mask:0xf
	v_fmac_f32_dpp v135, v228, v4 row_newbcast:1 row_mask:0xf bank_mask:0xf
	v_fmac_f32_dpp v201, v229, v5 row_newbcast:1 row_mask:0xf bank_mask:0xf
	v_fmac_f32_dpp v135, v230, v6 row_newbcast:1 row_mask:0xf bank_mask:0xf
	v_fmac_f32_dpp v201, v231, v7 row_newbcast:1 row_mask:0xf bank_mask:0xf
	v_fmac_f32_dpp v135, v228, v8 row_newbcast:2 row_mask:0xf bank_mask:0xf
	v_fmac_f32_dpp v201, v229, v9 row_newbcast:2 row_mask:0xf bank_mask:0xf
	v_fmac_f32_dpp v135, v230, v10 row_newbcast:2 row_mask:0xf bank_mask:0xf
	v_fmac_f32_dpp v201, v231, v11 row_newbcast:2 row_mask:0xf bank_mask:0xf
	v_fmac_f32_dpp v135, v228, v12 row_newbcast:3 row_mask:0xf bank_mask:0xf
	v_fmac_f32_dpp v201, v229, v13 row_newbcast:3 row_mask:0xf bank_mask:0xf
	v_fmac_f32_dpp v135, v230, v14 row_newbcast:3 row_mask:0xf bank_mask:0xf
	v_fmac_f32_dpp v201, v231, v15 row_newbcast:3 row_mask:0xf bank_mask:0xf
	v_fmac_f32_dpp v135, v228, v16 row_newbcast:4 row_mask:0xf bank_mask:0xf
	v_fmac_f32_dpp v201, v229, v17 row_newbcast:4 row_mask:0xf bank_mask:0xf
	v_fmac_f32_dpp v135, v230, v18 row_newbcast:4 row_mask:0xf bank_mask:0xf
	v_fmac_f32_dpp v201, v231, v19 row_newbcast:4 row_mask:0xf bank_mask:0xf
	v_fmac_f32_dpp v135, v228, v20 row_newbcast:5 row_mask:0xf bank_mask:0xf
	v_fmac_f32_dpp v201, v229, v21 row_newbcast:5 row_mask:0xf bank_mask:0xf
	v_fmac_f32_dpp v135, v230, v22 row_newbcast:5 row_mask:0xf bank_mask:0xf
	v_fmac_f32_dpp v201, v231, v23 row_newbcast:5 row_mask:0xf bank_mask:0xf
	v_fmac_f32_dpp v135, v228, v24 row_newbcast:6 row_mask:0xf bank_mask:0xf
	v_fmac_f32_dpp v201, v229, v25 row_newbcast:6 row_mask:0xf bank_mask:0xf
	v_fmac_f32_dpp v135, v230, v26 row_newbcast:6 row_mask:0xf bank_mask:0xf
	v_fmac_f32_dpp v201, v231, v27 row_newbcast:6 row_mask:0xf bank_mask:0xf
	v_fmac_f32_dpp v135, v228, v28 row_newbcast:7 row_mask:0xf bank_mask:0xf
	v_fmac_f32_dpp v201, v229, v29 row_newbcast:7 row_mask:0xf bank_mask:0xf
	v_fmac_f32_dpp v135, v230, v30 row_newbcast:7 row_mask:0xf bank_mask:0xf
	v_fmac_f32_dpp v201, v231, v31 row_newbcast:7 row_mask:0xf bank_mask:0xf
	v_fmac_f32_dpp v135, v228, v32 row_newbcast:8 row_mask:0xf bank_mask:0xf
	v_fmac_f32_dpp v201, v229, v33 row_newbcast:8 row_mask:0xf bank_mask:0xf
	v_fmac_f32_dpp v135, v230, v34 row_newbcast:8 row_mask:0xf bank_mask:0xf
	v_fmac_f32_dpp v201, v231, v35 row_newbcast:8 row_mask:0xf bank_mask:0xf
	v_fmac_f32_dpp v135, v228, v36 row_newbcast:9 row_mask:0xf bank_mask:0xf
	v_fmac_f32_dpp v201, v229, v37 row_newbcast:9 row_mask:0xf bank_mask:0xf
	v_fmac_f32_dpp v135, v230, v38 row_newbcast:9 row_mask:0xf bank_mask:0xf
	v_fmac_f32_dpp v201, v231, v39 row_newbcast:9 row_mask:0xf bank_mask:0xf
	v_fmac_f32_dpp v135, v228, v40 row_newbcast:10 row_mask:0xf bank_mask:0xf
	v_fmac_f32_dpp v201, v229, v41 row_newbcast:10 row_mask:0xf bank_mask:0xf
	v_fmac_f32_dpp v135, v230, v42 row_newbcast:10 row_mask:0xf bank_mask:0xf
	v_fmac_f32_dpp v201, v231, v43 row_newbcast:10 row_mask:0xf bank_mask:0xf
	v_fmac_f32_dpp v135, v228, v44 row_newbcast:11 row_mask:0xf bank_mask:0xf
	v_fmac_f32_dpp v201, v229, v45 row_newbcast:11 row_mask:0xf bank_mask:0xf
	v_fmac_f32_dpp v135, v230, v46 row_newbcast:11 row_mask:0xf bank_mask:0xf
	v_fmac_f32_dpp v201, v231, v47 row_newbcast:11 row_mask:0xf bank_mask:0xf
	v_fmac_f32_dpp v135, v228, v48 row_newbcast:12 row_mask:0xf bank_mask:0xf
	v_fmac_f32_dpp v201, v229, v49 row_newbcast:12 row_mask:0xf bank_mask:0xf
	v_fmac_f32_dpp v135, v230, v50 row_newbcast:12 row_mask:0xf bank_mask:0xf
	v_fmac_f32_dpp v201, v231, v51 row_newbcast:12 row_mask:0xf bank_mask:0xf
	v_fmac_f32_dpp v135, v228, v52 row_newbcast:13 row_mask:0xf bank_mask:0xf
	v_fmac_f32_dpp v201, v229, v53 row_newbcast:13 row_mask:0xf bank_mask:0xf
	v_fmac_f32_dpp v135, v230, v54 row_newbcast:13 row_mask:0xf bank_mask:0xf
	v_fmac_f32_dpp v201, v231, v55 row_newbcast:13 row_mask:0xf bank_mask:0xf
	v_fmac_f32_dpp v135, v228, v56 row_newbcast:14 row_mask:0xf bank_mask:0xf
	v_fmac_f32_dpp v201, v229, v57 row_newbcast:14 row_mask:0xf bank_mask:0xf
	v_fmac_f32_dpp v135, v230, v58 row_newbcast:14 row_mask:0xf bank_mask:0xf
	v_fmac_f32_dpp v201, v231, v59 row_newbcast:14 row_mask:0xf bank_mask:0xf
	v_fmac_f32_dpp v135, v228, v60 row_newbcast:15 row_mask:0xf bank_mask:0xf
	v_fmac_f32_dpp v201, v229, v61 row_newbcast:15 row_mask:0xf bank_mask:0xf
	v_fmac_f32_dpp v135, v230, v62 row_newbcast:15 row_mask:0xf bank_mask:0xf
	v_fmac_f32_dpp v201, v231, v63 row_newbcast:15 row_mask:0xf bank_mask:0xf
	v_add_f32_e32 v200, v135, v201
	s_waitcnt vmcnt(14)
; #define SB __builtin_amdgcn_sched_barrier(0)
; #define ST2(set, s) { DERIVE_BK(set); float sd[4]; ScanK<0>::dot(S, set.a, sd); float y0 = set.yo, y1 = 0.f; ScanK<0>::upd(S, set, -((sd[0] + sd[1]) + (sd[2] + sd[3])), __uint_as_float(set.v << 16), y0, y1); __builtin_amdgcn_raw_buffer_store_b32(__float_as_uint(y0 + y1), rY, lo4b, ob4 + (unsigned)((int)(s) * (int)stp * 4), 0); }
;     static __device__ __forceinline__ void dot(const float (&S)[64], const f32x4& a, float (&s)[4]) {
;         if constexpr (K == 0) {
;             asm volatile("v_mul_f32_dpp %0, %4, %8 row_newbcast:%16" DPPM "v_mul_f32_dpp %1, %5, %9 row_newbcast:%16" DPPM "v_mul_f32_dpp %2, %6, %10 row_newbcast:%16" DPPM "v_mul_f32_dpp %3, %7, %11 row_newbcast:%16" DPPM
;                          "v_fmac_f32_dpp %0, %4, %12 row_newbcast:%17" DPPM "v_fmac_f32_dpp %1, %5, %13 row_newbcast:%17" DPPM "v_fmac_f32_dpp %2, %6, %14 row_newbcast:%17" DPPM "v_fmac_f32_dpp %3, %7, %15 row_newbcast:%17" DPPM
;                          : "=&v"(s[0]), "=&v"(s[1]), "=&v"(s[2]), "=&v"(s[3])
;                          : "v"(a[0]), "v"(a[1]), "v"(a[2]), "v"(a[3]), "v"(S[K]), "v"(S[K + 1]), "v"(S[K + 2]), "v"(S[K + 3]), "v"(S[K + 4]), "v"(S[K + 5]), "v"(S[K + 6]), "v"(S[K + 7]), "n"(N0), "n"(N1));
;         } else
;         asm volatile("v_fmac_f32_dpp %0, %4, %8 row_newbcast:%16" DPPM "v_fmac_f32_dpp %1, %5, %9 row_newbcast:%16" DPPM "v_fmac_f32_dpp %2, %6, %10 row_newbcast:%16" DPPM "v_fmac_f32_dpp %3, %7, %11 row_newbcast:%16" DPPM
;                      "v_fmac_f32_dpp %0, %4, %12 row_newbcast:%17" DPPM "v_fmac_f32_dpp %1, %5, %13 row_newbcast:%17" DPPM "v_fmac_f32_dpp %2, %6, %14 row_newbcast:%17" DPPM "v_fmac_f32_dpp %3, %7, %15 row_newbcast:%17" DPPM
;                      : "+v"(s[0]), "+v"(s[1]), "+v"(s[2]), "+v"(s[3])
;                      : "v"(a[0]), "v"(a[1]), "v"(a[2]), "v"(a[3]), "v"(S[K]), "v"(S[K + 1]), "v"(S[K + 2]), "v"(S[K + 3]), "v"(S[K + 4]), "v"(S[K + 5]), "v"(S[K + 6]), "v"(S[K + 7]), "n"(N0), "n"(N1));
;         if constexpr (K + 8 < 64) ScanK<K + 8>::dot(S, a, s);
;     }
; __device__ __forceinline__ void scan_pass2(const Params& p, int d) {
;     ...
;         In2 i0, i1; LD2(i0, 0);
; #pragma unroll 1
;         for (int s = 0; s < LC; s += 2) { TOUCH2(i0); SB; LD2(i1, s + 1); SB; ST2(i0, s); TOUCH2(i1); SB; LD2(i0, s + 2); SB; ST2(i1, s + 1); }
	buffer_store_dword v200, v207, s[68:71], s79 offen
	s_add_u32 s79, s79, 0xfffff000
	buffer_load_dwordx4 v[116:119], v204, s[64:67], s72 offen
	buffer_load_dwordx4 v[120:123], v204, s[64:67], s73 offen
	buffer_load_dwordx4 v[124:127], v204, s[64:67], s74 offen
	buffer_load_dwordx4 v[128:131], v204, s[64:67], s75 offen
	buffer_load_dwordx2 v[132:133], v205, s[64:67], s76 offen
	buffer_load_ushort v134, v206, s[64:67], s77 offen
	buffer_load_dword v135, v207, s[68:71], s78 offen
	s_cmp_lt_u32 s80, 255
	s_cselect_b32 s81, 0xfffff000, 0
	s_cselect_b32 s82, 0xfffff800, 0
	s_cselect_b32 s9, 1, 0
	s_add_u32 s80, s80, s9
	s_add_u32 s72, s72, s81
	s_add_u32 s73, s73, s81
	s_add_u32 s74, s74, s81
	s_add_u32 s75, s75, s81
	s_add_u32 s78, s78, s81
	s_add_u32 s76, s76, s82
	s_add_u32 s77, s77, s82
	v_pk_mul_f32 v[224:225], v[140:141], v[216:217]
	v_pk_mul_f32 v[226:227], v[142:143], v[218:219]
	v_pk_mul_f32 v[216:217], v[216:217], v[136:137]
	v_pk_mul_f32 v[218:219], v[218:219], v[138:139]
	v_pk_fma_f32 v[184:185], v[144:145], v[188:189], v[192:193]
	v_pk_fma_f32 v[186:187], v[146:147], v[190:191], v[194:195]
	v_pk_mul_f32 v[176:177], v[140:141], v[144:145]
	v_pk_mul_f32 v[178:179], v[142:143], v[146:147]
	v_rcp_f32_e32 v220, v216
	v_rcp_f32_e32 v221, v217
	v_rcp_f32_e32 v222, v218
	v_rcp_f32_e32 v223, v219
	v_lshlrev_b32_e32 v180, 16, v152
	v_and_b32_e32 v181, 0xffff0000, v152
	v_lshlrev_b32_e32 v182, 16, v153
	v_and_b32_e32 v183, 0xffff0000, v153
	v_pk_mul_f32 v[180:181], v[180:181], v[184:185]
	v_pk_mul_f32 v[182:183], v[182:183], v[186:187]
	v_pk_mul_f32 v[228:229], v[148:149], v[216:217]
	v_pk_mul_f32 v[230:231], v[150:151], v[218:219]
	v_pk_mul_f32 v[176:177], v[176:177], v[220:221]
	v_pk_mul_f32 v[178:179], v[178:179], v[222:223]
	v_pk_mul_f32 v[180:181], v[180:181], v[220:221]
	v_pk_mul_f32 v[182:183], v[182:183], v[222:223]
	v_lshlrev_b32_e32 v203, 16, v154
	ds_write_b128 v208, v[176:179]
	ds_write_b128 v208, v[180:183] offset:256
	ds_read2_b32 v[64:65], v209 offset0:0 offset1:4
	ds_read2_b32 v[66:67], v209 offset0:8 offset1:12
	ds_read2_b32 v[68:69], v209 offset0:16 offset1:20
	ds_read2_b32 v[70:71], v209 offset0:24 offset1:28
	ds_read2_b32 v[72:73], v209 offset0:32 offset1:36
	ds_read2_b32 v[74:75], v209 offset0:40 offset1:44
	ds_read2_b32 v[76:77], v209 offset0:48 offset1:52
	ds_read2_b32 v[78:79], v209 offset0:56 offset1:60
	ds_read2_b32 v[80:81], v209 offset0:64 offset1:68
	ds_read2_b32 v[82:83], v209 offset0:72 offset1:76
	ds_read2_b32 v[84:85], v209 offset0:80 offset1:84
	ds_read2_b32 v[86:87], v209 offset0:88 offset1:92
	ds_read2_b32 v[88:89], v209 offset0:96 offset1:100
	ds_read2_b32 v[90:91], v209 offset0:104 offset1:108
	ds_read2_b32 v[92:93], v209 offset0:112 offset1:116
	ds_read2_b32 v[94:95], v209 offset0:120 offset1:124
	v_mul_f32_dpp v196, v224, v0 row_newbcast:0 row_mask:0xf bank_mask:0xf
	v_mul_f32_dpp v197, v225, v1 row_newbcast:0 row_mask:0xf bank_mask:0xf
	v_mul_f32_dpp v198, v226, v2 row_newbcast:0 row_mask:0xf bank_mask:0xf
	v_mul_f32_dpp v199, v227, v3 row_newbcast:0 row_mask:0xf bank_mask:0xf
	v_fmac_f32_dpp v196, v224, v4 row_newbcast:1 row_mask:0xf bank_mask:0xf
	v_fmac_f32_dpp v197, v225, v5 row_newbcast:1 row_mask:0xf bank_mask:0xf
	v_fmac_f32_dpp v198, v226, v6 row_newbcast:1 row_mask:0xf bank_mask:0xf
	v_fmac_f32_dpp v199, v227, v7 row_newbcast:1 row_mask:0xf bank_mask:0xf
	v_fmac_f32_dpp v196, v224, v8 row_newbcast:2 row_mask:0xf bank_mask:0xf
	v_fmac_f32_dpp v197, v225, v9 row_newbcast:2 row_mask:0xf bank_mask:0xf
	v_fmac_f32_dpp v198, v226, v10 row_newbcast:2 row_mask:0xf bank_mask:0xf
	v_fmac_f32_dpp v199, v227, v11 row_newbcast:2 row_mask:0xf bank_mask:0xf
	v_fmac_f32_dpp v196, v224, v12 row_newbcast:3 row_mask:0xf bank_mask:0xf
	v_fmac_f32_dpp v197, v225, v13 row_newbcast:3 row_mask:0xf bank_mask:0xf
	v_fmac_f32_dpp v198, v226, v14 row_newbcast:3 row_mask:0xf bank_mask:0xf
	v_fmac_f32_dpp v199, v227, v15 row_newbcast:3 row_mask:0xf bank_mask:0xf
	v_fmac_f32_dpp v196, v224, v16 row_newbcast:4 row_mask:0xf bank_mask:0xf
	v_fmac_f32_dpp v197, v225, v17 row_newbcast:4 row_mask:0xf bank_mask:0xf
	v_fmac_f32_dpp v198, v226, v18 row_newbcast:4 row_mask:0xf bank_mask:0xf
	v_fmac_f32_dpp v199, v227, v19 row_newbcast:4 row_mask:0xf bank_mask:0xf
	v_fmac_f32_dpp v196, v224, v20 row_newbcast:5 row_mask:0xf bank_mask:0xf
	v_fmac_f32_dpp v197, v225, v21 row_newbcast:5 row_mask:0xf bank_mask:0xf
	v_fmac_f32_dpp v198, v226, v22 row_newbcast:5 row_mask:0xf bank_mask:0xf
	v_fmac_f32_dpp v199, v227, v23 row_newbcast:5 row_mask:0xf bank_mask:0xf
	v_fmac_f32_dpp v196, v224, v24 row_newbcast:6 row_mask:0xf bank_mask:0xf
	v_fmac_f32_dpp v197, v225, v25 row_newbcast:6 row_mask:0xf bank_mask:0xf
	v_fmac_f32_dpp v198, v226, v26 row_newbcast:6 row_mask:0xf bank_mask:0xf
	v_fmac_f32_dpp v199, v227, v27 row_newbcast:6 row_mask:0xf bank_mask:0xf
	v_fmac_f32_dpp v196, v224, v28 row_newbcast:7 row_mask:0xf bank_mask:0xf
	v_fmac_f32_dpp v197, v225, v29 row_newbcast:7 row_mask:0xf bank_mask:0xf
	v_fmac_f32_dpp v198, v226, v30 row_newbcast:7 row_mask:0xf bank_mask:0xf
	v_fmac_f32_dpp v199, v227, v31 row_newbcast:7 row_mask:0xf bank_mask:0xf
	v_fmac_f32_dpp v196, v224, v32 row_newbcast:8 row_mask:0xf bank_mask:0xf
	v_fmac_f32_dpp v197, v225, v33 row_newbcast:8 row_mask:0xf bank_mask:0xf
	v_fmac_f32_dpp v198, v226, v34 row_newbcast:8 row_mask:0xf bank_mask:0xf
	v_fmac_f32_dpp v199, v227, v35 row_newbcast:8 row_mask:0xf bank_mask:0xf
	v_fmac_f32_dpp v196, v224, v36 row_newbcast:9 row_mask:0xf bank_mask:0xf
	v_fmac_f32_dpp v197, v225, v37 row_newbcast:9 row_mask:0xf bank_mask:0xf
	v_fmac_f32_dpp v198, v226, v38 row_newbcast:9 row_mask:0xf bank_mask:0xf
;     static __device__ __forceinline__ void dot(const float (&S)[64], const f32x4& a, float (&s)[4]) {
;         if constexpr (K == 0) {
;             asm volatile("v_mul_f32_dpp %0, %4, %8 row_newbcast:%16" DPPM "v_mul_f32_dpp %1, %5, %9 row_newbcast:%16" DPPM "v_mul_f32_dpp %2, %6, %10 row_newbcast:%16" DPPM "v_mul_f32_dpp %3, %7, %11 row_newbcast:%16" DPPM
;                          "v_fmac_f32_dpp %0, %4, %12 row_newbcast:%17" DPPM "v_fmac_f32_dpp %1, %5, %13 row_newbcast:%17" DPPM "v_fmac_f32_dpp %2, %6, %14 row_newbcast:%17" DPPM "v_fmac_f32_dpp %3, %7, %15 row_newbcast:%17" DPPM
;                          : "=&v"(s[0]), "=&v"(s[1]), "=&v"(s[2]), "=&v"(s[3])
;                          : "v"(a[0]), "v"(a[1]), "v"(a[2]), "v"(a[3]), "v"(S[K]), "v"(S[K + 1]), "v"(S[K + 2]), "v"(S[K + 3]), "v"(S[K + 4]), "v"(S[K + 5]), "v"(S[K + 6]), "v"(S[K + 7]), "n"(N0), "n"(N1));
;         } else
;         asm volatile("v_fmac_f32_dpp %0, %4, %8 row_newbcast:%16" DPPM "v_fmac_f32_dpp %1, %5, %9 row_newbcast:%16" DPPM "v_fmac_f32_dpp %2, %6, %10 row_newbcast:%16" DPPM "v_fmac_f32_dpp %3, %7, %11 row_newbcast:%16" DPPM
;                      "v_fmac_f32_dpp %0, %4, %12 row_newbcast:%17" DPPM "v_fmac_f32_dpp %1, %5, %13 row_newbcast:%17" DPPM "v_fmac_f32_dpp %2, %6, %14 row_newbcast:%17" DPPM "v_fmac_f32_dpp %3, %7, %15 row_newbcast:%17" DPPM
;                      : "+v"(s[0]), "+v"(s[1]), "+v"(s[2]), "+v"(s[3])
;                      : "v"(a[0]), "v"(a[1]), "v"(a[2]), "v"(a[3]), "v"(S[K]), "v"(S[K + 1]), "v"(S[K + 2]), "v"(S[K + 3]), "v"(S[K + 4]), "v"(S[K + 5]), "v"(S[K + 6]), "v"(S[K + 7]), "n"(N0), "n"(N1));
;         if constexpr (K + 8 < 64) ScanK<K + 8>::dot(S, a, s);
;     }
;     static __device__ __forceinline__ void upd(float (&S)[64], const In2& in, float sa, float vv, float& y0, float& y1) {
;         float t0, t1, t2, t3;
;         asm volatile("v_mul_f32_dpp %0, %10, %27 row_newbcast:%28" DPPM "v_mul_f32_dpp %1, %11, %27 row_newbcast:%28" DPPM "v_mul_f32_dpp %2, %12, %27 row_newbcast:%28" DPPM "v_mul_f32_dpp %3, %13, %27 row_newbcast:%28" DPPM
;                      "v_fmac_f32_dpp %0, %14, %6 row_newbcast:%28" DPPM "v_fmac_f32_dpp %1, %15, %7 row_newbcast:%28" DPPM "v_fmac_f32_dpp %2, %16, %8 row_newbcast:%28" DPPM "v_fmac_f32_dpp %3, %17, %9 row_newbcast:%28" DPPM
	v_fmac_f32_dpp v199, v227, v39 row_newbcast:9 row_mask:0xf bank_mask:0xf
	v_fmac_f32_dpp v196, v224, v40 row_newbcast:10 row_mask:0xf bank_mask:0xf
	v_fmac_f32_dpp v197, v225, v41 row_newbcast:10 row_mask:0xf bank_mask:0xf
	v_fmac_f32_dpp v198, v226, v42 row_newbcast:10 row_mask:0xf bank_mask:0xf
	v_fmac_f32_dpp v199, v227, v43 row_newbcast:10 row_mask:0xf bank_mask:0xf
	v_fmac_f32_dpp v196, v224, v44 row_newbcast:11 row_mask:0xf bank_mask:0xf
	v_fmac_f32_dpp v197, v225, v45 row_newbcast:11 row_mask:0xf bank_mask:0xf
	v_fmac_f32_dpp v198, v226, v46 row_newbcast:11 row_mask:0xf bank_mask:0xf
	v_fmac_f32_dpp v199, v227, v47 row_newbcast:11 row_mask:0xf bank_mask:0xf
	v_fmac_f32_dpp v196, v224, v48 row_newbcast:12 row_mask:0xf bank_mask:0xf
	v_fmac_f32_dpp v197, v225, v49 row_newbcast:12 row_mask:0xf bank_mask:0xf
	v_fmac_f32_dpp v198, v226, v50 row_newbcast:12 row_mask:0xf bank_mask:0xf
	v_fmac_f32_dpp v199, v227, v51 row_newbcast:12 row_mask:0xf bank_mask:0xf
	v_fmac_f32_dpp v196, v224, v52 row_newbcast:13 row_mask:0xf bank_mask:0xf
	v_fmac_f32_dpp v197, v225, v53 row_newbcast:13 row_mask:0xf bank_mask:0xf
	v_fmac_f32_dpp v198, v226, v54 row_newbcast:13 row_mask:0xf bank_mask:0xf
	v_fmac_f32_dpp v199, v227, v55 row_newbcast:13 row_mask:0xf bank_mask:0xf
	v_fmac_f32_dpp v196, v224, v56 row_newbcast:14 row_mask:0xf bank_mask:0xf
	v_fmac_f32_dpp v197, v225, v57 row_newbcast:14 row_mask:0xf bank_mask:0xf
	v_fmac_f32_dpp v198, v226, v58 row_newbcast:14 row_mask:0xf bank_mask:0xf
	v_fmac_f32_dpp v199, v227, v59 row_newbcast:14 row_mask:0xf bank_mask:0xf
	v_fmac_f32_dpp v196, v224, v60 row_newbcast:15 row_mask:0xf bank_mask:0xf
	v_fmac_f32_dpp v197, v225, v61 row_newbcast:15 row_mask:0xf bank_mask:0xf
	v_fmac_f32_dpp v198, v226, v62 row_newbcast:15 row_mask:0xf bank_mask:0xf
	v_fmac_f32_dpp v199, v227, v63 row_newbcast:15 row_mask:0xf bank_mask:0xf
	v_add_f32_e32 v196, v196, v197
	v_add_f32_e32 v198, v198, v199
	v_add_f32_e32 v196, v196, v198
	v_xor_b32_e32 v202, 0x80000000, v196
	s_waitcnt lgkmcnt(0)
	s_nop 1
	v_mfma_f32_4x4x1_16b_f32 v[0:3], v64, v202, v[0:3]
	v_mfma_f32_4x4x1_16b_f32 v[4:7], v65, v202, v[4:7]
	v_mfma_f32_4x4x1_16b_f32 v[8:11], v66, v202, v[8:11]
	v_mfma_f32_4x4x1_16b_f32 v[12:15], v67, v202, v[12:15]
	v_mfma_f32_4x4x1_16b_f32 v[16:19], v68, v202, v[16:19]
	v_mfma_f32_4x4x1_16b_f32 v[20:23], v69, v202, v[20:23]
	v_mfma_f32_4x4x1_16b_f32 v[24:27], v70, v202, v[24:27]
	v_mfma_f32_4x4x1_16b_f32 v[28:31], v71, v202, v[28:31]
	v_mfma_f32_4x4x1_16b_f32 v[32:35], v72, v202, v[32:35]
	v_mfma_f32_4x4x1_16b_f32 v[36:39], v73, v202, v[36:39]
	v_mfma_f32_4x4x1_16b_f32 v[40:43], v74, v202, v[40:43]
	v_mfma_f32_4x4x1_16b_f32 v[44:47], v75, v202, v[44:47]
	v_mfma_f32_4x4x1_16b_f32 v[48:51], v76, v202, v[48:51]
	v_mfma_f32_4x4x1_16b_f32 v[52:55], v77, v202, v[52:55]
	v_mfma_f32_4x4x1_16b_f32 v[56:59], v78, v202, v[56:59]
	v_mfma_f32_4x4x1_16b_f32 v[60:63], v79, v202, v[60:63]
	v_mfma_f32_4x4x1_16b_f32 v[0:3], v80, v203, v[0:3]
	v_mfma_f32_4x4x1_16b_f32 v[4:7], v81, v203, v[4:7]
	v_mfma_f32_4x4x1_16b_f32 v[8:11], v82, v203, v[8:11]
	v_mfma_f32_4x4x1_16b_f32 v[12:15], v83, v203, v[12:15]
	v_mfma_f32_4x4x1_16b_f32 v[16:19], v84, v203, v[16:19]
	v_mfma_f32_4x4x1_16b_f32 v[20:23], v85, v203, v[20:23]
	v_mfma_f32_4x4x1_16b_f32 v[24:27], v86, v203, v[24:27]
	v_mfma_f32_4x4x1_16b_f32 v[28:31], v87, v203, v[28:31]
	v_mfma_f32_4x4x1_16b_f32 v[32:35], v88, v203, v[32:35]
	v_mfma_f32_4x4x1_16b_f32 v[36:39], v89, v203, v[36:39]
	v_mfma_f32_4x4x1_16b_f32 v[40:43], v90, v203, v[40:43]
	v_mfma_f32_4x4x1_16b_f32 v[44:47], v91, v203, v[44:47]
	v_mfma_f32_4x4x1_16b_f32 v[48:51], v92, v203, v[48:51]
	v_mfma_f32_4x4x1_16b_f32 v[52:55], v93, v203, v[52:55]
	v_mfma_f32_4x4x1_16b_f32 v[56:59], v94, v203, v[56:59]
	v_mfma_f32_4x4x1_16b_f32 v[60:63], v95, v203, v[60:63]
	v_fmac_f32_dpp v155, v228, v0 row_newbcast:0 row_mask:0xf bank_mask:0xf
	v_mul_f32_dpp v201, v229, v1 row_newbcast:0 row_mask:0xf bank_mask:0xf
	v_fmac_f32_dpp v155, v230, v2 row_newbcast:0 row_mask:0xf bank_mask:0xf
	v_fmac_f32_dpp v201, v231, v3 row_newbcast:0 row_mask:0xf bank_mask:0xf
	v_fmac_f32_dpp v155, v228, v4 row_newbcast:1 row_mask:0xf bank_mask:0xf
	v_fmac_f32_dpp v201, v229, v5 row_newbcast:1 row_mask:0xf bank_mask:0xf
	v_fmac_f32_dpp v155, v230, v6 row_newbcast:1 row_mask:0xf bank_mask:0xf
	v_fmac_f32_dpp v201, v231, v7 row_newbcast:1 row_mask:0xf bank_mask:0xf
	v_fmac_f32_dpp v155, v228, v8 row_newbcast:2 row_mask:0xf bank_mask:0xf
	v_fmac_f32_dpp v201, v229, v9 row_newbcast:2 row_mask:0xf bank_mask:0xf
	v_fmac_f32_dpp v155, v230, v10 row_newbcast:2 row_mask:0xf bank_mask:0xf
	v_fmac_f32_dpp v201, v231, v11 row_newbcast:2 row_mask:0xf bank_mask:0xf
	v_fmac_f32_dpp v155, v228, v12 row_newbcast:3 row_mask:0xf bank_mask:0xf
	v_fmac_f32_dpp v201, v229, v13 row_newbcast:3 row_mask:0xf bank_mask:0xf
	v_fmac_f32_dpp v155, v230, v14 row_newbcast:3 row_mask:0xf bank_mask:0xf
	v_fmac_f32_dpp v201, v231, v15 row_newbcast:3 row_mask:0xf bank_mask:0xf
	v_fmac_f32_dpp v155, v228, v16 row_newbcast:4 row_mask:0xf bank_mask:0xf
	v_fmac_f32_dpp v201, v229, v17 row_newbcast:4 row_mask:0xf bank_mask:0xf
	v_fmac_f32_dpp v155, v230, v18 row_newbcast:4 row_mask:0xf bank_mask:0xf
	v_fmac_f32_dpp v201, v231, v19 row_newbcast:4 row_mask:0xf bank_mask:0xf
	v_fmac_f32_dpp v155, v228, v20 row_newbcast:5 row_mask:0xf bank_mask:0xf
	v_fmac_f32_dpp v201, v229, v21 row_newbcast:5 row_mask:0xf bank_mask:0xf
	v_fmac_f32_dpp v155, v230, v22 row_newbcast:5 row_mask:0xf bank_mask:0xf
	v_fmac_f32_dpp v201, v231, v23 row_newbcast:5 row_mask:0xf bank_mask:0xf
	v_fmac_f32_dpp v155, v228, v24 row_newbcast:6 row_mask:0xf bank_mask:0xf
; #define SB __builtin_amdgcn_sched_barrier(0)
; #define ST2(set, s) { DERIVE_BK(set); float sd[4]; ScanK<0>::dot(S, set.a, sd); float y0 = set.yo, y1 = 0.f; ScanK<0>::upd(S, set, -((sd[0] + sd[1]) + (sd[2] + sd[3])), __uint_as_float(set.v << 16), y0, y1); __builtin_amdgcn_raw_buffer_store_b32(__float_as_uint(y0 + y1), rY, lo4b, ob4 + (unsigned)((int)(s) * (int)stp * 4), 0); }
; #define TOUCH2(set) asm volatile("" :: "v"(set.w), "v"(set.a), "v"(set.b), "v"(set.kw), "v"(set.r), "v"(set.v), "v"(set.yo))
; __device__ __forceinline__ void scan_pass2(const Params& p, int d) {
;     ...
;         In2 i0, i1; LD2(i0, 0);
; #pragma unroll 1
;         for (int s = 0; s < LC; s += 2) { TOUCH2(i0); SB; LD2(i1, s + 1); SB; ST2(i0, s); TOUCH2(i1); SB; LD2(i0, s + 2); SB; ST2(i1, s + 1); }
	v_fmac_f32_dpp v201, v229, v25 row_newbcast:6 row_mask:0xf bank_mask:0xf
	v_fmac_f32_dpp v155, v230, v26 row_newbcast:6 row_mask:0xf bank_mask:0xf
	v_fmac_f32_dpp v201, v231, v27 row_newbcast:6 row_mask:0xf bank_mask:0xf
	v_fmac_f32_dpp v155, v228, v28 row_newbcast:7 row_mask:0xf bank_mask:0xf
	v_fmac_f32_dpp v201, v229, v29 row_newbcast:7 row_mask:0xf bank_mask:0xf
	v_fmac_f32_dpp v155, v230, v30 row_newbcast:7 row_mask:0xf bank_mask:0xf
	v_fmac_f32_dpp v201, v231, v31 row_newbcast:7 row_mask:0xf bank_mask:0xf
	v_fmac_f32_dpp v155, v228, v32 row_newbcast:8 row_mask:0xf bank_mask:0xf
	v_fmac_f32_dpp v201, v229, v33 row_newbcast:8 row_mask:0xf bank_mask:0xf
	v_fmac_f32_dpp v155, v230, v34 row_newbcast:8 row_mask:0xf bank_mask:0xf
	v_fmac_f32_dpp v201, v231, v35 row_newbcast:8 row_mask:0xf bank_mask:0xf
	v_fmac_f32_dpp v155, v228, v36 row_newbcast:9 row_mask:0xf bank_mask:0xf
	v_fmac_f32_dpp v201, v229, v37 row_newbcast:9 row_mask:0xf bank_mask:0xf
	v_fmac_f32_dpp v155, v230, v38 row_newbcast:9 row_mask:0xf bank_mask:0xf
	v_fmac_f32_dpp v201, v231, v39 row_newbcast:9 row_mask:0xf bank_mask:0xf
	v_fmac_f32_dpp v155, v228, v40 row_newbcast:10 row_mask:0xf bank_mask:0xf
	v_fmac_f32_dpp v201, v229, v41 row_newbcast:10 row_mask:0xf bank_mask:0xf
	v_fmac_f32_dpp v155, v230, v42 row_newbcast:10 row_mask:0xf bank_mask:0xf
	v_fmac_f32_dpp v201, v231, v43 row_newbcast:10 row_mask:0xf bank_mask:0xf
	v_fmac_f32_dpp v155, v228, v44 row_newbcast:11 row_mask:0xf bank_mask:0xf
	v_fmac_f32_dpp v201, v229, v45 row_newbcast:11 row_mask:0xf bank_mask:0xf
	v_fmac_f32_dpp v155, v230, v46 row_newbcast:11 row_mask:0xf bank_mask:0xf
	v_fmac_f32_dpp v201, v231, v47 row_newbcast:11 row_mask:0xf bank_mask:0xf
	v_fmac_f32_dpp v155, v228, v48 row_newbcast:12 row_mask:0xf bank_mask:0xf
	v_fmac_f32_dpp v201, v229, v49 row_newbcast:12 row_mask:0xf bank_mask:0xf
	v_fmac_f32_dpp v155, v230, v50 row_newbcast:12 row_mask:0xf bank_mask:0xf
	v_fmac_f32_dpp v201, v231, v51 row_newbcast:12 row_mask:0xf bank_mask:0xf
	v_fmac_f32_dpp v155, v228, v52 row_newbcast:13 row_mask:0xf bank_mask:0xf
	v_fmac_f32_dpp v201, v229, v53 row_newbcast:13 row_mask:0xf bank_mask:0xf
	v_fmac_f32_dpp v155, v230, v54 row_newbcast:13 row_mask:0xf bank_mask:0xf
	v_fmac_f32_dpp v201, v231, v55 row_newbcast:13 row_mask:0xf bank_mask:0xf
	v_fmac_f32_dpp v155, v228, v56 row_newbcast:14 row_mask:0xf bank_mask:0xf
	v_fmac_f32_dpp v201, v229, v57 row_newbcast:14 row_mask:0xf bank_mask:0xf
	v_fmac_f32_dpp v155, v230, v58 row_newbcast:14 row_mask:0xf bank_mask:0xf
	v_fmac_f32_dpp v201, v231, v59 row_newbcast:14 row_mask:0xf bank_mask:0xf
	v_fmac_f32_dpp v155, v228, v60 row_newbcast:15 row_mask:0xf bank_mask:0xf
	v_fmac_f32_dpp v201, v229, v61 row_newbcast:15 row_mask:0xf bank_mask:0xf
	v_fmac_f32_dpp v155, v230, v62 row_newbcast:15 row_mask:0xf bank_mask:0xf
	v_fmac_f32_dpp v201, v231, v63 row_newbcast:15 row_mask:0xf bank_mask:0xf
	v_add_f32_e32 v200, v155, v201
	s_waitcnt vmcnt(14)
	buffer_store_dword v200, v207, s[68:71], s79 offen
	s_add_u32 s79, s79, 0xfffff000
	buffer_load_dwordx4 v[136:139], v204, s[64:67], s72 offen
	buffer_load_dwordx4 v[140:143], v204, s[64:67], s73 offen
	buffer_load_dwordx4 v[144:147], v204, s[64:67], s74 offen
	buffer_load_dwordx4 v[148:151], v204, s[64:67], s75 offen
	buffer_load_dwordx2 v[152:153], v205, s[64:67], s76 offen
	buffer_load_ushort v154, v206, s[64:67], s77 offen
	buffer_load_dword v155, v207, s[68:71], s78 offen
	s_cmp_lt_u32 s80, 255
	s_cselect_b32 s81, 0xfffff000, 0
	s_cselect_b32 s82, 0xfffff800, 0
	s_cselect_b32 s9, 1, 0
	s_add_u32 s80, s80, s9
	s_add_u32 s72, s72, s81
	s_add_u32 s73, s73, s81
	s_add_u32 s74, s74, s81
	s_add_u32 s75, s75, s81
	s_add_u32 s78, s78, s81
	s_add_u32 s76, s76, s82
	s_add_u32 s77, s77, s82
	v_pk_mul_f32 v[224:225], v[160:161], v[216:217]
	v_pk_mul_f32 v[226:227], v[162:163], v[218:219]
	v_pk_mul_f32 v[216:217], v[216:217], v[156:157]
	v_pk_mul_f32 v[218:219], v[218:219], v[158:159]
	v_pk_fma_f32 v[184:185], v[164:165], v[188:189], v[192:193]
	v_pk_fma_f32 v[186:187], v[166:167], v[190:191], v[194:195]
	v_pk_mul_f32 v[176:177], v[160:161], v[164:165]
	v_pk_mul_f32 v[178:179], v[162:163], v[166:167]
	v_rcp_f32_e32 v220, v216
	v_rcp_f32_e32 v221, v217
	v_rcp_f32_e32 v222, v218
	v_rcp_f32_e32 v223, v219
	v_lshlrev_b32_e32 v180, 16, v172
	v_and_b32_e32 v181, 0xffff0000, v172
	v_lshlrev_b32_e32 v182, 16, v173
	v_and_b32_e32 v183, 0xffff0000, v173
	v_pk_mul_f32 v[180:181], v[180:181], v[184:185]
	v_pk_mul_f32 v[182:183], v[182:183], v[186:187]
	v_pk_mul_f32 v[228:229], v[168:169], v[216:217]
	v_pk_mul_f32 v[230:231], v[170:171], v[218:219]
	v_pk_mul_f32 v[176:177], v[176:177], v[220:221]
	v_pk_mul_f32 v[178:179], v[178:179], v[222:223]
	v_pk_mul_f32 v[180:181], v[180:181], v[220:221]
	v_pk_mul_f32 v[182:183], v[182:183], v[222:223]
	v_lshlrev_b32_e32 v203, 16, v174
	ds_write_b128 v208, v[176:179]
	ds_write_b128 v208, v[180:183] offset:256
	ds_read2_b32 v[64:65], v209 offset0:0 offset1:4
	ds_read2_b32 v[66:67], v209 offset0:8 offset1:12
	ds_read2_b32 v[68:69], v209 offset0:16 offset1:20
	ds_read2_b32 v[70:71], v209 offset0:24 offset1:28
	ds_read2_b32 v[72:73], v209 offset0:32 offset1:36
	ds_read2_b32 v[74:75], v209 offset0:40 offset1:44
	ds_read2_b32 v[76:77], v209 offset0:48 offset1:52
	ds_read2_b32 v[78:79], v209 offset0:56 offset1:60
	ds_read2_b32 v[80:81], v209 offset0:64 offset1:68
	ds_read2_b32 v[82:83], v209 offset0:72 offset1:76
	ds_read2_b32 v[84:85], v209 offset0:80 offset1:84
	ds_read2_b32 v[86:87], v209 offset0:88 offset1:92
	ds_read2_b32 v[88:89], v209 offset0:96 offset1:100
	ds_read2_b32 v[90:91], v209 offset0:104 offset1:108
;     static __device__ __forceinline__ void dot(const float (&S)[64], const f32x4& a, float (&s)[4]) {
;         if constexpr (K == 0) {
;             asm volatile("v_mul_f32_dpp %0, %4, %8 row_newbcast:%16" DPPM "v_mul_f32_dpp %1, %5, %9 row_newbcast:%16" DPPM "v_mul_f32_dpp %2, %6, %10 row_newbcast:%16" DPPM "v_mul_f32_dpp %3, %7, %11 row_newbcast:%16" DPPM
;                          "v_fmac_f32_dpp %0, %4, %12 row_newbcast:%17" DPPM "v_fmac_f32_dpp %1, %5, %13 row_newbcast:%17" DPPM "v_fmac_f32_dpp %2, %6, %14 row_newbcast:%17" DPPM "v_fmac_f32_dpp %3, %7, %15 row_newbcast:%17" DPPM
;                          : "=&v"(s[0]), "=&v"(s[1]), "=&v"(s[2]), "=&v"(s[3])
;                          : "v"(a[0]), "v"(a[1]), "v"(a[2]), "v"(a[3]), "v"(S[K]), "v"(S[K + 1]), "v"(S[K + 2]), "v"(S[K + 3]), "v"(S[K + 4]), "v"(S[K + 5]), "v"(S[K + 6]), "v"(S[K + 7]), "n"(N0), "n"(N1));
;         } else
;         asm volatile("v_fmac_f32_dpp %0, %4, %8 row_newbcast:%16" DPPM "v_fmac_f32_dpp %1, %5, %9 row_newbcast:%16" DPPM "v_fmac_f32_dpp %2, %6, %10 row_newbcast:%16" DPPM "v_fmac_f32_dpp %3, %7, %11 row_newbcast:%16" DPPM
;                      "v_fmac_f32_dpp %0, %4, %12 row_newbcast:%17" DPPM "v_fmac_f32_dpp %1, %5, %13 row_newbcast:%17" DPPM "v_fmac_f32_dpp %2, %6, %14 row_newbcast:%17" DPPM "v_fmac_f32_dpp %3, %7, %15 row_newbcast:%17" DPPM
;                      : "+v"(s[0]), "+v"(s[1]), "+v"(s[2]), "+v"(s[3])
;                      : "v"(a[0]), "v"(a[1]), "v"(a[2]), "v"(a[3]), "v"(S[K]), "v"(S[K + 1]), "v"(S[K + 2]), "v"(S[K + 3]), "v"(S[K + 4]), "v"(S[K + 5]), "v"(S[K + 6]), "v"(S[K + 7]), "n"(N0), "n"(N1));
;         if constexpr (K + 8 < 64) ScanK<K + 8>::dot(S, a, s);
;     }
	ds_read2_b32 v[92:93], v209 offset0:112 offset1:116
	ds_read2_b32 v[94:95], v209 offset0:120 offset1:124
	v_mul_f32_dpp v196, v224, v0 row_newbcast:0 row_mask:0xf bank_mask:0xf
	v_mul_f32_dpp v197, v225, v1 row_newbcast:0 row_mask:0xf bank_mask:0xf
	v_mul_f32_dpp v198, v226, v2 row_newbcast:0 row_mask:0xf bank_mask:0xf
	v_mul_f32_dpp v199, v227, v3 row_newbcast:0 row_mask:0xf bank_mask:0xf
	v_fmac_f32_dpp v196, v224, v4 row_newbcast:1 row_mask:0xf bank_mask:0xf
	v_fmac_f32_dpp v197, v225, v5 row_newbcast:1 row_mask:0xf bank_mask:0xf
	v_fmac_f32_dpp v198, v226, v6 row_newbcast:1 row_mask:0xf bank_mask:0xf
	v_fmac_f32_dpp v199, v227, v7 row_newbcast:1 row_mask:0xf bank_mask:0xf
	v_fmac_f32_dpp v196, v224, v8 row_newbcast:2 row_mask:0xf bank_mask:0xf
	v_fmac_f32_dpp v197, v225, v9 row_newbcast:2 row_mask:0xf bank_mask:0xf
	v_fmac_f32_dpp v198, v226, v10 row_newbcast:2 row_mask:0xf bank_mask:0xf
	v_fmac_f32_dpp v199, v227, v11 row_newbcast:2 row_mask:0xf bank_mask:0xf
	v_fmac_f32_dpp v196, v224, v12 row_newbcast:3 row_mask:0xf bank_mask:0xf
	v_fmac_f32_dpp v197, v225, v13 row_newbcast:3 row_mask:0xf bank_mask:0xf
	v_fmac_f32_dpp v198, v226, v14 row_newbcast:3 row_mask:0xf bank_mask:0xf
	v_fmac_f32_dpp v199, v227, v15 row_newbcast:3 row_mask:0xf bank_mask:0xf
	v_fmac_f32_dpp v196, v224, v16 row_newbcast:4 row_mask:0xf bank_mask:0xf
	v_fmac_f32_dpp v197, v225, v17 row_newbcast:4 row_mask:0xf bank_mask:0xf
	v_fmac_f32_dpp v198, v226, v18 row_newbcast:4 row_mask:0xf bank_mask:0xf
	v_fmac_f32_dpp v199, v227, v19 row_newbcast:4 row_mask:0xf bank_mask:0xf
	v_fmac_f32_dpp v196, v224, v20 row_newbcast:5 row_mask:0xf bank_mask:0xf
	v_fmac_f32_dpp v197, v225, v21 row_newbcast:5 row_mask:0xf bank_mask:0xf
	v_fmac_f32_dpp v198, v226, v22 row_newbcast:5 row_mask:0xf bank_mask:0xf
	v_fmac_f32_dpp v199, v227, v23 row_newbcast:5 row_mask:0xf bank_mask:0xf
	v_fmac_f32_dpp v196, v224, v24 row_newbcast:6 row_mask:0xf bank_mask:0xf
	v_fmac_f32_dpp v197, v225, v25 row_newbcast:6 row_mask:0xf bank_mask:0xf
	v_fmac_f32_dpp v198, v226, v26 row_newbcast:6 row_mask:0xf bank_mask:0xf
	v_fmac_f32_dpp v199, v227, v27 row_newbcast:6 row_mask:0xf bank_mask:0xf
	v_fmac_f32_dpp v196, v224, v28 row_newbcast:7 row_mask:0xf bank_mask:0xf
	v_fmac_f32_dpp v197, v225, v29 row_newbcast:7 row_mask:0xf bank_mask:0xf
	v_fmac_f32_dpp v198, v226, v30 row_newbcast:7 row_mask:0xf bank_mask:0xf
	v_fmac_f32_dpp v199, v227, v31 row_newbcast:7 row_mask:0xf bank_mask:0xf
	v_fmac_f32_dpp v196, v224, v32 row_newbcast:8 row_mask:0xf bank_mask:0xf
	v_fmac_f32_dpp v197, v225, v33 row_newbcast:8 row_mask:0xf bank_mask:0xf
	v_fmac_f32_dpp v198, v226, v34 row_newbcast:8 row_mask:0xf bank_mask:0xf
	v_fmac_f32_dpp v199, v227, v35 row_newbcast:8 row_mask:0xf bank_mask:0xf
	v_fmac_f32_dpp v196, v224, v36 row_newbcast:9 row_mask:0xf bank_mask:0xf
	v_fmac_f32_dpp v197, v225, v37 row_newbcast:9 row_mask:0xf bank_mask:0xf
	v_fmac_f32_dpp v198, v226, v38 row_newbcast:9 row_mask:0xf bank_mask:0xf
	v_fmac_f32_dpp v199, v227, v39 row_newbcast:9 row_mask:0xf bank_mask:0xf
	v_fmac_f32_dpp v196, v224, v40 row_newbcast:10 row_mask:0xf bank_mask:0xf
	v_fmac_f32_dpp v197, v225, v41 row_newbcast:10 row_mask:0xf bank_mask:0xf
	v_fmac_f32_dpp v198, v226, v42 row_newbcast:10 row_mask:0xf bank_mask:0xf
	v_fmac_f32_dpp v199, v227, v43 row_newbcast:10 row_mask:0xf bank_mask:0xf
	v_fmac_f32_dpp v196, v224, v44 row_newbcast:11 row_mask:0xf bank_mask:0xf
	v_fmac_f32_dpp v197, v225, v45 row_newbcast:11 row_mask:0xf bank_mask:0xf
	v_fmac_f32_dpp v198, v226, v46 row_newbcast:11 row_mask:0xf bank_mask:0xf
	v_fmac_f32_dpp v199, v227, v47 row_newbcast:11 row_mask:0xf bank_mask:0xf
	v_fmac_f32_dpp v196, v224, v48 row_newbcast:12 row_mask:0xf bank_mask:0xf
	v_fmac_f32_dpp v197, v225, v49 row_newbcast:12 row_mask:0xf bank_mask:0xf
	v_fmac_f32_dpp v198, v226, v50 row_newbcast:12 row_mask:0xf bank_mask:0xf
	v_fmac_f32_dpp v199, v227, v51 row_newbcast:12 row_mask:0xf bank_mask:0xf
	v_fmac_f32_dpp v196, v224, v52 row_newbcast:13 row_mask:0xf bank_mask:0xf
	v_fmac_f32_dpp v197, v225, v53 row_newbcast:13 row_mask:0xf bank_mask:0xf
	v_fmac_f32_dpp v198, v226, v54 row_newbcast:13 row_mask:0xf bank_mask:0xf
	v_fmac_f32_dpp v199, v227, v55 row_newbcast:13 row_mask:0xf bank_mask:0xf
	v_fmac_f32_dpp v196, v224, v56 row_newbcast:14 row_mask:0xf bank_mask:0xf
	v_fmac_f32_dpp v197, v225, v57 row_newbcast:14 row_mask:0xf bank_mask:0xf
	v_fmac_f32_dpp v198, v226, v58 row_newbcast:14 row_mask:0xf bank_mask:0xf
	v_fmac_f32_dpp v199, v227, v59 row_newbcast:14 row_mask:0xf bank_mask:0xf
	v_fmac_f32_dpp v196, v224, v60 row_newbcast:15 row_mask:0xf bank_mask:0xf
	v_fmac_f32_dpp v197, v225, v61 row_newbcast:15 row_mask:0xf bank_mask:0xf
	v_fmac_f32_dpp v198, v226, v62 row_newbcast:15 row_mask:0xf bank_mask:0xf
	v_fmac_f32_dpp v199, v227, v63 row_newbcast:15 row_mask:0xf bank_mask:0xf
	v_add_f32_e32 v196, v196, v197
	v_add_f32_e32 v198, v198, v199
	v_add_f32_e32 v196, v196, v198
	v_xor_b32_e32 v202, 0x80000000, v196
	s_waitcnt lgkmcnt(0)
; #define SB __builtin_amdgcn_sched_barrier(0)
; #define ST2(set, s) { DERIVE_BK(set); float sd[4]; ScanK<0>::dot(S, set.a, sd); float y0 = set.yo, y1 = 0.f; ScanK<0>::upd(S, set, -((sd[0] + sd[1]) + (sd[2] + sd[3])), __uint_as_float(set.v << 16), y0, y1); __builtin_amdgcn_raw_buffer_store_b32(__float_as_uint(y0 + y1), rY, lo4b, ob4 + (unsigned)((int)(s) * (int)stp * 4), 0); }
;     static __device__ __forceinline__ void upd(float (&S)[64], const In2& in, float sa, float vv, float& y0, float& y1) {
;         float t0, t1, t2, t3;
;         asm volatile("v_mul_f32_dpp %0, %10, %27 row_newbcast:%28" DPPM "v_mul_f32_dpp %1, %11, %27 row_newbcast:%28" DPPM "v_mul_f32_dpp %2, %12, %27 row_newbcast:%28" DPPM "v_mul_f32_dpp %3, %13, %27 row_newbcast:%28" DPPM
;                      "v_fmac_f32_dpp %0, %14, %6 row_newbcast:%28" DPPM "v_fmac_f32_dpp %1, %15, %7 row_newbcast:%28" DPPM "v_fmac_f32_dpp %2, %16, %8 row_newbcast:%28" DPPM "v_fmac_f32_dpp %3, %17, %9 row_newbcast:%28" DPPM
;                      "v_fmac_f32_dpp %0, %18, %26 row_newbcast:%28" DPPM "v_fmac_f32_dpp %1, %19, %26 row_newbcast:%28" DPPM "v_fmac_f32_dpp %2, %20, %26 row_newbcast:%28" DPPM "v_fmac_f32_dpp %3, %21, %26 row_newbcast:%28" DPPM
;                      "v_fmac_f32_dpp %4, %22, %0 row_newbcast:%28" DPPM "v_fmac_f32_dpp %5, %23, %1 row_newbcast:%28" DPPM "v_fmac_f32_dpp %4, %24, %2 row_newbcast:%28" DPPM "v_fmac_f32_dpp %5, %25, %3 row_newbcast:%28" DPPM
;                      : "=&v"(t0), "=&v"(t1), "=&v"(t2), "=&v"(t3), "+v"(y0), "+v"(y1)
;                      : "v"(S[K]), "v"(S[K + 1]), "v"(S[K + 2]), "v"(S[K + 3]), "v"(in.kd[0]), "v"(in.kd[1]), "v"(in.kd[2]), "v"(in.kd[3]), "v"(in.w[0]), "v"(in.w[1]), "v"(in.w[2]), "v"(in.w[3]),
;                        "v"(in.b[0]), "v"(in.b[1]), "v"(in.b[2]), "v"(in.b[3]), "v"(in.r[0]), "v"(in.r[1]), "v"(in.r[2]), "v"(in.r[3]), "v"(sa), "v"(vv), "n"(N0));
;         S[K] = t0; S[K + 1] = t1; S[K + 2] = t2; S[K + 3] = t3;
;         if constexpr (K + 4 < 64) ScanK<K + 4>::upd(S, in, sa, vv, y0, y1);
;     }
; __device__ __forceinline__ void scan_pass2(const Params& p, int d) {
;     ...
;         In2 i0, i1; LD2(i0, 0);
; #pragma unroll 1
;         for (int s = 0; s < LC; s += 2) { TOUCH2(i0); SB; LD2(i1, s + 1); SB; ST2(i0, s); TOUCH2(i1); SB; LD2(i0, s + 2); SB; ST2(i1, s + 1); }
;     ...
;     }
	s_nop 1
	v_mfma_f32_4x4x1_16b_f32 v[0:3], v64, v202, v[0:3]
	v_mfma_f32_4x4x1_16b_f32 v[4:7], v65, v202, v[4:7]
	v_mfma_f32_4x4x1_16b_f32 v[8:11], v66, v202, v[8:11]
	v_mfma_f32_4x4x1_16b_f32 v[12:15], v67, v202, v[12:15]
	v_mfma_f32_4x4x1_16b_f32 v[16:19], v68, v202, v[16:19]
	v_mfma_f32_4x4x1_16b_f32 v[20:23], v69, v202, v[20:23]
	v_mfma_f32_4x4x1_16b_f32 v[24:27], v70, v202, v[24:27]
	v_mfma_f32_4x4x1_16b_f32 v[28:31], v71, v202, v[28:31]
	v_mfma_f32_4x4x1_16b_f32 v[32:35], v72, v202, v[32:35]
	v_mfma_f32_4x4x1_16b_f32 v[36:39], v73, v202, v[36:39]
	v_mfma_f32_4x4x1_16b_f32 v[40:43], v74, v202, v[40:43]
	v_mfma_f32_4x4x1_16b_f32 v[44:47], v75, v202, v[44:47]
	v_mfma_f32_4x4x1_16b_f32 v[48:51], v76, v202, v[48:51]
	v_mfma_f32_4x4x1_16b_f32 v[52:55], v77, v202, v[52:55]
	v_mfma_f32_4x4x1_16b_f32 v[56:59], v78, v202, v[56:59]
	v_mfma_f32_4x4x1_16b_f32 v[60:63], v79, v202, v[60:63]
	v_mfma_f32_4x4x1_16b_f32 v[0:3], v80, v203, v[0:3]
	v_mfma_f32_4x4x1_16b_f32 v[4:7], v81, v203, v[4:7]
	v_mfma_f32_4x4x1_16b_f32 v[8:11], v82, v203, v[8:11]
	v_mfma_f32_4x4x1_16b_f32 v[12:15], v83, v203, v[12:15]
	v_mfma_f32_4x4x1_16b_f32 v[16:19], v84, v203, v[16:19]
	v_mfma_f32_4x4x1_16b_f32 v[20:23], v85, v203, v[20:23]
	v_mfma_f32_4x4x1_16b_f32 v[24:27], v86, v203, v[24:27]
	v_mfma_f32_4x4x1_16b_f32 v[28:31], v87, v203, v[28:31]
	v_mfma_f32_4x4x1_16b_f32 v[32:35], v88, v203, v[32:35]
	v_mfma_f32_4x4x1_16b_f32 v[36:39], v89, v203, v[36:39]
	v_mfma_f32_4x4x1_16b_f32 v[40:43], v90, v203, v[40:43]
	v_mfma_f32_4x4x1_16b_f32 v[44:47], v91, v203, v[44:47]
	v_mfma_f32_4x4x1_16b_f32 v[48:51], v92, v203, v[48:51]
	v_mfma_f32_4x4x1_16b_f32 v[52:55], v93, v203, v[52:55]
	v_mfma_f32_4x4x1_16b_f32 v[56:59], v94, v203, v[56:59]
	v_mfma_f32_4x4x1_16b_f32 v[60:63], v95, v203, v[60:63]
	v_fmac_f32_dpp v175, v228, v0 row_newbcast:0 row_mask:0xf bank_mask:0xf
	v_mul_f32_dpp v201, v229, v1 row_newbcast:0 row_mask:0xf bank_mask:0xf
	v_fmac_f32_dpp v175, v230, v2 row_newbcast:0 row_mask:0xf bank_mask:0xf
	v_fmac_f32_dpp v201, v231, v3 row_newbcast:0 row_mask:0xf bank_mask:0xf
	v_fmac_f32_dpp v175, v228, v4 row_newbcast:1 row_mask:0xf bank_mask:0xf
	v_fmac_f32_dpp v201, v229, v5 row_newbcast:1 row_mask:0xf bank_mask:0xf
	v_fmac_f32_dpp v175, v230, v6 row_newbcast:1 row_mask:0xf bank_mask:0xf
	v_fmac_f32_dpp v201, v231, v7 row_newbcast:1 row_mask:0xf bank_mask:0xf
	v_fmac_f32_dpp v175, v228, v8 row_newbcast:2 row_mask:0xf bank_mask:0xf
	v_fmac_f32_dpp v201, v229, v9 row_newbcast:2 row_mask:0xf bank_mask:0xf
	v_fmac_f32_dpp v175, v230, v10 row_newbcast:2 row_mask:0xf bank_mask:0xf
	v_fmac_f32_dpp v201, v231, v11 row_newbcast:2 row_mask:0xf bank_mask:0xf
	v_fmac_f32_dpp v175, v228, v12 row_newbcast:3 row_mask:0xf bank_mask:0xf
	v_fmac_f32_dpp v201, v229, v13 row_newbcast:3 row_mask:0xf bank_mask:0xf
	v_fmac_f32_dpp v175, v230, v14 row_newbcast:3 row_mask:0xf bank_mask:0xf
	v_fmac_f32_dpp v201, v231, v15 row_newbcast:3 row_mask:0xf bank_mask:0xf
	v_fmac_f32_dpp v175, v228, v16 row_newbcast:4 row_mask:0xf bank_mask:0xf
	v_fmac_f32_dpp v201, v229, v17 row_newbcast:4 row_mask:0xf bank_mask:0xf
	v_fmac_f32_dpp v175, v230, v18 row_newbcast:4 row_mask:0xf bank_mask:0xf
	v_fmac_f32_dpp v201, v231, v19 row_newbcast:4 row_mask:0xf bank_mask:0xf
	v_fmac_f32_dpp v175, v228, v20 row_newbcast:5 row_mask:0xf bank_mask:0xf
	v_fmac_f32_dpp v201, v229, v21 row_newbcast:5 row_mask:0xf bank_mask:0xf
	v_fmac_f32_dpp v175, v230, v22 row_newbcast:5 row_mask:0xf bank_mask:0xf
	v_fmac_f32_dpp v201, v231, v23 row_newbcast:5 row_mask:0xf bank_mask:0xf
	v_fmac_f32_dpp v175, v228, v24 row_newbcast:6 row_mask:0xf bank_mask:0xf
	v_fmac_f32_dpp v201, v229, v25 row_newbcast:6 row_mask:0xf bank_mask:0xf
	v_fmac_f32_dpp v175, v230, v26 row_newbcast:6 row_mask:0xf bank_mask:0xf
	v_fmac_f32_dpp v201, v231, v27 row_newbcast:6 row_mask:0xf bank_mask:0xf
	v_fmac_f32_dpp v175, v228, v28 row_newbcast:7 row_mask:0xf bank_mask:0xf
	v_fmac_f32_dpp v201, v229, v29 row_newbcast:7 row_mask:0xf bank_mask:0xf
	v_fmac_f32_dpp v175, v230, v30 row_newbcast:7 row_mask:0xf bank_mask:0xf
	v_fmac_f32_dpp v201, v231, v31 row_newbcast:7 row_mask:0xf bank_mask:0xf
	v_fmac_f32_dpp v175, v228, v32 row_newbcast:8 row_mask:0xf bank_mask:0xf
	v_fmac_f32_dpp v201, v229, v33 row_newbcast:8 row_mask:0xf bank_mask:0xf
	v_fmac_f32_dpp v175, v230, v34 row_newbcast:8 row_mask:0xf bank_mask:0xf
	v_fmac_f32_dpp v201, v231, v35 row_newbcast:8 row_mask:0xf bank_mask:0xf
	v_fmac_f32_dpp v175, v228, v36 row_newbcast:9 row_mask:0xf bank_mask:0xf
	v_fmac_f32_dpp v201, v229, v37 row_newbcast:9 row_mask:0xf bank_mask:0xf
	v_fmac_f32_dpp v175, v230, v38 row_newbcast:9 row_mask:0xf bank_mask:0xf
	v_fmac_f32_dpp v201, v231, v39 row_newbcast:9 row_mask:0xf bank_mask:0xf
	v_fmac_f32_dpp v175, v228, v40 row_newbcast:10 row_mask:0xf bank_mask:0xf
	v_fmac_f32_dpp v201, v229, v41 row_newbcast:10 row_mask:0xf bank_mask:0xf
	v_fmac_f32_dpp v175, v230, v42 row_newbcast:10 row_mask:0xf bank_mask:0xf
	v_fmac_f32_dpp v201, v231, v43 row_newbcast:10 row_mask:0xf bank_mask:0xf
	v_fmac_f32_dpp v175, v228, v44 row_newbcast:11 row_mask:0xf bank_mask:0xf
	v_fmac_f32_dpp v201, v229, v45 row_newbcast:11 row_mask:0xf bank_mask:0xf
	v_fmac_f32_dpp v175, v230, v46 row_newbcast:11 row_mask:0xf bank_mask:0xf
	v_fmac_f32_dpp v201, v231, v47 row_newbcast:11 row_mask:0xf bank_mask:0xf
	v_fmac_f32_dpp v175, v228, v48 row_newbcast:12 row_mask:0xf bank_mask:0xf
	v_fmac_f32_dpp v201, v229, v49 row_newbcast:12 row_mask:0xf bank_mask:0xf
	v_fmac_f32_dpp v175, v230, v50 row_newbcast:12 row_mask:0xf bank_mask:0xf
	v_fmac_f32_dpp v201, v231, v51 row_newbcast:12 row_mask:0xf bank_mask:0xf
	v_fmac_f32_dpp v175, v228, v52 row_newbcast:13 row_mask:0xf bank_mask:0xf
	v_fmac_f32_dpp v201, v229, v53 row_newbcast:13 row_mask:0xf bank_mask:0xf
	v_fmac_f32_dpp v175, v230, v54 row_newbcast:13 row_mask:0xf bank_mask:0xf
	v_fmac_f32_dpp v201, v231, v55 row_newbcast:13 row_mask:0xf bank_mask:0xf
	v_fmac_f32_dpp v175, v228, v56 row_newbcast:14 row_mask:0xf bank_mask:0xf
	v_fmac_f32_dpp v201, v229, v57 row_newbcast:14 row_mask:0xf bank_mask:0xf
	v_fmac_f32_dpp v175, v230, v58 row_newbcast:14 row_mask:0xf bank_mask:0xf
	v_fmac_f32_dpp v201, v231, v59 row_newbcast:14 row_mask:0xf bank_mask:0xf
	v_fmac_f32_dpp v175, v228, v60 row_newbcast:15 row_mask:0xf bank_mask:0xf
	v_fmac_f32_dpp v201, v229, v61 row_newbcast:15 row_mask:0xf bank_mask:0xf
	v_fmac_f32_dpp v175, v230, v62 row_newbcast:15 row_mask:0xf bank_mask:0xf
	v_fmac_f32_dpp v201, v231, v63 row_newbcast:15 row_mask:0xf bank_mask:0xf
	v_add_f32_e32 v200, v175, v201
	s_sub_u32 s83, s83, 1
	s_cmp_eq_u32 s83, 0
	s_cbranch_scc1 .Lmy_p2d1_ldone
	s_and_b32 s9, s83, 7
	s_cmp_eq_u32 s9, 0
	s_cbranch_scc1 .Lmy_p2d1_renorm
	s_branch .Lmy_p2d1_loop
.Lmy_p2d1_ldone:
	buffer_store_dword v200, v207, s[68:71], s79 offen
	s_add_u32 s79, s79, 0xfffff000
	s_lshl_b32 s6, s96, 3
	s_add_i32 s0, s0, s6
	s_branch .Lmy_p2d1_item
